# GEMM epilogues (q/kv up-proj, gate, residual x2, FF1): packed v_pk_mul/add/fma_f32 expanded into scalar f32 pairs (bit-identical per lane)
# baseline (speedup 1.0000x reference)
;     __device__ __forceinline__ void rope8(f32x4& v0, f32x4& v1, const f32x4 (&c)[4], int fq) const {
;         const float sg = (fq < 2) ? -1.f : 1.f;
; #pragma unroll
;         for (int e = 0; e < 4; ++e) {
;             const float p0 = __shfl_xor(v0[e], 32), p1 = __shfl_xor(v1[e], 32);
;             v0[e] = v0[e] * c[0][e] + sg * p0 * c[2][e]; v1[e] = v1[e] * c[1][e] + sg * p1 * c[3][e];
;         }
;     }
;     __device__ __forceinline__ void operator()(const f32x4 (&acc)[2][2][4][2], const Unit& u, int wr, int wc, int fr, int fq) const {
;     ...
;                     f32x4 v0 = acc[ai][bj][m][0] * rs1, v1 = acc[ai][bj][m][1] * rs1;
;                     if (mode == EP_PLAIN) { store8(O + (size_t)row * ldc + col8, v0, v1); }
;                     else if (mode == EP_RELU2) {
; #pragma unroll
;                         for (int e = 0; e < 4; ++e) { float a = fmaxf(v0[e], 0.f), b = fmaxf(v1[e], 0.f); v0[e] = a * a; v1[e] = b * b; }
;                         store8(O + (size_t)row * ldc + col8, v0, v1);
;                     } else if (mode == EP_Z1) {
;                         const int grp = grp0 + bj * 4;
;                         if (grp >= 20 && grp < 24) {
;                             const int b = row / SEQ, s = row % SEQ, kvh = wc >> 1;
;                             storeT(O2 + (size_t)(b * 2 + kvh) * 64 * SEQ, (wc & 1) * 32 + 8 * fq, s, v0, v1);
;                         } else if (grp == 44) {
;                             rope8(v0, v1, cst[m], fq);
;                             bf16_t* kr = O3 + (size_t)row * NQB + 64 + 8 * fq;
; #pragma unroll
;                             for (int h = 0; h < 8; ++h) store8(kr + h * 96, v0, v1);
;                         } else if (grp < 44) {
;                             if (grp < 16) { v0 = v0 * QA_SCALE; v1 = v1 * QA_SCALE; }
;                             store8(O + (size_t)row * ldc + col8, v0, v1);
;                             if (grp >= 24) {
;                                 float q = (v0[0] * v0[0] + v0[1] * v0[1]) + (v0[2] * v0[2] + v0[3] * v0[3]) + (v1[0] * v1[0] + v1[1] * v1[1]) + (v1[2] * v1[2] + v1[3] * v1[3]);
;                                 q += __shfl_xor(q, 16); q += __shfl_xor(q, 32);
;                                 if (fq == 0) ss_out[(size_t)row * 32 + grp - 24] = q;
;                             }
;                         }
;                     } else if (mode == EP_QB) {
.LBB0_459:
	s_waitcnt lgkmcnt(7)
	v_add_f32_e32 v180, v180, v181
	v_fmamk_f32 v180, v180, 0x3b2aaaab, v195
	v_rsq_f32_e32 v188, v180
	v_cndmask_b32_e64 v180, 0, 1, s[6:7]
	v_cmp_ne_u32_e64 s[0:1], 1, v180
	s_andn2_b64 vcc, exec, s[6:7]
	v_mul_f32_e32 v152, v152, v188
	v_mul_f32_e32 v153, v153, v188
	v_mul_f32_e32 v150, v150, v188
	v_mul_f32_e32 v151, v151, v188
	v_mul_f32_e32 v148, v148, v188
	v_mul_f32_e32 v149, v149, v188
	v_mul_f32_e32 v146, v146, v188
	v_mul_f32_e32 v147, v147, v188
	s_cbranch_vccnz .LBB0_461
	ds_bpermute_b32 v181, v217, v146
	v_mov_b32_e32 v212, v146
	s_waitcnt vmcnt(5)
	v_mov_b32_e32 v213, v118
	v_mov_b32_e32 v192, v114
	v_mov_b32_e32 v222, v147
	s_waitcnt lgkmcnt(0)
	v_mul_f32_e32 v193, v168, v181
	v_mul_f32_e32 v146, v118, v193
	v_fma_f32 v192, v212, v192, v146
	v_fma_f32 v193, v213, v193, v146
	ds_bpermute_b32 v146, v217, v147
	v_mov_b32_e32 v223, v119
	v_mov_b32_e32 v212, v115
	ds_bpermute_b32 v187, v217, v148
	ds_bpermute_b32 v180, v217, v150
	s_waitcnt lgkmcnt(2)
	v_mul_f32_e32 v213, v168, v146
	v_mul_f32_e32 v146, v147, v115
	v_fma_f32 v147, v223, v213, v146
	v_fma_f32 v146, v222, v212, v146
	ds_bpermute_b32 v146, v217, v152
	s_waitcnt lgkmcnt(2)
	v_mul_f32_e32 v223, v168, v187
	ds_bpermute_b32 v181, v217, v151
	v_mov_b32_e32 v224, v148
	v_mov_b32_e32 v225, v120
	s_waitcnt lgkmcnt(1)
	v_mul_f32_e32 v146, v168, v146
	s_waitcnt vmcnt(4)
	v_mul_f32_e32 v212, v132, v146
	v_mov_b32_e32 v222, v116
	v_mul_f32_e32 v146, v120, v223
	v_fma_f32 v222, v224, v222, v146
	v_fma_f32 v223, v225, v223, v146
	ds_bpermute_b32 v146, v217, v153
	ds_bpermute_b32 v148, v217, v149
	v_mul_f32_e32 v150, v150, v126
	v_mul_f32_e32 v151, v151, v127
	s_waitcnt lgkmcnt(2)
	v_mul_f32_e32 v180, v168, v180
	v_mul_f32_e32 v181, v169, v181
	v_mov_b32_e32 v226, v153
	s_waitcnt lgkmcnt(1)
	v_mul_f32_e32 v225, v168, v146
	v_mov_b32_e32 v227, v133
	v_mov_b32_e32 v224, v129
	v_fma_f32 v150, v130, v180, v150
	v_fma_f32 v151, v131, v181, v151
	s_waitcnt lgkmcnt(0)
	v_mul_f32_e32 v181, v168, v148
	v_mul_f32_e32 v224, v226, v224
	v_mul_f32_e32 v225, v227, v225
	v_mov_b32_e32 v148, v149
	v_mov_b32_e32 v149, v121
	v_mov_b32_e32 v180, v117
	v_mul_f32_e32 v146, v121, v181
	v_mul_f32_e32 v152, v152, v128
	v_mov_b32_e32 v153, v224
	v_mov_b32_e32 v213, v225
	v_fma_f32 v180, v148, v180, v146
	v_fma_f32 v181, v149, v181, v146
	v_add_f32_e32 v152, v152, v212
	v_add_f32_e32 v153, v153, v213
	v_mov_b32_e32 v146, v192
	v_mov_b32_e32 v148, v222
	v_mov_b32_e32 v149, v180
.LBB0_461:
	v_lshl_or_b32 v180, s21, 8, v196
	v_pk_mul_f32 v[212:213], v[146:147], s[18:19] op_sel_hi:[1,0]
	v_mov_b64_e32 v[146:147], s[44:45]
	v_pk_mul_f32 v[152:153], v[152:153], s[18:19] op_sel_hi:[1,0]
	v_pk_mul_f32 v[150:151], v[150:151], s[18:19] op_sel_hi:[1,0]
	v_pk_mul_f32 v[192:193], v[148:149], s[18:19] op_sel_hi:[1,0]
	v_mad_i64_i32 v[146:147], s[6:7], v178, s33, v[146:147]
	v_ashrrev_i32_e32 v181, 31, v180
	v_lshl_add_u64 v[146:147], v[180:181], 1, v[146:147]
	v_cvt_pk_bf16_f32 v148, v150, v151
	v_cvt_pk_bf16_f32 v149, v152, v153
	v_cvt_pk_bf16_f32 v150, v212, v213
	v_cvt_pk_bf16_f32 v151, v192, v193
	v_mov_b32_e32 v189, v188
	global_store_dwordx4 v[146:147], v[148:151], off
	s_andn2_b64 vcc, exec, s[4:5]
	s_nop 0
	v_mov_b32_e32 v150, v188
	v_mov_b32_e32 v151, v188
	v_mul_f32_e32 v148, v142, v188
	v_mul_f32_e32 v149, v143, v189
	v_mul_f32_e32 v142, v140, v150
	v_mul_f32_e32 v143, v141, v151
	v_cndmask_b32_e64 v140, 0, 1, s[4:5]
	v_mul_f32_e32 v144, v144, v150
	v_mul_f32_e32 v145, v145, v151
	v_cmp_ne_u32_e64 s[38:39], 1, v140
	v_mul_f32_e32 v140, v138, v188
	v_mul_f32_e32 v141, v139, v189
	s_cbranch_vccnz .LBB0_463
	ds_bpermute_b32 v139, v217, v140
	v_mov_b32_e32 v152, v140
	s_waitcnt vmcnt(6)
	v_mov_b32_e32 v153, v118
	v_mov_b32_e32 v150, v114
	v_mov_b32_e32 v188, v141
	s_waitcnt lgkmcnt(0)
	v_mul_f32_e32 v151, v168, v139
	v_mul_f32_e32 v140, v118, v151
	v_fma_f32 v150, v152, v150, v140
	v_fma_f32 v151, v153, v151, v140
	ds_bpermute_b32 v140, v217, v141
	v_mov_b32_e32 v189, v119
	v_mov_b32_e32 v152, v115
	ds_bpermute_b32 v151, v217, v142
	ds_bpermute_b32 v138, v217, v148
	s_waitcnt lgkmcnt(2)
	v_mul_f32_e32 v153, v168, v140
	v_mul_f32_e32 v140, v141, v115
	v_fma_f32 v141, v189, v153, v140
	v_fma_f32 v140, v188, v152, v140
	ds_bpermute_b32 v140, v217, v144
	s_waitcnt lgkmcnt(2)
	v_mul_f32_e32 v189, v168, v151
	ds_bpermute_b32 v139, v217, v149
	v_mov_b32_e32 v192, v142
	v_mov_b32_e32 v193, v120
	s_waitcnt lgkmcnt(1)
	v_mul_f32_e32 v140, v168, v140
	s_waitcnt vmcnt(5)
	v_mul_f32_e32 v152, v132, v140
	v_mov_b32_e32 v188, v116
	v_mul_f32_e32 v140, v120, v189
	v_fma_f32 v188, v192, v188, v140
	v_fma_f32 v189, v193, v189, v140
	ds_bpermute_b32 v140, v217, v145
	ds_bpermute_b32 v142, v217, v143
	v_mul_f32_e32 v148, v148, v126
	v_mul_f32_e32 v149, v149, v127
	s_waitcnt lgkmcnt(2)
	v_mul_f32_e32 v138, v168, v138
	v_mul_f32_e32 v139, v169, v139
	v_mov_b32_e32 v212, v145
	s_waitcnt lgkmcnt(1)
	v_mul_f32_e32 v193, v168, v140
	v_mov_b32_e32 v213, v133
	v_mov_b32_e32 v192, v129
	v_fma_f32 v148, v130, v138, v148
	v_fma_f32 v149, v131, v139, v149
	s_waitcnt lgkmcnt(0)
	v_mul_f32_e32 v139, v168, v142
	v_mul_f32_e32 v192, v212, v192
	v_mul_f32_e32 v193, v213, v193
	v_mov_b32_e32 v142, v143
	v_mov_b32_e32 v143, v121
	v_mov_b32_e32 v138, v117
	v_mul_f32_e32 v140, v121, v139
	v_mul_f32_e32 v144, v144, v128
	v_mov_b32_e32 v145, v192
	v_mov_b32_e32 v153, v193
	v_fma_f32 v138, v142, v138, v140
	v_fma_f32 v139, v143, v139, v140
	v_add_f32_e32 v144, v144, v152
	v_add_f32_e32 v145, v145, v153
	v_mov_b32_e32 v140, v150
	v_mov_b32_e32 v142, v188
	v_mov_b32_e32 v143, v138
;     __device__ __forceinline__ void rope8(f32x4& v0, f32x4& v1, const f32x4 (&c)[4], int fq) const {
;         const float sg = (fq < 2) ? -1.f : 1.f;
; #pragma unroll
;         for (int e = 0; e < 4; ++e) {
;             const float p0 = __shfl_xor(v0[e], 32), p1 = __shfl_xor(v1[e], 32);
;             v0[e] = v0[e] * c[0][e] + sg * p0 * c[2][e]; v1[e] = v1[e] * c[1][e] + sg * p1 * c[3][e];
;         }
;     }
;     __device__ __forceinline__ void operator()(const f32x4 (&acc)[2][2][4][2], const Unit& u, int wr, int wc, int fr, int fq) const {
;     ...
;                     f32x4 v0 = acc[ai][bj][m][0] * rs1, v1 = acc[ai][bj][m][1] * rs1;
;                     if (mode == EP_PLAIN) { store8(O + (size_t)row * ldc + col8, v0, v1); }
;                     else if (mode == EP_RELU2) {
; #pragma unroll
;                         for (int e = 0; e < 4; ++e) { float a = fmaxf(v0[e], 0.f), b = fmaxf(v1[e], 0.f); v0[e] = a * a; v1[e] = b * b; }
;                         store8(O + (size_t)row * ldc + col8, v0, v1);
;                     } else if (mode == EP_Z1) {
;                         const int grp = grp0 + bj * 4;
;                         if (grp >= 20 && grp < 24) {
;                             const int b = row / SEQ, s = row % SEQ, kvh = wc >> 1;
;                             storeT(O2 + (size_t)(b * 2 + kvh) * 64 * SEQ, (wc & 1) * 32 + 8 * fq, s, v0, v1);
;                         } else if (grp == 44) {
;                             rope8(v0, v1, cst[m], fq);
;                             bf16_t* kr = O3 + (size_t)row * NQB + 64 + 8 * fq;
; #pragma unroll
;                             for (int h = 0; h < 8; ++h) store8(kr + h * 96, v0, v1);
;                         } else if (grp < 44) {
;                             if (grp < 16) { v0 = v0 * QA_SCALE; v1 = v1 * QA_SCALE; }
;                             store8(O + (size_t)row * ldc + col8, v0, v1);
;                             if (grp >= 24) {
;                                 float q = (v0[0] * v0[0] + v0[1] * v0[1]) + (v0[2] * v0[2] + v0[3] * v0[3]) + (v1[0] * v1[0] + v1[1] * v1[1]) + (v1[2] * v1[2] + v1[3] * v1[3]);
;                                 q += __shfl_xor(q, 16); q += __shfl_xor(q, 32);
;                                 if (fq == 0) ss_out[(size_t)row * 32 + grp - 24] = q;
;                             }
;                         }
;                     } else if (mode == EP_QB) {
.LBB0_463:
	s_waitcnt lgkmcnt(6)
	v_add_f32_e32 v138, v210, v211
	v_fmamk_f32 v138, v138, 0x3b2aaaab, v195
	v_rsq_f32_e32 v138, v138
	v_pk_mul_f32 v[144:145], v[144:145], s[18:19] op_sel_hi:[1,0]
	v_pk_mul_f32 v[148:149], v[148:149], s[18:19] op_sel_hi:[1,0]
	v_pk_mul_f32 v[150:151], v[142:143], s[18:19] op_sel_hi:[1,0]
	v_pk_mul_f32 v[142:143], v[140:141], s[18:19] op_sel_hi:[1,0]
	v_cvt_pk_bf16_f32 v140, v148, v149
	v_cvt_pk_bf16_f32 v141, v144, v145
	v_cvt_pk_bf16_f32 v142, v142, v143
	v_cvt_pk_bf16_f32 v143, v150, v151
	v_mul_f32_e32 v104, v104, v138
	v_mul_f32_e32 v105, v105, v138
	v_mul_f32_e32 v102, v102, v138
	v_mul_f32_e32 v103, v103, v138
	v_mul_f32_e32 v100, v100, v138
	v_mul_f32_e32 v101, v101, v138
	s_and_b64 vcc, exec, s[0:1]
	v_mul_f32_e32 v98, v98, v138
	v_mul_f32_e32 v99, v99, v138
	global_store_dwordx4 v[146:147], v[140:143], off offset:256
	s_cbranch_vccnz .LBB0_465
	ds_bpermute_b32 v139, v217, v98
	v_mov_b32_e32 v144, v98
	s_waitcnt vmcnt(3)
	v_mov_b32_e32 v145, v74
	v_mov_b32_e32 v142, v78
	v_mov_b32_e32 v146, v99
	s_waitcnt lgkmcnt(0)
	v_mul_f32_e32 v143, v168, v139
	v_mul_f32_e32 v98, v74, v143
	v_fma_f32 v142, v144, v142, v98
	v_fma_f32 v143, v145, v143, v98
	ds_bpermute_b32 v98, v217, v99
	v_mov_b32_e32 v147, v75
	v_mov_b32_e32 v144, v79
	ds_bpermute_b32 v139, v217, v100
	ds_bpermute_b32 v140, v217, v102
	s_waitcnt lgkmcnt(2)
	v_mul_f32_e32 v145, v168, v98
	v_mul_f32_e32 v98, v99, v79
	v_fma_f32 v99, v147, v145, v98
	v_fma_f32 v98, v146, v144, v98
	ds_bpermute_b32 v98, v217, v104
	s_waitcnt lgkmcnt(2)
	v_mul_f32_e32 v147, v168, v139
	ds_bpermute_b32 v141, v217, v103
	v_mov_b32_e32 v148, v100
	v_mov_b32_e32 v149, v76
	s_waitcnt lgkmcnt(1)
	v_mul_f32_e32 v98, v168, v98
	s_waitcnt vmcnt(2)
	v_mul_f32_e32 v144, v88, v98
	v_mov_b32_e32 v146, v80
	v_mul_f32_e32 v98, v76, v147
	v_fma_f32 v146, v148, v146, v98
	v_fma_f32 v147, v149, v147, v98
	ds_bpermute_b32 v98, v217, v105
	ds_bpermute_b32 v100, v217, v101
	v_mul_f32_e32 v102, v102, v82
	v_mul_f32_e32 v103, v103, v83
	s_waitcnt lgkmcnt(2)
	v_mul_f32_e32 v140, v168, v140
	v_mul_f32_e32 v141, v169, v141
	v_mov_b32_e32 v150, v105
	s_waitcnt lgkmcnt(1)
	v_mul_f32_e32 v149, v168, v98
	v_mov_b32_e32 v151, v89
	v_mov_b32_e32 v148, v85
	v_fma_f32 v102, v86, v140, v102
	v_fma_f32 v103, v87, v141, v103
	s_waitcnt lgkmcnt(0)
	v_mul_f32_e32 v141, v168, v100
	v_mul_f32_e32 v148, v150, v148
	v_mul_f32_e32 v149, v151, v149
	v_mov_b32_e32 v100, v101
	v_mov_b32_e32 v101, v77
	v_mov_b32_e32 v140, v81
	v_mul_f32_e32 v98, v77, v141
	v_mul_f32_e32 v104, v104, v84
	v_mov_b32_e32 v105, v148
	v_mov_b32_e32 v145, v149
	v_fma_f32 v140, v100, v140, v98
	v_fma_f32 v141, v101, v141, v98
	v_add_f32_e32 v104, v104, v144
	v_add_f32_e32 v105, v105, v145
	v_mov_b32_e32 v98, v142
	v_mov_b32_e32 v100, v146
	v_mov_b32_e32 v101, v140
.LBB0_465:
	s_nop 0
	v_pk_mul_f32 v[142:143], v[98:99], s[18:19] op_sel_hi:[1,0]
	v_mov_b64_e32 v[98:99], s[44:45]
	v_pk_mul_f32 v[104:105], v[104:105], s[18:19] op_sel_hi:[1,0]
	v_pk_mul_f32 v[102:103], v[102:103], s[18:19] op_sel_hi:[1,0]
	v_pk_mul_f32 v[140:141], v[100:101], s[18:19] op_sel_hi:[1,0]
	v_mad_i64_i32 v[98:99], s[4:5], v186, s33, v[98:99]
	v_lshl_add_u64 v[98:99], v[180:181], 1, v[98:99]
	v_cvt_pk_bf16_f32 v100, v102, v103
	v_cvt_pk_bf16_f32 v101, v104, v105
	v_cvt_pk_bf16_f32 v102, v142, v143
	v_cvt_pk_bf16_f32 v103, v140, v141
	v_mov_b32_e32 v139, v138
	global_store_dwordx4 v[98:99], v[100:103], off
	v_mul_f32_e32 v94, v94, v138
	v_mul_f32_e32 v95, v95, v139
	s_and_b64 vcc, exec, s[38:39]
	v_mov_b32_e32 v100, v138
	v_mov_b32_e32 v101, v138
	v_mul_f32_e32 v96, v96, v100
	v_mul_f32_e32 v97, v97, v101
	v_mul_f32_e32 v92, v92, v100
	v_mul_f32_e32 v93, v93, v101
	v_mul_f32_e32 v90, v90, v138
	v_mul_f32_e32 v91, v91, v139
	s_cbranch_vccnz .LBB0_467
	ds_bpermute_b32 v101, v217, v90
	v_mov_b32_e32 v104, v90
	s_waitcnt vmcnt(4)
	v_mov_b32_e32 v105, v74
	v_mov_b32_e32 v102, v78
	v_mov_b32_e32 v138, v91
	s_waitcnt lgkmcnt(0)
	v_mul_f32_e32 v103, v168, v101
	v_mul_f32_e32 v90, v74, v103
	v_fma_f32 v102, v104, v102, v90
	v_fma_f32 v103, v105, v103, v90
	ds_bpermute_b32 v90, v217, v91
	v_mov_b32_e32 v139, v75
	v_mov_b32_e32 v104, v79
	ds_bpermute_b32 v103, v217, v92
	ds_bpermute_b32 v100, v217, v94
	s_waitcnt lgkmcnt(2)
	v_mul_f32_e32 v105, v168, v90
	v_mul_f32_e32 v90, v91, v79
	v_fma_f32 v91, v139, v105, v90
	v_fma_f32 v90, v138, v104, v90
	ds_bpermute_b32 v90, v217, v96
	s_waitcnt lgkmcnt(2)
	v_mul_f32_e32 v139, v168, v103
	ds_bpermute_b32 v101, v217, v95
	v_mov_b32_e32 v140, v92
	v_mov_b32_e32 v141, v76
	s_waitcnt lgkmcnt(1)
	v_mul_f32_e32 v90, v168, v90
	s_waitcnt vmcnt(3)
	v_mul_f32_e32 v104, v88, v90
	v_mov_b32_e32 v138, v80
	v_mul_f32_e32 v90, v76, v139
	v_fma_f32 v138, v140, v138, v90
	v_fma_f32 v139, v141, v139, v90
	ds_bpermute_b32 v90, v217, v97
	ds_bpermute_b32 v92, v217, v93
	v_mul_f32_e32 v94, v94, v82
	v_mul_f32_e32 v95, v95, v83
	s_waitcnt lgkmcnt(2)
	v_mul_f32_e32 v100, v168, v100
	v_mul_f32_e32 v101, v169, v101
	v_mov_b32_e32 v142, v97
	s_waitcnt lgkmcnt(1)
	v_mul_f32_e32 v141, v168, v90
	v_mov_b32_e32 v143, v89
	v_mov_b32_e32 v140, v85
	v_fma_f32 v94, v86, v100, v94
	v_fma_f32 v95, v87, v101, v95
	s_waitcnt lgkmcnt(0)
	v_mul_f32_e32 v101, v168, v92
	v_mul_f32_e32 v140, v142, v140
	v_mul_f32_e32 v141, v143, v141
	v_mov_b32_e32 v92, v93
	v_mov_b32_e32 v93, v77
	v_mov_b32_e32 v100, v81
	v_mul_f32_e32 v90, v77, v101
	v_mul_f32_e32 v96, v96, v84
	v_mov_b32_e32 v97, v140
	v_mov_b32_e32 v105, v141
	v_fma_f32 v100, v92, v100, v90
	v_fma_f32 v101, v93, v101, v90
	v_add_f32_e32 v96, v96, v104
	v_add_f32_e32 v97, v97, v105
	v_mov_b32_e32 v90, v102
	v_mov_b32_e32 v92, v138
	v_mov_b32_e32 v93, v100

;     __device__ __forceinline__ void rope8(f32x4& v0, f32x4& v1, const f32x4 (&c)[4], int fq) const {
;         const float sg = (fq < 2) ? -1.f : 1.f;
; #pragma unroll
;         for (int e = 0; e < 4; ++e) {
;             const float p0 = __shfl_xor(v0[e], 32), p1 = __shfl_xor(v1[e], 32);
;             v0[e] = v0[e] * c[0][e] + sg * p0 * c[2][e]; v1[e] = v1[e] * c[1][e] + sg * p1 * c[3][e];
;         }
;     }
;     __device__ __forceinline__ void operator()(const f32x4 (&acc)[2][2][4][2], const Unit& u, int wr, int wc, int fr, int fq) const {
;     ...
;                     f32x4 v0 = acc[ai][bj][m][0] * rs1, v1 = acc[ai][bj][m][1] * rs1;
;                     if (mode == EP_PLAIN) { store8(O + (size_t)row * ldc + col8, v0, v1); }
;                     else if (mode == EP_RELU2) {
; #pragma unroll
;                         for (int e = 0; e < 4; ++e) { float a = fmaxf(v0[e], 0.f), b = fmaxf(v1[e], 0.f); v0[e] = a * a; v1[e] = b * b; }
;                         store8(O + (size_t)row * ldc + col8, v0, v1);
;                     } else if (mode == EP_Z1) {
;                         const int grp = grp0 + bj * 4;
;                         if (grp >= 20 && grp < 24) {
;                             const int b = row / SEQ, s = row % SEQ, kvh = wc >> 1;
;                             storeT(O2 + (size_t)(b * 2 + kvh) * 64 * SEQ, (wc & 1) * 32 + 8 * fq, s, v0, v1);
;                         } else if (grp == 44) {
;                             rope8(v0, v1, cst[m], fq);
;                             bf16_t* kr = O3 + (size_t)row * NQB + 64 + 8 * fq;
; #pragma unroll
;                             for (int h = 0; h < 8; ++h) store8(kr + h * 96, v0, v1);
;                         } else if (grp < 44) {
;                             if (grp < 16) { v0 = v0 * QA_SCALE; v1 = v1 * QA_SCALE; }
;                             store8(O + (size_t)row * ldc + col8, v0, v1);
;                             if (grp >= 24) {
;                                 float q = (v0[0] * v0[0] + v0[1] * v0[1]) + (v0[2] * v0[2] + v0[3] * v0[3]) + (v1[0] * v1[0] + v1[1] * v1[1]) + (v1[2] * v1[2] + v1[3] * v1[3]);
;                                 q += __shfl_xor(q, 16); q += __shfl_xor(q, 32);
;                                 if (fq == 0) ss_out[(size_t)row * 32 + grp - 24] = q;
;                             }
;                         }
;                     } else if (mode == EP_QB) {
.LBB0_469:
	s_waitcnt lgkmcnt(5)
	v_add_f32_e32 v183, v208, v209
	v_fmamk_f32 v183, v183, 0x3b2aaaab, v195
	v_rsq_f32_e32 v186, v183
	s_and_b64 vcc, exec, s[0:1]
	v_mul_f32_e32 v160, v160, v186
	v_mul_f32_e32 v161, v161, v186
	v_mul_f32_e32 v158, v158, v186
	v_mul_f32_e32 v159, v159, v186
	v_mul_f32_e32 v156, v156, v186
	v_mul_f32_e32 v157, v157, v186
	v_mul_f32_e32 v154, v154, v186
	v_mul_f32_e32 v155, v155, v186
	s_cbranch_vccnz .LBB0_471
	ds_bpermute_b32 v183, v217, v154
	v_mov_b32_e32 v208, v154
	s_waitcnt vmcnt(5)
	v_mov_b32_e32 v209, v142
	v_mov_b32_e32 v192, v138
	v_mov_b32_e32 v210, v155
	s_waitcnt lgkmcnt(0)
	v_mul_f32_e32 v193, v168, v183
	v_mul_f32_e32 v154, v142, v193
	v_fma_f32 v192, v208, v192, v154
	v_fma_f32 v193, v209, v193, v154
	ds_bpermute_b32 v154, v217, v155
	v_mov_b32_e32 v211, v143
	v_mov_b32_e32 v208, v139
	ds_bpermute_b32 v183, v217, v156
	ds_bpermute_b32 v188, v217, v158
	s_waitcnt lgkmcnt(2)
	v_mul_f32_e32 v209, v168, v154
	v_mul_f32_e32 v154, v155, v139
	v_fma_f32 v155, v211, v209, v154
	v_fma_f32 v154, v210, v208, v154
	ds_bpermute_b32 v154, v217, v160
	s_waitcnt lgkmcnt(2)
	v_mul_f32_e32 v211, v168, v183
	ds_bpermute_b32 v189, v217, v159
	v_mov_b32_e32 v212, v156
	v_mov_b32_e32 v213, v144
	s_waitcnt lgkmcnt(1)
	v_mul_f32_e32 v154, v168, v154
	s_waitcnt vmcnt(4)
	v_mul_f32_e32 v208, v152, v154
	v_mov_b32_e32 v210, v140
	v_mul_f32_e32 v154, v144, v211
	v_fma_f32 v210, v212, v210, v154
	v_fma_f32 v211, v213, v211, v154
	ds_bpermute_b32 v154, v217, v161
	ds_bpermute_b32 v156, v217, v157
	v_mul_f32_e32 v158, v158, v146
	v_mul_f32_e32 v159, v159, v147
	s_waitcnt lgkmcnt(2)
	v_mul_f32_e32 v188, v168, v188
	v_mul_f32_e32 v189, v169, v189
	v_mov_b32_e32 v222, v161
	s_waitcnt lgkmcnt(1)
	v_mul_f32_e32 v213, v168, v154
	v_mov_b32_e32 v223, v153
	v_mov_b32_e32 v212, v149
	v_fma_f32 v158, v150, v188, v158
	v_fma_f32 v159, v151, v189, v159
	s_waitcnt lgkmcnt(0)
	v_mul_f32_e32 v189, v168, v156
	v_mul_f32_e32 v212, v222, v212
	v_mul_f32_e32 v213, v223, v213
	v_mov_b32_e32 v156, v157
	v_mov_b32_e32 v157, v145
	v_mov_b32_e32 v188, v141
	v_mul_f32_e32 v154, v145, v189
	v_mul_f32_e32 v160, v160, v148
	v_mov_b32_e32 v161, v212
	v_mov_b32_e32 v209, v213
	v_fma_f32 v188, v156, v188, v154
	v_fma_f32 v189, v157, v189, v154
	v_add_f32_e32 v160, v160, v208
	v_add_f32_e32 v161, v161, v209
	v_mov_b32_e32 v154, v192
	v_mov_b32_e32 v156, v210
	v_mov_b32_e32 v157, v188
.LBB0_471:
	v_pk_mul_f32 v[192:193], v[154:155], s[18:19] op_sel_hi:[1,0]
	v_mov_b64_e32 v[154:155], s[44:45]
	v_pk_mul_f32 v[160:161], v[160:161], s[18:19] op_sel_hi:[1,0]
	v_pk_mul_f32 v[158:159], v[158:159], s[18:19] op_sel_hi:[1,0]
	v_pk_mul_f32 v[188:189], v[156:157], s[18:19] op_sel_hi:[1,0]
	v_mad_i64_i32 v[154:155], s[4:5], v184, s33, v[154:155]
	v_lshl_add_u64 v[154:155], v[180:181], 1, v[154:155]
	v_cvt_pk_bf16_f32 v156, v158, v159
	v_cvt_pk_bf16_f32 v157, v160, v161
	v_cvt_pk_bf16_f32 v158, v192, v193
	v_cvt_pk_bf16_f32 v159, v188, v189
	v_mov_b32_e32 v187, v186
	global_store_dwordx4 v[154:155], v[156:159], off
	s_and_b64 vcc, exec, s[38:39]
	s_nop 0
	v_mov_b32_e32 v158, v186
	v_mov_b32_e32 v159, v186
	v_mul_f32_e32 v136, v136, v158
	v_mul_f32_e32 v137, v137, v159
	v_mul_f32_e32 v156, v134, v186
	v_mul_f32_e32 v157, v135, v187
	v_mul_f32_e32 v134, v124, v158
	v_mul_f32_e32 v135, v125, v159
	v_mul_f32_e32 v124, v122, v186
	v_mul_f32_e32 v125, v123, v187
	s_cbranch_vccnz .LBB0_473
	ds_bpermute_b32 v123, v217, v124
	v_mov_b32_e32 v160, v124
	s_waitcnt vmcnt(6)
	v_mov_b32_e32 v161, v142
	v_mov_b32_e32 v158, v138
	v_mov_b32_e32 v184, v125
	s_waitcnt lgkmcnt(0)
	v_mul_f32_e32 v159, v168, v123
	v_mul_f32_e32 v124, v142, v159
	v_fma_f32 v158, v160, v158, v124
	v_fma_f32 v159, v161, v159, v124
	ds_bpermute_b32 v124, v217, v125
	v_mov_b32_e32 v185, v143
	v_mov_b32_e32 v160, v139
	ds_bpermute_b32 v159, v217, v134
	ds_bpermute_b32 v122, v217, v156
	s_waitcnt lgkmcnt(2)
	v_mul_f32_e32 v161, v168, v124
	v_mul_f32_e32 v124, v125, v139
	v_fma_f32 v125, v185, v161, v124
	v_fma_f32 v124, v184, v160, v124
	ds_bpermute_b32 v124, v217, v136
	s_waitcnt lgkmcnt(2)
	v_mul_f32_e32 v185, v168, v159
	ds_bpermute_b32 v123, v217, v157
	v_mov_b32_e32 v186, v134
	v_mov_b32_e32 v187, v144
	s_waitcnt lgkmcnt(1)
	v_mul_f32_e32 v124, v168, v124
	s_waitcnt vmcnt(5)
	v_mul_f32_e32 v160, v152, v124
	v_mov_b32_e32 v184, v140
	v_mul_f32_e32 v124, v144, v185
	v_fma_f32 v184, v186, v184, v124
	v_fma_f32 v185, v187, v185, v124
	ds_bpermute_b32 v124, v217, v137
	ds_bpermute_b32 v134, v217, v135
	v_mul_f32_e32 v156, v156, v146
	v_mul_f32_e32 v157, v157, v147
	s_waitcnt lgkmcnt(2)
	v_mul_f32_e32 v122, v168, v122
	v_mul_f32_e32 v123, v169, v123
	v_mov_b32_e32 v188, v137
	s_waitcnt lgkmcnt(1)
	v_mul_f32_e32 v187, v168, v124
	v_mov_b32_e32 v189, v153
	v_mov_b32_e32 v186, v149
	v_fma_f32 v156, v150, v122, v156
	v_fma_f32 v157, v151, v123, v157
	s_waitcnt lgkmcnt(0)
	v_mul_f32_e32 v123, v168, v134
	v_mul_f32_e32 v186, v188, v186
	v_mul_f32_e32 v187, v189, v187
	v_mov_b32_e32 v134, v135
	v_mov_b32_e32 v135, v145
	v_mov_b32_e32 v122, v141
	v_mul_f32_e32 v124, v145, v123
	v_mul_f32_e32 v136, v136, v148
	v_mov_b32_e32 v137, v186
	v_mov_b32_e32 v161, v187
	v_fma_f32 v122, v134, v122, v124
	v_fma_f32 v123, v135, v123, v124
	v_add_f32_e32 v136, v136, v160
	v_add_f32_e32 v137, v137, v161
	v_mov_b32_e32 v124, v158
	v_mov_b32_e32 v134, v184
	v_mov_b32_e32 v135, v122
;     __device__ __forceinline__ void rope8(f32x4& v0, f32x4& v1, const f32x4 (&c)[4], int fq) const {
;         const float sg = (fq < 2) ? -1.f : 1.f;
; #pragma unroll
;         for (int e = 0; e < 4; ++e) {
;             const float p0 = __shfl_xor(v0[e], 32), p1 = __shfl_xor(v1[e], 32);
;             v0[e] = v0[e] * c[0][e] + sg * p0 * c[2][e]; v1[e] = v1[e] * c[1][e] + sg * p1 * c[3][e];
;         }
;     }
;     __device__ __forceinline__ void operator()(const f32x4 (&acc)[2][2][4][2], const Unit& u, int wr, int wc, int fr, int fq) const {
;     ...
;                     f32x4 v0 = acc[ai][bj][m][0] * rs1, v1 = acc[ai][bj][m][1] * rs1;
;                     if (mode == EP_PLAIN) { store8(O + (size_t)row * ldc + col8, v0, v1); }
;                     else if (mode == EP_RELU2) {
; #pragma unroll
;                         for (int e = 0; e < 4; ++e) { float a = fmaxf(v0[e], 0.f), b = fmaxf(v1[e], 0.f); v0[e] = a * a; v1[e] = b * b; }
;                         store8(O + (size_t)row * ldc + col8, v0, v1);
;                     } else if (mode == EP_Z1) {
;                         const int grp = grp0 + bj * 4;
;                         if (grp >= 20 && grp < 24) {
;                             const int b = row / SEQ, s = row % SEQ, kvh = wc >> 1;
;                             storeT(O2 + (size_t)(b * 2 + kvh) * 64 * SEQ, (wc & 1) * 32 + 8 * fq, s, v0, v1);
;                         } else if (grp == 44) {
;                             rope8(v0, v1, cst[m], fq);
;                             bf16_t* kr = O3 + (size_t)row * NQB + 64 + 8 * fq;
; #pragma unroll
;                             for (int h = 0; h < 8; ++h) store8(kr + h * 96, v0, v1);
;                         } else if (grp < 44) {
;                             if (grp < 16) { v0 = v0 * QA_SCALE; v1 = v1 * QA_SCALE; }
;                             store8(O + (size_t)row * ldc + col8, v0, v1);
;                             if (grp >= 24) {
;                                 float q = (v0[0] * v0[0] + v0[1] * v0[1]) + (v0[2] * v0[2] + v0[3] * v0[3]) + (v1[0] * v1[0] + v1[1] * v1[1]) + (v1[2] * v1[2] + v1[3] * v1[3]);
;                                 q += __shfl_xor(q, 16); q += __shfl_xor(q, 32);
;                                 if (fq == 0) ss_out[(size_t)row * 32 + grp - 24] = q;
;                             }
;                         }
;                     } else if (mode == EP_QB) {
.LBB0_473:
	s_waitcnt lgkmcnt(4)
	v_add_f32_e32 v122, v206, v207
	v_fmamk_f32 v122, v122, 0x3b2aaaab, v195
	v_rsq_f32_e32 v122, v122
	v_pk_mul_f32 v[136:137], v[136:137], s[18:19] op_sel_hi:[1,0]
	v_pk_mul_f32 v[156:157], v[156:157], s[18:19] op_sel_hi:[1,0]
	v_pk_mul_f32 v[158:159], v[134:135], s[18:19] op_sel_hi:[1,0]
	v_pk_mul_f32 v[124:125], v[124:125], s[18:19] op_sel_hi:[1,0]
	v_cvt_pk_bf16_f32 v134, v156, v157
	v_cvt_pk_bf16_f32 v135, v136, v137
	v_cvt_pk_bf16_f32 v136, v124, v125
	v_cvt_pk_bf16_f32 v137, v158, v159
	v_mul_f32_e32 v112, v112, v122
	v_mul_f32_e32 v113, v113, v122
	v_mul_f32_e32 v110, v110, v122
	v_mul_f32_e32 v111, v111, v122
	v_mul_f32_e32 v108, v108, v122
	v_mul_f32_e32 v109, v109, v122
	s_and_b64 vcc, exec, s[0:1]
	v_mul_f32_e32 v106, v106, v122
	v_mul_f32_e32 v107, v107, v122
	global_store_dwordx4 v[154:155], v[134:137], off offset:256
	s_cbranch_vccnz .LBB0_475
	ds_bpermute_b32 v123, v217, v106
	v_mov_b32_e32 v136, v106
	s_waitcnt vmcnt(3)
	v_mov_b32_e32 v137, v90
	v_mov_b32_e32 v134, v94
	v_mov_b32_e32 v154, v107
	s_waitcnt lgkmcnt(0)
	v_mul_f32_e32 v135, v168, v123
	v_mul_f32_e32 v106, v90, v135
	v_fma_f32 v134, v136, v134, v106
	v_fma_f32 v135, v137, v135, v106
	ds_bpermute_b32 v106, v217, v107
	v_mov_b32_e32 v155, v91
	v_mov_b32_e32 v136, v95
	ds_bpermute_b32 v123, v217, v108
	ds_bpermute_b32 v124, v217, v110
	s_waitcnt lgkmcnt(2)
	v_mul_f32_e32 v137, v168, v106
	v_mul_f32_e32 v106, v107, v95
	v_fma_f32 v107, v155, v137, v106
	v_fma_f32 v106, v154, v136, v106
	ds_bpermute_b32 v106, v217, v112
	s_waitcnt lgkmcnt(2)
	v_mul_f32_e32 v155, v168, v123
	ds_bpermute_b32 v125, v217, v111
	v_mov_b32_e32 v156, v108
	v_mov_b32_e32 v157, v92
	s_waitcnt lgkmcnt(1)
	v_mul_f32_e32 v106, v168, v106
	s_waitcnt vmcnt(2)
	v_mul_f32_e32 v136, v104, v106
	v_mov_b32_e32 v154, v96
	v_mul_f32_e32 v106, v92, v155
	v_fma_f32 v154, v156, v154, v106
	v_fma_f32 v155, v157, v155, v106
	ds_bpermute_b32 v106, v217, v113
	ds_bpermute_b32 v108, v217, v109
	v_mul_f32_e32 v110, v110, v98
	v_mul_f32_e32 v111, v111, v99
	s_waitcnt lgkmcnt(2)
	v_mul_f32_e32 v124, v168, v124
	v_mul_f32_e32 v125, v169, v125
	v_mov_b32_e32 v158, v113
	s_waitcnt lgkmcnt(1)
	v_mul_f32_e32 v157, v168, v106
	v_mov_b32_e32 v159, v105
	v_mov_b32_e32 v156, v101
	v_fma_f32 v110, v102, v124, v110
	v_fma_f32 v111, v103, v125, v111
	s_waitcnt lgkmcnt(0)
	v_mul_f32_e32 v125, v168, v108
	v_mul_f32_e32 v156, v158, v156
	v_mul_f32_e32 v157, v159, v157
	v_mov_b32_e32 v108, v109
	v_mov_b32_e32 v109, v93
	v_mov_b32_e32 v124, v97
	v_mul_f32_e32 v106, v93, v125
	v_mul_f32_e32 v112, v112, v100
	v_mov_b32_e32 v113, v156
	v_mov_b32_e32 v137, v157
	v_fma_f32 v124, v108, v124, v106
	v_fma_f32 v125, v109, v125, v106
	v_add_f32_e32 v112, v112, v136
	v_add_f32_e32 v113, v113, v137
	v_mov_b32_e32 v106, v134
	v_mov_b32_e32 v108, v154
	v_mov_b32_e32 v109, v124
.LBB0_475:
	s_nop 0
	v_pk_mul_f32 v[134:135], v[106:107], s[18:19] op_sel_hi:[1,0]
	v_mov_b64_e32 v[106:107], s[44:45]
	v_pk_mul_f32 v[112:113], v[112:113], s[18:19] op_sel_hi:[1,0]
	v_pk_mul_f32 v[110:111], v[110:111], s[18:19] op_sel_hi:[1,0]
	v_pk_mul_f32 v[124:125], v[108:109], s[18:19] op_sel_hi:[1,0]
	v_mad_i64_i32 v[106:107], s[4:5], v182, s33, v[106:107]
	v_lshl_add_u64 v[106:107], v[180:181], 1, v[106:107]
	v_cvt_pk_bf16_f32 v108, v110, v111
	v_cvt_pk_bf16_f32 v109, v112, v113
	v_cvt_pk_bf16_f32 v110, v134, v135
	v_cvt_pk_bf16_f32 v111, v124, v125
	v_mov_b32_e32 v123, v122
	global_store_dwordx4 v[106:107], v[108:111], off
	v_mul_f32_e32 v70, v70, v122
	v_mul_f32_e32 v71, v71, v123
	s_and_b64 vcc, exec, s[38:39]
	v_mov_b32_e32 v108, v122
	v_mov_b32_e32 v109, v122
	v_mul_f32_e32 v72, v72, v108
	v_mul_f32_e32 v73, v73, v109
	v_mul_f32_e32 v68, v68, v108
	v_mul_f32_e32 v69, v69, v109
	v_mul_f32_e32 v66, v66, v122
	v_mul_f32_e32 v67, v67, v123
	s_cbranch_vccnz .LBB0_477
	ds_bpermute_b32 v109, v217, v66
	v_mov_b32_e32 v112, v66
	s_waitcnt vmcnt(4)
	v_mov_b32_e32 v113, v90
	v_mov_b32_e32 v110, v94
	v_mov_b32_e32 v122, v67
	s_waitcnt lgkmcnt(0)
	v_mul_f32_e32 v111, v168, v109
	v_mul_f32_e32 v66, v90, v111
	v_fma_f32 v110, v112, v110, v66
	v_fma_f32 v111, v113, v111, v66
	ds_bpermute_b32 v66, v217, v67
	v_mov_b32_e32 v123, v91
	v_mov_b32_e32 v112, v95
	ds_bpermute_b32 v111, v217, v68
	ds_bpermute_b32 v108, v217, v70
	s_waitcnt lgkmcnt(2)
	v_mul_f32_e32 v113, v168, v66
	v_mul_f32_e32 v66, v67, v95
	v_fma_f32 v67, v123, v113, v66
	v_fma_f32 v66, v122, v112, v66
	ds_bpermute_b32 v66, v217, v72
	s_waitcnt lgkmcnt(2)
	v_mul_f32_e32 v123, v168, v111
	ds_bpermute_b32 v109, v217, v71
	v_mov_b32_e32 v124, v68
	v_mov_b32_e32 v125, v92
	s_waitcnt lgkmcnt(1)
	v_mul_f32_e32 v66, v168, v66
	s_waitcnt vmcnt(3)
	v_mul_f32_e32 v112, v104, v66
	v_mov_b32_e32 v122, v96
	v_mul_f32_e32 v66, v92, v123
	v_fma_f32 v122, v124, v122, v66
	v_fma_f32 v123, v125, v123, v66
	ds_bpermute_b32 v66, v217, v73
	ds_bpermute_b32 v68, v217, v69
	v_mul_f32_e32 v70, v70, v98
	v_mul_f32_e32 v71, v71, v99
	s_waitcnt lgkmcnt(2)
	v_mul_f32_e32 v108, v168, v108
	v_mul_f32_e32 v109, v169, v109
	v_mov_b32_e32 v134, v73
	s_waitcnt lgkmcnt(1)
	v_mul_f32_e32 v125, v168, v66
	v_mov_b32_e32 v135, v105
	v_mov_b32_e32 v124, v101
	v_fma_f32 v70, v102, v108, v70
	v_fma_f32 v71, v103, v109, v71
	s_waitcnt lgkmcnt(0)
	v_mul_f32_e32 v109, v168, v68
	v_mul_f32_e32 v124, v134, v124
	v_mul_f32_e32 v125, v135, v125
	v_mov_b32_e32 v68, v69
	v_mov_b32_e32 v69, v93
	v_mov_b32_e32 v108, v97
	v_mul_f32_e32 v66, v93, v109
	v_mul_f32_e32 v72, v72, v100
	v_mov_b32_e32 v73, v124
	v_mov_b32_e32 v113, v125
	v_fma_f32 v108, v68, v108, v66
	v_fma_f32 v109, v69, v109, v66
	v_add_f32_e32 v72, v72, v112
	v_add_f32_e32 v73, v73, v113
	v_mov_b32_e32 v66, v110
	v_mov_b32_e32 v68, v122
	v_mov_b32_e32 v69, v108

;     __device__ __forceinline__ void rope8(f32x4& v0, f32x4& v1, const f32x4 (&c)[4], int fq) const {
;         const float sg = (fq < 2) ? -1.f : 1.f;
; #pragma unroll
;         for (int e = 0; e < 4; ++e) {
;             const float p0 = __shfl_xor(v0[e], 32), p1 = __shfl_xor(v1[e], 32);
;             v0[e] = v0[e] * c[0][e] + sg * p0 * c[2][e]; v1[e] = v1[e] * c[1][e] + sg * p1 * c[3][e];
;         }
;     }
;     __device__ __forceinline__ void operator()(const f32x4 (&acc)[2][2][4][2], const Unit& u, int wr, int wc, int fr, int fq) const {
;     ...
;                     f32x4 v0 = acc[ai][bj][m][0] * rs1, v1 = acc[ai][bj][m][1] * rs1;
;                     if (mode == EP_PLAIN) { store8(O + (size_t)row * ldc + col8, v0, v1); }
;                     else if (mode == EP_RELU2) {
; #pragma unroll
;                         for (int e = 0; e < 4; ++e) { float a = fmaxf(v0[e], 0.f), b = fmaxf(v1[e], 0.f); v0[e] = a * a; v1[e] = b * b; }
;                         store8(O + (size_t)row * ldc + col8, v0, v1);
;                     } else if (mode == EP_Z1) {
;                         const int grp = grp0 + bj * 4;
;                         if (grp >= 20 && grp < 24) {
;                             const int b = row / SEQ, s = row % SEQ, kvh = wc >> 1;
;                             storeT(O2 + (size_t)(b * 2 + kvh) * 64 * SEQ, (wc & 1) * 32 + 8 * fq, s, v0, v1);
;                         } else if (grp == 44) {
;                             rope8(v0, v1, cst[m], fq);
;                             bf16_t* kr = O3 + (size_t)row * NQB + 64 + 8 * fq;
; #pragma unroll
;                             for (int h = 0; h < 8; ++h) store8(kr + h * 96, v0, v1);
;                         } else if (grp < 44) {
;                             if (grp < 16) { v0 = v0 * QA_SCALE; v1 = v1 * QA_SCALE; }
;                             store8(O + (size_t)row * ldc + col8, v0, v1);
;                             if (grp >= 24) {
;                                 float q = (v0[0] * v0[0] + v0[1] * v0[1]) + (v0[2] * v0[2] + v0[3] * v0[3]) + (v1[0] * v1[0] + v1[1] * v1[1]) + (v1[2] * v1[2] + v1[3] * v1[3]);
;                                 q += __shfl_xor(q, 16); q += __shfl_xor(q, 32);
;                                 if (fq == 0) ss_out[(size_t)row * 32 + grp - 24] = q;
;                             }
;                         }
;                     } else if (mode == EP_QB) {
.LBB0_479:
	s_waitcnt lgkmcnt(3)
	v_add_f32_e32 v67, v204, v205
	v_fmamk_f32 v67, v67, 0x3b2aaaab, v195
	v_rsq_f32_e32 v68, v67
	s_and_b64 vcc, exec, s[0:1]
	v_mul_f32_e32 v64, v64, v68
	v_mul_f32_e32 v65, v65, v68
	v_mul_f32_e32 v62, v62, v68
	v_mul_f32_e32 v63, v63, v68
	v_mul_f32_e32 v60, v60, v68
	v_mul_f32_e32 v61, v61, v68
	v_mul_f32_e32 v58, v58, v68
	v_mul_f32_e32 v59, v59, v68
	s_cbranch_vccnz .LBB0_481
	ds_bpermute_b32 v67, v217, v58
	v_mov_b32_e32 v106, v58
	s_waitcnt vmcnt(5)
	v_mov_b32_e32 v107, v118
	v_mov_b32_e32 v72, v114
	v_mov_b32_e32 v108, v59
	s_waitcnt lgkmcnt(0)
	v_mul_f32_e32 v73, v168, v67
	v_mul_f32_e32 v58, v118, v73
	v_fma_f32 v72, v106, v72, v58
	v_fma_f32 v73, v107, v73, v58
	ds_bpermute_b32 v58, v217, v59
	v_mov_b32_e32 v109, v119
	v_mov_b32_e32 v106, v115
	ds_bpermute_b32 v67, v217, v60
	ds_bpermute_b32 v70, v217, v62
	s_waitcnt lgkmcnt(2)
	v_mul_f32_e32 v107, v168, v58
	v_mul_f32_e32 v58, v59, v115
	v_fma_f32 v59, v109, v107, v58
	v_fma_f32 v58, v108, v106, v58
	ds_bpermute_b32 v58, v217, v64
	s_waitcnt lgkmcnt(2)
	v_mul_f32_e32 v109, v168, v67
	ds_bpermute_b32 v71, v217, v63
	v_mov_b32_e32 v110, v60
	v_mov_b32_e32 v111, v120
	s_waitcnt lgkmcnt(1)
	v_mul_f32_e32 v58, v168, v58
	s_waitcnt vmcnt(4)
	v_mul_f32_e32 v106, v132, v58
	v_mov_b32_e32 v108, v116
	v_mul_f32_e32 v58, v120, v109
	v_fma_f32 v108, v110, v108, v58
	v_fma_f32 v109, v111, v109, v58
	ds_bpermute_b32 v58, v217, v65
	ds_bpermute_b32 v60, v217, v61
	v_mul_f32_e32 v62, v62, v126
	v_mul_f32_e32 v63, v63, v127
	s_waitcnt lgkmcnt(2)
	v_mul_f32_e32 v70, v168, v70
	v_mul_f32_e32 v71, v169, v71
	v_mov_b32_e32 v112, v65
	s_waitcnt lgkmcnt(1)
	v_mul_f32_e32 v111, v168, v58
	v_mov_b32_e32 v113, v133
	v_mov_b32_e32 v110, v129
	v_fma_f32 v62, v130, v70, v62
	v_fma_f32 v63, v131, v71, v63
	s_waitcnt lgkmcnt(0)
	v_mul_f32_e32 v71, v168, v60
	v_mul_f32_e32 v110, v112, v110
	v_mul_f32_e32 v111, v113, v111
	v_mov_b32_e32 v60, v61
	v_mov_b32_e32 v61, v121
	v_mov_b32_e32 v70, v117
	v_mul_f32_e32 v58, v121, v71
	v_mul_f32_e32 v64, v64, v128
	v_mov_b32_e32 v65, v110
	v_mov_b32_e32 v107, v111
	v_fma_f32 v70, v60, v70, v58
	v_fma_f32 v71, v61, v71, v58
	v_add_f32_e32 v64, v64, v106
	v_add_f32_e32 v65, v65, v107
	v_mov_b32_e32 v58, v72
	v_mov_b32_e32 v60, v108
	v_mov_b32_e32 v61, v70
.LBB0_481:
	v_pk_mul_f32 v[72:73], v[58:59], s[18:19] op_sel_hi:[1,0]
	v_mov_b64_e32 v[58:59], s[44:45]
	v_pk_mul_f32 v[64:65], v[64:65], s[18:19] op_sel_hi:[1,0]
	v_pk_mul_f32 v[62:63], v[62:63], s[18:19] op_sel_hi:[1,0]
	v_pk_mul_f32 v[70:71], v[60:61], s[18:19] op_sel_hi:[1,0]
	v_mad_i64_i32 v[58:59], s[4:5], v66, s33, v[58:59]
	v_lshl_add_u64 v[58:59], v[180:181], 1, v[58:59]
	v_cvt_pk_bf16_f32 v60, v62, v63
	v_cvt_pk_bf16_f32 v61, v64, v65
	v_cvt_pk_bf16_f32 v62, v72, v73
	v_cvt_pk_bf16_f32 v63, v70, v71
	v_mov_b32_e32 v69, v68
	global_store_dwordx4 v[58:59], v[60:63], off
	s_and_b64 vcc, exec, s[38:39]
	s_nop 0
	v_mov_b32_e32 v62, v68
	v_mov_b32_e32 v63, v68
	v_mul_f32_e32 v56, v56, v62
	v_mul_f32_e32 v57, v57, v63
	v_mul_f32_e32 v60, v54, v68
	v_mul_f32_e32 v61, v55, v69
	v_mul_f32_e32 v54, v52, v62
	v_mul_f32_e32 v55, v53, v63
	v_mul_f32_e32 v52, v50, v68
	v_mul_f32_e32 v53, v51, v69
	s_cbranch_vccnz .LBB0_483
	ds_bpermute_b32 v51, v217, v52
	v_mov_b32_e32 v64, v52
	s_waitcnt vmcnt(6)
	v_mov_b32_e32 v65, v118
	v_mov_b32_e32 v62, v114
	ds_bpermute_b32 v50, v217, v60
	s_waitcnt lgkmcnt(1)
	v_mul_f32_e32 v63, v168, v51
	v_mul_f32_e32 v52, v118, v63
	v_fma_f32 v62, v64, v62, v52
	v_fma_f32 v63, v65, v63, v52
	ds_bpermute_b32 v52, v217, v53
	v_mov_b32_e32 v118, v53
	v_mov_b32_e32 v64, v115
	ds_bpermute_b32 v63, v217, v54
	ds_bpermute_b32 v51, v217, v61
	s_waitcnt lgkmcnt(2)
	v_mul_f32_e32 v65, v168, v52
	v_mul_f32_e32 v52, v53, v115
	v_fma_f32 v53, v119, v65, v52
	v_fma_f32 v52, v118, v64, v52
	ds_bpermute_b32 v52, v217, v56
	s_waitcnt lgkmcnt(2)
	v_mul_f32_e32 v67, v168, v63
	v_mov_b32_e32 v68, v54
	v_mov_b32_e32 v69, v120
	v_mov_b32_e32 v66, v116
	s_waitcnt lgkmcnt(0)
	v_mul_f32_e32 v52, v168, v52
	s_waitcnt vmcnt(5)
	v_mul_f32_e32 v64, v132, v52
	v_mul_f32_e32 v52, v120, v67
	v_fma_f32 v66, v68, v66, v52
	v_fma_f32 v67, v69, v67, v52
	ds_bpermute_b32 v52, v217, v57
	ds_bpermute_b32 v54, v217, v55
	v_mul_f32_e32 v60, v60, v126
	v_mul_f32_e32 v61, v61, v127
	v_mul_f32_e32 v50, v168, v50
	v_mul_f32_e32 v51, v169, v51
	v_mov_b32_e32 v132, v57
	s_waitcnt lgkmcnt(1)
	v_mul_f32_e32 v69, v168, v52
	v_mov_b32_e32 v68, v129
	v_fma_f32 v60, v130, v50, v60
	v_fma_f32 v61, v131, v51, v61
	s_waitcnt lgkmcnt(0)
	v_mul_f32_e32 v51, v168, v54
	v_mul_f32_e32 v68, v132, v68
	v_mul_f32_e32 v69, v133, v69
	v_mov_b32_e32 v120, v55
	v_mov_b32_e32 v50, v117
	v_mul_f32_e32 v52, v121, v51
	v_mul_f32_e32 v56, v56, v128
	v_mov_b32_e32 v57, v68
	v_mov_b32_e32 v65, v69
	v_fma_f32 v50, v120, v50, v52
	v_fma_f32 v51, v121, v51, v52
	v_add_f32_e32 v56, v56, v64
	v_add_f32_e32 v57, v57, v65
	v_mov_b32_e32 v52, v62
	v_mov_b32_e32 v54, v66
	v_mov_b32_e32 v55, v50
;     __device__ __forceinline__ void rope8(f32x4& v0, f32x4& v1, const f32x4 (&c)[4], int fq) const {
;         const float sg = (fq < 2) ? -1.f : 1.f;
; #pragma unroll
;         for (int e = 0; e < 4; ++e) {
;             const float p0 = __shfl_xor(v0[e], 32), p1 = __shfl_xor(v1[e], 32);
;             v0[e] = v0[e] * c[0][e] + sg * p0 * c[2][e]; v1[e] = v1[e] * c[1][e] + sg * p1 * c[3][e];
;         }
;     }
;     __device__ __forceinline__ void operator()(const f32x4 (&acc)[2][2][4][2], const Unit& u, int wr, int wc, int fr, int fq) const {
;     ...
;                     f32x4 v0 = acc[ai][bj][m][0] * rs1, v1 = acc[ai][bj][m][1] * rs1;
;                     if (mode == EP_PLAIN) { store8(O + (size_t)row * ldc + col8, v0, v1); }
;                     else if (mode == EP_RELU2) {
; #pragma unroll
;                         for (int e = 0; e < 4; ++e) { float a = fmaxf(v0[e], 0.f), b = fmaxf(v1[e], 0.f); v0[e] = a * a; v1[e] = b * b; }
;                         store8(O + (size_t)row * ldc + col8, v0, v1);
;                     } else if (mode == EP_Z1) {
;                         const int grp = grp0 + bj * 4;
;                         if (grp >= 20 && grp < 24) {
;                             const int b = row / SEQ, s = row % SEQ, kvh = wc >> 1;
;                             storeT(O2 + (size_t)(b * 2 + kvh) * 64 * SEQ, (wc & 1) * 32 + 8 * fq, s, v0, v1);
;                         } else if (grp == 44) {
;                             rope8(v0, v1, cst[m], fq);
;                             bf16_t* kr = O3 + (size_t)row * NQB + 64 + 8 * fq;
; #pragma unroll
;                             for (int h = 0; h < 8; ++h) store8(kr + h * 96, v0, v1);
;                         } else if (grp < 44) {
;                             if (grp < 16) { v0 = v0 * QA_SCALE; v1 = v1 * QA_SCALE; }
;                             store8(O + (size_t)row * ldc + col8, v0, v1);
;                             if (grp >= 24) {
;                                 float q = (v0[0] * v0[0] + v0[1] * v0[1]) + (v0[2] * v0[2] + v0[3] * v0[3]) + (v1[0] * v1[0] + v1[1] * v1[1]) + (v1[2] * v1[2] + v1[3] * v1[3]);
;                                 q += __shfl_xor(q, 16); q += __shfl_xor(q, 32);
;                                 if (fq == 0) ss_out[(size_t)row * 32 + grp - 24] = q;
;                             }
;                         }
;                     } else if (mode == EP_QB) {
.LBB0_483:
	s_waitcnt lgkmcnt(2)
	v_add_f32_e32 v50, v202, v203
	v_fmamk_f32 v50, v50, 0x3b2aaaab, v195
	v_rsq_f32_e32 v50, v50
	v_pk_mul_f32 v[56:57], v[56:57], s[18:19] op_sel_hi:[1,0]
	v_pk_mul_f32 v[60:61], v[60:61], s[18:19] op_sel_hi:[1,0]
	v_pk_mul_f32 v[62:63], v[54:55], s[18:19] op_sel_hi:[1,0]
	v_pk_mul_f32 v[54:55], v[52:53], s[18:19] op_sel_hi:[1,0]
	v_cvt_pk_bf16_f32 v52, v60, v61
	v_cvt_pk_bf16_f32 v53, v56, v57
	v_cvt_pk_bf16_f32 v54, v54, v55
	v_cvt_pk_bf16_f32 v55, v62, v63
	v_mul_f32_e32 v48, v48, v50
	v_mul_f32_e32 v49, v49, v50
	v_mul_f32_e32 v46, v46, v50
	v_mul_f32_e32 v47, v47, v50
	v_mul_f32_e32 v44, v44, v50
	v_mul_f32_e32 v45, v45, v50
	s_and_b64 vcc, exec, s[0:1]
	v_mul_f32_e32 v42, v42, v50
	v_mul_f32_e32 v43, v43, v50
	global_store_dwordx4 v[58:59], v[52:55], off offset:256
	s_cbranch_vccnz .LBB0_485
	ds_bpermute_b32 v51, v217, v42
	v_mov_b32_e32 v56, v42
	s_waitcnt vmcnt(4)
	v_mov_b32_e32 v57, v74
	s_waitcnt vmcnt(3)
	v_mov_b32_e32 v54, v78
	v_mov_b32_e32 v58, v43
	s_waitcnt lgkmcnt(0)
	v_mul_f32_e32 v55, v168, v51
	v_mul_f32_e32 v42, v74, v55
	v_fma_f32 v54, v56, v54, v42
	v_fma_f32 v55, v57, v55, v42
	ds_bpermute_b32 v42, v217, v43
	v_mov_b32_e32 v59, v75
	v_mov_b32_e32 v56, v79
	ds_bpermute_b32 v51, v217, v44
	ds_bpermute_b32 v52, v217, v46
	s_waitcnt lgkmcnt(2)
	v_mul_f32_e32 v57, v168, v42
	v_mul_f32_e32 v42, v43, v79
	v_fma_f32 v43, v59, v57, v42
	v_fma_f32 v42, v58, v56, v42
	ds_bpermute_b32 v42, v217, v48
	s_waitcnt lgkmcnt(2)
	v_mul_f32_e32 v59, v168, v51
	ds_bpermute_b32 v53, v217, v47
	v_mov_b32_e32 v60, v44
	v_mov_b32_e32 v61, v76
	s_waitcnt lgkmcnt(1)
	v_mul_f32_e32 v42, v168, v42
	s_waitcnt vmcnt(2)
	v_mul_f32_e32 v56, v88, v42
	v_mov_b32_e32 v58, v80
	v_mul_f32_e32 v42, v76, v59
	v_fma_f32 v58, v60, v58, v42
	v_fma_f32 v59, v61, v59, v42
	ds_bpermute_b32 v42, v217, v49
	ds_bpermute_b32 v44, v217, v45
	v_mul_f32_e32 v46, v46, v82
	v_mul_f32_e32 v47, v47, v83
	s_waitcnt lgkmcnt(2)
	v_mul_f32_e32 v52, v168, v52
	v_mul_f32_e32 v53, v169, v53
	v_mov_b32_e32 v62, v49
	s_waitcnt lgkmcnt(1)
	v_mul_f32_e32 v61, v168, v42
	v_mov_b32_e32 v63, v89
	v_mov_b32_e32 v60, v85
	v_fma_f32 v46, v86, v52, v46
	v_fma_f32 v47, v87, v53, v47
	s_waitcnt lgkmcnt(0)
	v_mul_f32_e32 v53, v168, v44
	v_mul_f32_e32 v60, v62, v60
	v_mul_f32_e32 v61, v63, v61
	v_mov_b32_e32 v44, v45
	v_mov_b32_e32 v45, v77
	v_mov_b32_e32 v52, v81
	v_mul_f32_e32 v42, v77, v53
	v_mul_f32_e32 v48, v48, v84
	v_mov_b32_e32 v49, v60
	v_mov_b32_e32 v57, v61
	v_fma_f32 v52, v44, v52, v42
	v_fma_f32 v53, v45, v53, v42
	v_add_f32_e32 v48, v48, v56
	v_add_f32_e32 v49, v49, v57
	v_mov_b32_e32 v42, v54
	v_mov_b32_e32 v44, v58
	v_mov_b32_e32 v45, v52
.LBB0_485:
	v_add_u32_e32 v56, 0x90, v178
	v_pk_mul_f32 v[54:55], v[42:43], s[18:19] op_sel_hi:[1,0]
	v_mov_b64_e32 v[42:43], s[44:45]
	v_pk_mul_f32 v[48:49], v[48:49], s[18:19] op_sel_hi:[1,0]
	v_pk_mul_f32 v[46:47], v[46:47], s[18:19] op_sel_hi:[1,0]
	v_pk_mul_f32 v[52:53], v[44:45], s[18:19] op_sel_hi:[1,0]
	v_mad_i64_i32 v[42:43], s[4:5], v56, s33, v[42:43]
	v_lshl_add_u64 v[42:43], v[180:181], 1, v[42:43]
	v_cvt_pk_bf16_f32 v44, v46, v47
	v_cvt_pk_bf16_f32 v45, v48, v49
	v_cvt_pk_bf16_f32 v46, v54, v55
	v_cvt_pk_bf16_f32 v47, v52, v53
	v_mov_b32_e32 v51, v50
	global_store_dwordx4 v[42:43], v[44:47], off
	v_mul_f32_e32 v38, v38, v50
	v_mul_f32_e32 v39, v39, v51
	s_and_b64 vcc, exec, s[38:39]
	v_mov_b32_e32 v44, v50
	v_mov_b32_e32 v45, v50
	v_mul_f32_e32 v40, v40, v44
	v_mul_f32_e32 v41, v41, v45
	v_mul_f32_e32 v36, v36, v44
	v_mul_f32_e32 v37, v37, v45
	v_mul_f32_e32 v34, v34, v50
	v_mul_f32_e32 v35, v35, v51
	s_cbranch_vccnz .LBB0_487
	ds_bpermute_b32 v45, v217, v34
	v_mov_b32_e32 v48, v34
	s_waitcnt vmcnt(5)
	v_mov_b32_e32 v49, v74
	s_waitcnt vmcnt(4)
	v_mov_b32_e32 v46, v78
	ds_bpermute_b32 v44, v217, v38
	s_waitcnt lgkmcnt(1)
	v_mul_f32_e32 v47, v168, v45
	v_mul_f32_e32 v34, v74, v47
	v_fma_f32 v46, v48, v46, v34
	v_fma_f32 v47, v49, v47, v34
	ds_bpermute_b32 v34, v217, v35
	v_mov_b32_e32 v74, v35
	v_mov_b32_e32 v48, v79
	ds_bpermute_b32 v47, v217, v36
	ds_bpermute_b32 v45, v217, v39
	s_waitcnt lgkmcnt(2)
	v_mul_f32_e32 v49, v168, v34
	v_mul_f32_e32 v34, v35, v79
	v_fma_f32 v35, v75, v49, v34
	v_fma_f32 v34, v74, v48, v34
	ds_bpermute_b32 v34, v217, v40
	s_waitcnt lgkmcnt(2)
	v_mul_f32_e32 v51, v168, v47
	v_mov_b32_e32 v52, v36
	v_mov_b32_e32 v53, v76
	v_mov_b32_e32 v50, v80
	s_waitcnt lgkmcnt(0)
	v_mul_f32_e32 v34, v168, v34
	s_waitcnt vmcnt(3)
	v_mul_f32_e32 v48, v88, v34
	v_mul_f32_e32 v34, v76, v51
	v_fma_f32 v50, v52, v50, v34
	v_fma_f32 v51, v53, v51, v34
	ds_bpermute_b32 v34, v217, v41
	ds_bpermute_b32 v36, v217, v37
	v_mul_f32_e32 v38, v38, v82
	v_mul_f32_e32 v39, v39, v83
	v_mul_f32_e32 v44, v168, v44
	v_mul_f32_e32 v45, v169, v45
	v_mov_b32_e32 v88, v41
	s_waitcnt lgkmcnt(1)
	v_mul_f32_e32 v53, v168, v34
	v_mov_b32_e32 v52, v85
	v_fma_f32 v38, v86, v44, v38
	v_fma_f32 v39, v87, v45, v39
	s_waitcnt lgkmcnt(0)
	v_mul_f32_e32 v45, v168, v36
	v_mul_f32_e32 v52, v88, v52
	v_mul_f32_e32 v53, v89, v53
	v_mov_b32_e32 v76, v37
	v_mov_b32_e32 v44, v81
	v_mul_f32_e32 v34, v77, v45
	v_mul_f32_e32 v40, v40, v84
	v_mov_b32_e32 v41, v52
	v_mov_b32_e32 v49, v53
	v_fma_f32 v44, v76, v44, v34
	v_fma_f32 v45, v77, v45, v34
	v_add_f32_e32 v40, v40, v48
	v_add_f32_e32 v41, v41, v49
	v_mov_b32_e32 v34, v46
	v_mov_b32_e32 v36, v50
	v_mov_b32_e32 v37, v44

;     __device__ __forceinline__ void rope8(f32x4& v0, f32x4& v1, const f32x4 (&c)[4], int fq) const {
;         const float sg = (fq < 2) ? -1.f : 1.f;
; #pragma unroll
;         for (int e = 0; e < 4; ++e) {
;             const float p0 = __shfl_xor(v0[e], 32), p1 = __shfl_xor(v1[e], 32);
;             v0[e] = v0[e] * c[0][e] + sg * p0 * c[2][e]; v1[e] = v1[e] * c[1][e] + sg * p1 * c[3][e];
;         }
;     }
;     __device__ __forceinline__ void operator()(const f32x4 (&acc)[2][2][4][2], const Unit& u, int wr, int wc, int fr, int fq) const {
;     ...
;                     f32x4 v0 = acc[ai][bj][m][0] * rs1, v1 = acc[ai][bj][m][1] * rs1;
;                     if (mode == EP_PLAIN) { store8(O + (size_t)row * ldc + col8, v0, v1); }
;                     else if (mode == EP_RELU2) {
; #pragma unroll
;                         for (int e = 0; e < 4; ++e) { float a = fmaxf(v0[e], 0.f), b = fmaxf(v1[e], 0.f); v0[e] = a * a; v1[e] = b * b; }
;                         store8(O + (size_t)row * ldc + col8, v0, v1);
;                     } else if (mode == EP_Z1) {
;                         const int grp = grp0 + bj * 4;
;                         if (grp >= 20 && grp < 24) {
;                             const int b = row / SEQ, s = row % SEQ, kvh = wc >> 1;
;                             storeT(O2 + (size_t)(b * 2 + kvh) * 64 * SEQ, (wc & 1) * 32 + 8 * fq, s, v0, v1);
;                         } else if (grp == 44) {
;                             rope8(v0, v1, cst[m], fq);
;                             bf16_t* kr = O3 + (size_t)row * NQB + 64 + 8 * fq;
; #pragma unroll
;                             for (int h = 0; h < 8; ++h) store8(kr + h * 96, v0, v1);
;                         } else if (grp < 44) {
;                             if (grp < 16) { v0 = v0 * QA_SCALE; v1 = v1 * QA_SCALE; }
;                             store8(O + (size_t)row * ldc + col8, v0, v1);
;                             if (grp >= 24) {
;                                 float q = (v0[0] * v0[0] + v0[1] * v0[1]) + (v0[2] * v0[2] + v0[3] * v0[3]) + (v1[0] * v1[0] + v1[1] * v1[1]) + (v1[2] * v1[2] + v1[3] * v1[3]);
;                                 q += __shfl_xor(q, 16); q += __shfl_xor(q, 32);
;                                 if (fq == 0) ss_out[(size_t)row * 32 + grp - 24] = q;
;                             }
;                         }
;                     } else if (mode == EP_QB) {
.LBB0_489:
	s_waitcnt lgkmcnt(1)
	v_add_f32_e32 v35, v200, v201
	v_fmamk_f32 v35, v35, 0x3b2aaaab, v195
	v_rsq_f32_e32 v36, v35
	s_and_b64 vcc, exec, s[0:1]
	v_mul_f32_e32 v32, v32, v36
	v_mul_f32_e32 v33, v33, v36
	v_mul_f32_e32 v30, v30, v36
	v_mul_f32_e32 v31, v31, v36
	v_mul_f32_e32 v28, v28, v36
	v_mul_f32_e32 v29, v29, v36
	v_mul_f32_e32 v26, v26, v36
	v_mul_f32_e32 v27, v27, v36
	s_cbranch_vccnz .LBB0_491
	ds_bpermute_b32 v35, v217, v26
	v_mov_b32_e32 v42, v26
	s_waitcnt vmcnt(5)
	v_mov_b32_e32 v43, v142
	v_mov_b32_e32 v40, v138
	v_mov_b32_e32 v44, v27
	s_waitcnt lgkmcnt(0)
	v_mul_f32_e32 v41, v168, v35
	v_mul_f32_e32 v26, v142, v41
	v_fma_f32 v40, v42, v40, v26
	v_fma_f32 v41, v43, v41, v26
	ds_bpermute_b32 v26, v217, v27
	v_mov_b32_e32 v45, v143
	v_mov_b32_e32 v42, v139
	ds_bpermute_b32 v35, v217, v28
	ds_bpermute_b32 v38, v217, v30
	s_waitcnt lgkmcnt(2)
	v_mul_f32_e32 v43, v168, v26
	v_mul_f32_e32 v26, v27, v139
	v_fma_f32 v27, v45, v43, v26
	v_fma_f32 v26, v44, v42, v26
	ds_bpermute_b32 v26, v217, v32
	s_waitcnt lgkmcnt(2)
	v_mul_f32_e32 v45, v168, v35
	ds_bpermute_b32 v39, v217, v31
	v_mov_b32_e32 v46, v28
	v_mov_b32_e32 v47, v144
	s_waitcnt lgkmcnt(1)
	v_mul_f32_e32 v26, v168, v26
	s_waitcnt vmcnt(4)
	v_mul_f32_e32 v42, v152, v26
	v_mov_b32_e32 v44, v140
	v_mul_f32_e32 v26, v144, v45
	v_fma_f32 v44, v46, v44, v26
	v_fma_f32 v45, v47, v45, v26
	ds_bpermute_b32 v26, v217, v33
	ds_bpermute_b32 v28, v217, v29
	v_mul_f32_e32 v30, v30, v146
	v_mul_f32_e32 v31, v31, v147
	s_waitcnt lgkmcnt(2)
	v_mul_f32_e32 v38, v168, v38
	v_mul_f32_e32 v39, v169, v39
	v_mov_b32_e32 v48, v33
	s_waitcnt lgkmcnt(1)
	v_mul_f32_e32 v47, v168, v26
	v_mov_b32_e32 v49, v153
	v_mov_b32_e32 v46, v149
	v_fma_f32 v30, v150, v38, v30
	v_fma_f32 v31, v151, v39, v31
	s_waitcnt lgkmcnt(0)
	v_mul_f32_e32 v39, v168, v28
	v_mul_f32_e32 v46, v48, v46
	v_mul_f32_e32 v47, v49, v47
	v_mov_b32_e32 v28, v29
	v_mov_b32_e32 v29, v145
	v_mov_b32_e32 v38, v141
	v_mul_f32_e32 v26, v145, v39
	v_mul_f32_e32 v32, v32, v148
	v_mov_b32_e32 v33, v46
	v_mov_b32_e32 v43, v47
	v_fma_f32 v38, v28, v38, v26
	v_fma_f32 v39, v29, v39, v26
	v_add_f32_e32 v32, v32, v42
	v_add_f32_e32 v33, v33, v43
	v_mov_b32_e32 v26, v40
	v_mov_b32_e32 v28, v44
	v_mov_b32_e32 v29, v38
.LBB0_491:
	v_pk_mul_f32 v[40:41], v[26:27], s[18:19] op_sel_hi:[1,0]
	v_mov_b64_e32 v[26:27], s[44:45]
	v_pk_mul_f32 v[32:33], v[32:33], s[18:19] op_sel_hi:[1,0]
	v_pk_mul_f32 v[30:31], v[30:31], s[18:19] op_sel_hi:[1,0]
	v_pk_mul_f32 v[38:39], v[28:29], s[18:19] op_sel_hi:[1,0]
	v_mad_i64_i32 v[26:27], s[4:5], v34, s33, v[26:27]
	v_lshl_add_u64 v[26:27], v[180:181], 1, v[26:27]
	v_cvt_pk_bf16_f32 v28, v30, v31
	v_cvt_pk_bf16_f32 v29, v32, v33
	v_cvt_pk_bf16_f32 v30, v40, v41
	v_cvt_pk_bf16_f32 v31, v38, v39
	v_mov_b32_e32 v37, v36
	global_store_dwordx4 v[26:27], v[28:31], off
	s_and_b64 vcc, exec, s[38:39]
	s_nop 0
	v_mov_b32_e32 v30, v36
	v_mov_b32_e32 v31, v36
	v_mul_f32_e32 v24, v24, v30
	v_mul_f32_e32 v25, v25, v31
	v_mul_f32_e32 v28, v22, v36
	v_mul_f32_e32 v29, v23, v37
	v_mul_f32_e32 v22, v20, v30
	v_mul_f32_e32 v23, v21, v31
	v_mul_f32_e32 v20, v18, v36
	v_mul_f32_e32 v21, v19, v37
	s_cbranch_vccnz .LBB0_493
	ds_bpermute_b32 v19, v217, v20
	v_mov_b32_e32 v32, v20
	s_waitcnt vmcnt(6)
	v_mov_b32_e32 v33, v142
	v_mov_b32_e32 v30, v138
	ds_bpermute_b32 v18, v217, v28
	s_waitcnt lgkmcnt(1)
	v_mul_f32_e32 v31, v168, v19
	v_mul_f32_e32 v20, v142, v31
	v_fma_f32 v30, v32, v30, v20
	v_fma_f32 v31, v33, v31, v20
	ds_bpermute_b32 v20, v217, v21
	v_mov_b32_e32 v142, v21
	v_mov_b32_e32 v32, v139
	ds_bpermute_b32 v31, v217, v22
	ds_bpermute_b32 v19, v217, v29
	s_waitcnt lgkmcnt(2)
	v_mul_f32_e32 v33, v168, v20
	v_mul_f32_e32 v20, v21, v139
	v_fma_f32 v21, v143, v33, v20
	v_fma_f32 v20, v142, v32, v20
	ds_bpermute_b32 v20, v217, v24
	s_waitcnt lgkmcnt(2)
	v_mul_f32_e32 v35, v168, v31
	v_mov_b32_e32 v36, v22
	v_mov_b32_e32 v37, v144
	v_mov_b32_e32 v34, v140
	s_waitcnt lgkmcnt(0)
	v_mul_f32_e32 v20, v168, v20
	s_waitcnt vmcnt(5)
	v_mul_f32_e32 v32, v152, v20
	v_mul_f32_e32 v20, v144, v35
	v_fma_f32 v34, v36, v34, v20
	v_fma_f32 v35, v37, v35, v20
	ds_bpermute_b32 v20, v217, v25
	ds_bpermute_b32 v22, v217, v23
	v_mul_f32_e32 v28, v28, v146
	v_mul_f32_e32 v29, v29, v147
	v_mul_f32_e32 v18, v168, v18
	v_mul_f32_e32 v19, v169, v19
	v_mov_b32_e32 v152, v25
	s_waitcnt lgkmcnt(1)
	v_mul_f32_e32 v37, v168, v20
	v_mov_b32_e32 v36, v149
	v_fma_f32 v28, v150, v18, v28
	v_fma_f32 v29, v151, v19, v29
	s_waitcnt lgkmcnt(0)
	v_mul_f32_e32 v19, v168, v22
	v_mul_f32_e32 v36, v152, v36
	v_mul_f32_e32 v37, v153, v37
	v_mov_b32_e32 v144, v23
	v_mov_b32_e32 v18, v141
	v_mul_f32_e32 v20, v145, v19
	v_mul_f32_e32 v24, v24, v148
	v_mov_b32_e32 v25, v36
	v_mov_b32_e32 v33, v37
	v_fma_f32 v18, v144, v18, v20
	v_fma_f32 v19, v145, v19, v20
	v_add_f32_e32 v24, v24, v32
	v_add_f32_e32 v25, v25, v33
	v_mov_b32_e32 v20, v30
	v_mov_b32_e32 v22, v34
	v_mov_b32_e32 v23, v18
;     __device__ __forceinline__ void rope8(f32x4& v0, f32x4& v1, const f32x4 (&c)[4], int fq) const {
;         const float sg = (fq < 2) ? -1.f : 1.f;
; #pragma unroll
;         for (int e = 0; e < 4; ++e) {
;             const float p0 = __shfl_xor(v0[e], 32), p1 = __shfl_xor(v1[e], 32);
;             v0[e] = v0[e] * c[0][e] + sg * p0 * c[2][e]; v1[e] = v1[e] * c[1][e] + sg * p1 * c[3][e];
;         }
;     }
;     __device__ __forceinline__ void operator()(const f32x4 (&acc)[2][2][4][2], const Unit& u, int wr, int wc, int fr, int fq) const {
;     ...
;                     f32x4 v0 = acc[ai][bj][m][0] * rs1, v1 = acc[ai][bj][m][1] * rs1;
;                     if (mode == EP_PLAIN) { store8(O + (size_t)row * ldc + col8, v0, v1); }
;                     else if (mode == EP_RELU2) {
; #pragma unroll
;                         for (int e = 0; e < 4; ++e) { float a = fmaxf(v0[e], 0.f), b = fmaxf(v1[e], 0.f); v0[e] = a * a; v1[e] = b * b; }
;                         store8(O + (size_t)row * ldc + col8, v0, v1);
;                     } else if (mode == EP_Z1) {
;                         const int grp = grp0 + bj * 4;
;                         if (grp >= 20 && grp < 24) {
;                             const int b = row / SEQ, s = row % SEQ, kvh = wc >> 1;
;                             storeT(O2 + (size_t)(b * 2 + kvh) * 64 * SEQ, (wc & 1) * 32 + 8 * fq, s, v0, v1);
;                         } else if (grp == 44) {
;                             rope8(v0, v1, cst[m], fq);
;                             bf16_t* kr = O3 + (size_t)row * NQB + 64 + 8 * fq;
; #pragma unroll
;                             for (int h = 0; h < 8; ++h) store8(kr + h * 96, v0, v1);
;                         } else if (grp < 44) {
;                             if (grp < 16) { v0 = v0 * QA_SCALE; v1 = v1 * QA_SCALE; }
;                             store8(O + (size_t)row * ldc + col8, v0, v1);
;                             if (grp >= 24) {
;                                 float q = (v0[0] * v0[0] + v0[1] * v0[1]) + (v0[2] * v0[2] + v0[3] * v0[3]) + (v1[0] * v1[0] + v1[1] * v1[1]) + (v1[2] * v1[2] + v1[3] * v1[3]);
;                                 q += __shfl_xor(q, 16); q += __shfl_xor(q, 32);
;                                 if (fq == 0) ss_out[(size_t)row * 32 + grp - 24] = q;
;                             }
;                         }
;                     } else if (mode == EP_QB) {
.LBB0_493:
	s_waitcnt lgkmcnt(0)
	v_add_f32_e32 v18, v198, v199
	v_fmamk_f32 v18, v18, 0x3b2aaaab, v195
	v_rsq_f32_e32 v18, v18
	v_pk_mul_f32 v[24:25], v[24:25], s[18:19] op_sel_hi:[1,0]
	v_pk_mul_f32 v[28:29], v[28:29], s[18:19] op_sel_hi:[1,0]
	v_pk_mul_f32 v[30:31], v[22:23], s[18:19] op_sel_hi:[1,0]
	v_pk_mul_f32 v[22:23], v[20:21], s[18:19] op_sel_hi:[1,0]
	v_cvt_pk_bf16_f32 v20, v28, v29
	v_cvt_pk_bf16_f32 v21, v24, v25
	v_cvt_pk_bf16_f32 v22, v22, v23
	v_cvt_pk_bf16_f32 v23, v30, v31
	v_mul_f32_e32 v16, v16, v18
	v_mul_f32_e32 v17, v17, v18
	v_mul_f32_e32 v14, v14, v18
	v_mul_f32_e32 v15, v15, v18
	v_mul_f32_e32 v12, v12, v18
	v_mul_f32_e32 v13, v13, v18
	s_and_b64 vcc, exec, s[0:1]
	v_mul_f32_e32 v10, v10, v18
	v_mul_f32_e32 v11, v11, v18
	global_store_dwordx4 v[26:27], v[20:23], off offset:256
	s_cbranch_vccnz .LBB0_495
	ds_bpermute_b32 v19, v217, v10
	v_mov_b32_e32 v24, v10
	s_waitcnt vmcnt(4)
	v_mov_b32_e32 v25, v90
	s_waitcnt vmcnt(3)
	v_mov_b32_e32 v22, v94
	v_mov_b32_e32 v26, v11
	s_waitcnt lgkmcnt(0)
	v_mul_f32_e32 v23, v168, v19
	v_mul_f32_e32 v10, v90, v23
	v_fma_f32 v22, v24, v22, v10
	v_fma_f32 v23, v25, v23, v10
	ds_bpermute_b32 v10, v217, v11
	v_mov_b32_e32 v27, v91
	v_mov_b32_e32 v24, v95
	ds_bpermute_b32 v19, v217, v12
	ds_bpermute_b32 v20, v217, v14
	s_waitcnt lgkmcnt(2)
	v_mul_f32_e32 v25, v168, v10
	v_mul_f32_e32 v10, v11, v95
	v_fma_f32 v11, v27, v25, v10
	v_fma_f32 v10, v26, v24, v10
	ds_bpermute_b32 v10, v217, v16
	s_waitcnt lgkmcnt(2)
	v_mul_f32_e32 v27, v168, v19
	ds_bpermute_b32 v21, v217, v15
	v_mov_b32_e32 v28, v12
	v_mov_b32_e32 v29, v92
	s_waitcnt lgkmcnt(1)
	v_mul_f32_e32 v10, v168, v10
	s_waitcnt vmcnt(2)
	v_mul_f32_e32 v24, v104, v10
	v_mov_b32_e32 v26, v96
	v_mul_f32_e32 v10, v92, v27
	v_fma_f32 v26, v28, v26, v10
	v_fma_f32 v27, v29, v27, v10
	ds_bpermute_b32 v10, v217, v17
	ds_bpermute_b32 v12, v217, v13
	v_mul_f32_e32 v14, v14, v98
	v_mul_f32_e32 v15, v15, v99
	s_waitcnt lgkmcnt(2)
	v_mul_f32_e32 v20, v168, v20
	v_mul_f32_e32 v21, v169, v21
	v_mov_b32_e32 v30, v17
	s_waitcnt lgkmcnt(1)
	v_mul_f32_e32 v29, v168, v10
	v_mov_b32_e32 v31, v105
	v_mov_b32_e32 v28, v101
	v_fma_f32 v14, v102, v20, v14
	v_fma_f32 v15, v103, v21, v15
	s_waitcnt lgkmcnt(0)
	v_mul_f32_e32 v21, v168, v12
	v_mul_f32_e32 v28, v30, v28
	v_mul_f32_e32 v29, v31, v29
	v_mov_b32_e32 v12, v13
	v_mov_b32_e32 v13, v93
	v_mov_b32_e32 v20, v97
	v_mul_f32_e32 v10, v93, v21
	v_mul_f32_e32 v16, v16, v100
	v_mov_b32_e32 v17, v28
	v_mov_b32_e32 v25, v29
	v_fma_f32 v20, v12, v20, v10
	v_fma_f32 v21, v13, v21, v10
	v_add_f32_e32 v16, v16, v24
	v_add_f32_e32 v17, v17, v25
	v_mov_b32_e32 v10, v22
	v_mov_b32_e32 v12, v26
	v_mov_b32_e32 v13, v20
.LBB0_495:
	v_add_u32_e32 v24, 0xb0, v178
	v_pk_mul_f32 v[22:23], v[10:11], s[18:19] op_sel_hi:[1,0]
	v_mov_b64_e32 v[10:11], s[44:45]
	v_pk_mul_f32 v[16:17], v[16:17], s[18:19] op_sel_hi:[1,0]
	v_pk_mul_f32 v[14:15], v[14:15], s[18:19] op_sel_hi:[1,0]
	v_pk_mul_f32 v[20:21], v[12:13], s[18:19] op_sel_hi:[1,0]
	v_mad_i64_i32 v[10:11], s[0:1], v24, s33, v[10:11]
	v_lshl_add_u64 v[10:11], v[180:181], 1, v[10:11]
	v_cvt_pk_bf16_f32 v12, v14, v15
	v_cvt_pk_bf16_f32 v13, v16, v17
	v_cvt_pk_bf16_f32 v14, v22, v23
	v_cvt_pk_bf16_f32 v15, v20, v21
	v_mov_b32_e32 v19, v18
	global_store_dwordx4 v[10:11], v[12:15], off
	v_mul_f32_e32 v6, v6, v18
	v_mul_f32_e32 v7, v7, v19
	s_and_b64 vcc, exec, s[38:39]
	v_mov_b32_e32 v12, v18
	v_mov_b32_e32 v13, v18
	v_mul_f32_e32 v8, v8, v12
	v_mul_f32_e32 v9, v9, v13
	v_mul_f32_e32 v4, v4, v12
	v_mul_f32_e32 v5, v5, v13
	v_mul_f32_e32 v2, v2, v18
	v_mul_f32_e32 v3, v3, v19
	s_cbranch_vccnz .LBB0_497
	ds_bpermute_b32 v13, v217, v2
	v_mov_b32_e32 v16, v2
	s_waitcnt vmcnt(5)
	v_mov_b32_e32 v17, v90
	s_waitcnt vmcnt(4)
	v_mov_b32_e32 v14, v94
	ds_bpermute_b32 v12, v217, v6
	s_waitcnt lgkmcnt(1)
	v_mul_f32_e32 v15, v168, v13
	v_mul_f32_e32 v2, v90, v15
	v_fma_f32 v14, v16, v14, v2
	v_fma_f32 v15, v17, v15, v2
	ds_bpermute_b32 v2, v217, v3
	v_mov_b32_e32 v90, v3
	v_mov_b32_e32 v16, v95
	ds_bpermute_b32 v15, v217, v4
	ds_bpermute_b32 v13, v217, v7
	s_waitcnt lgkmcnt(2)
	v_mul_f32_e32 v17, v168, v2
	v_mul_f32_e32 v2, v3, v95
	v_fma_f32 v3, v91, v17, v2
	v_fma_f32 v2, v90, v16, v2
	ds_bpermute_b32 v2, v217, v8
	s_waitcnt lgkmcnt(2)
	v_mul_f32_e32 v19, v168, v15
	v_mov_b32_e32 v20, v4
	v_mov_b32_e32 v21, v92
	v_mov_b32_e32 v18, v96
	s_waitcnt lgkmcnt(0)
	v_mul_f32_e32 v2, v168, v2
	s_waitcnt vmcnt(3)
	v_mul_f32_e32 v16, v104, v2
	v_mul_f32_e32 v2, v92, v19
	v_fma_f32 v18, v20, v18, v2
	v_fma_f32 v19, v21, v19, v2
	ds_bpermute_b32 v2, v217, v9
	ds_bpermute_b32 v4, v217, v5
	v_mul_f32_e32 v6, v6, v98
	v_mul_f32_e32 v7, v7, v99
	v_mul_f32_e32 v12, v168, v12
	v_mul_f32_e32 v13, v169, v13
	v_mov_b32_e32 v104, v9
	s_waitcnt lgkmcnt(1)
	v_mul_f32_e32 v21, v168, v2
	v_mov_b32_e32 v20, v101
	v_fma_f32 v6, v102, v12, v6
	v_fma_f32 v7, v103, v13, v7
	s_waitcnt lgkmcnt(0)
	v_mul_f32_e32 v13, v168, v4
	v_mul_f32_e32 v20, v104, v20
	v_mul_f32_e32 v21, v105, v21
	v_mov_b32_e32 v92, v5
	v_mov_b32_e32 v12, v97
	v_mul_f32_e32 v2, v93, v13
	v_mul_f32_e32 v8, v8, v100
	v_mov_b32_e32 v9, v20
	v_mov_b32_e32 v17, v21
	v_fma_f32 v12, v92, v12, v2
	v_fma_f32 v13, v93, v13, v2
	v_add_f32_e32 v8, v8, v16
	v_add_f32_e32 v9, v9, v17
	v_mov_b32_e32 v2, v14
	v_mov_b32_e32 v4, v18
	v_mov_b32_e32 v5, v12

; __device__ __forceinline__ unsigned pk_bf16(float lo, float hi) { typedef float f2_t __attribute__((ext_vector_type(2))); typedef __bf16 b2_t __attribute__((ext_vector_type(2))); f2_t v = {lo, hi}; b2_t b = __builtin_convertvector(v, b2_t); return __builtin_bit_cast(unsigned, b); }
; __device__ __forceinline__ int vperm16(int s) { return (s & 3) + ((s >> 3) & 1) * 4 + ((s >> 2) & 1) * 8; }
;     __device__ __forceinline__ void storeT(bf16_t* vt  , int d0, int s, f32x4 v0, f32x4 v1) const {
;         const int pos = (s & ~15) + vperm16(s & 15);
; #pragma unroll
;         for (int e = 0; e < 4; ++e) { vt[(size_t)(d0 + e) * SEQ + pos] = (bf16_t)(pk_bf16(v0[e], 0.f) & 0xffffu); vt[(size_t)(d0 + 4 + e) * SEQ + pos] = (bf16_t)(pk_bf16(v1[e], 0.f) & 0xffffu); }
;     }
;     __device__ __forceinline__ void operator()(const f32x4 (&acc)[2][2][4][2], const Unit& u, int wr, int wc, int fr, int fq) const {
;     ...
;             for (int ai = 0; ai < 2; ++ai)
; #pragma unroll
;                 for (int m = 0; m < 4; ++m) {
;                     float t = (part[ai][m][0] + part[ai][m][1]) + (part[ai][m][2] + part[ai][m][3]);
;                     t += __shfl_xor(t, 16); t += __shfl_xor(t, 32);
;                     rsc[ai][m] = __builtin_amdgcn_rsqf(t * rs_inv + EPS);
.LBB0_531:
	s_or_b64 exec, exec, s[0:1]
	v_add_f32_e32 v138, v182, v138
	v_add_f32_e32 v139, v183, v139
	s_mov_b64 s[0:1], -1
	v_add_f32_e32 v0, v138, v139
	ds_bpermute_b32 v138, v216, v0
	s_and_b64 vcc, exec, s[10:11]
	s_waitcnt lgkmcnt(0)
	v_add_f32_e32 v0, v0, v138
	ds_bpermute_b32 v138, v217, v0
	s_waitcnt lgkmcnt(0)
	v_add_f32_e32 v0, v0, v138
	v_fmamk_f32 v0, v0, 0x3b800000, v195
	v_rsq_f32_e32 v138, v0
	s_waitcnt vmcnt(0)
	v_add_f32_e32 v0, v130, v131
	v_add_f32_e32 v130, v132, v133
	v_add_f32_e32 v0, v0, v130
	ds_bpermute_b32 v130, v216, v0
	v_mul_f32_e32 v128, v128, v138
	v_mul_f32_e32 v129, v129, v138
	v_mul_f32_e32 v126, v126, v138
	v_mul_f32_e32 v127, v127, v138
	v_mul_f32_e32 v132, v124, v138
	v_mul_f32_e32 v133, v125, v138
	s_waitcnt lgkmcnt(0)
	v_add_f32_e32 v181, v0, v130
	v_add_f32_e32 v0, v144, v145
	v_add_f32_e32 v130, v146, v147
	v_add_f32_e32 v0, v0, v130
	ds_bpermute_b32 v130, v216, v0
	ds_bpermute_b32 v182, v217, v181
	s_waitcnt lgkmcnt(1)
	v_add_f32_e32 v177, v0, v130
	v_add_f32_e32 v0, v134, v135
	v_add_f32_e32 v130, v136, v137
	v_add_f32_e32 v0, v0, v130
	ds_bpermute_b32 v130, v216, v0
	ds_bpermute_b32 v179, v217, v177
	v_mul_f32_e32 v134, v122, v138
	v_mul_f32_e32 v135, v123, v138
	v_lshlrev_b32_e32 v122, 1, v170
	s_waitcnt lgkmcnt(1)
	v_add_f32_e32 v146, v0, v130
	v_add_f32_e32 v0, v148, v149
	v_add_f32_e32 v130, v150, v151
	v_add_f32_e32 v0, v0, v130
	ds_bpermute_b32 v130, v216, v0
	v_lshrrev_b32_e32 v148, 19, v175
	ds_bpermute_b32 v147, v217, v146
	s_waitcnt lgkmcnt(1)
	v_add_f32_e32 v144, v0, v130
	v_add_f32_e32 v0, v140, v141
	v_add_f32_e32 v130, v142, v143
	v_add_f32_e32 v0, v0, v130
	ds_bpermute_b32 v130, v216, v0
	ds_bpermute_b32 v145, v217, v144
	s_waitcnt lgkmcnt(1)
	v_add_f32_e32 v142, v0, v130
	v_add_f32_e32 v0, v156, v157
	v_add_f32_e32 v130, v158, v159
	v_add_f32_e32 v0, v0, v130
	ds_bpermute_b32 v130, v216, v0
	ds_bpermute_b32 v143, v217, v142
	s_waitcnt lgkmcnt(1)
	v_add_f32_e32 v140, v0, v130
	v_add_f32_e32 v0, v152, v153
	v_add_f32_e32 v130, v154, v155
	v_add_f32_e32 v0, v0, v130
	ds_bpermute_b32 v130, v216, v0
	ds_bpermute_b32 v141, v217, v140
	s_waitcnt lgkmcnt(1)
	v_add_f32_e32 v136, v0, v130
	v_add_u32_e32 v0, v174, v148
	v_ashrrev_i32_e32 v0, 13, v0
	v_mul_i32_i24_e32 v130, 0x2000, v0
	ds_bpermute_b32 v137, v217, v136
	v_sub_u32_e32 v130, v174, v130
	v_lshlrev_b32_e32 v149, 3, v0
	v_lshrrev_b32_e32 v0, 1, v130
	v_lshlrev_b32_e32 v131, 1, v130
	v_and_b32_e32 v0, 4, v0
	v_and_b32_e32 v131, 8, v131
	v_and_b32_e32 v130, 0xffffffc3, v130
	v_or3_b32 v130, v0, v130, v131
	v_ashrrev_i32_e32 v131, 31, v130
	s_cbranch_vccz .LBB0_533
	s_lshl_b32 s46, s67, 1
	v_add_u32_e32 v124, s46, v149
	v_ashrrev_i32_e32 v125, 31, v124
	v_lshlrev_b64 v[124:125], 20, v[124:125]
	v_lshl_add_u64 v[124:125], s[34:35], 0, v[124:125]
	v_lshl_add_u64 v[124:125], v[130:131], 1, v[124:125]
	v_mov_b32_e32 v123, v1
	v_cvt_pk_bf16_f32 v0, v126, s0
	v_lshl_add_u64 v[124:125], v[124:125], 0, v[122:123]
	global_store_short v[124:125], v0, off
	v_cvt_pk_bf16_f32 v0, v134, s0
	s_mov_b32 s0, 0x10000
	v_add_co_u32_e32 v150, vcc, s0, v124
	s_nop 1
	v_addc_co_u32_e32 v151, vcc, 0, v125, vcc
	global_store_short v[150:151], v0, off
	v_cvt_pk_bf16_f32 v0, v127, s0
	s_movk_i32 s0, 0x4000
	v_add_co_u32_e32 v150, vcc, s0, v124
	s_nop 1
	v_addc_co_u32_e32 v151, vcc, 0, v125, vcc
	global_store_short v[150:151], v0, off
	v_cvt_pk_bf16_f32 v0, v135, s0
	s_mov_b32 s0, 0x14000
	v_add_co_u32_e32 v150, vcc, s0, v124
	s_nop 1
	v_addc_co_u32_e32 v151, vcc, 0, v125, vcc
	global_store_short v[150:151], v0, off
	v_cvt_pk_bf16_f32 v0, v128, s0
	s_mov_b32 s0, 0x8000
	v_add_co_u32_e32 v150, vcc, s0, v124
	s_nop 1
	v_addc_co_u32_e32 v151, vcc, 0, v125, vcc
	global_store_short v[150:151], v0, off
	v_cvt_pk_bf16_f32 v0, v132, s0
	s_mov_b32 s0, 0x18000
	v_add_co_u32_e32 v150, vcc, s0, v124
	s_nop 1
	v_addc_co_u32_e32 v151, vcc, 0, v125, vcc
	global_store_short v[150:151], v0, off
	v_add_co_u32_e32 v150, vcc, 0xc000, v124
	v_cvt_pk_bf16_f32 v0, v129, s0
	s_nop 0
	v_addc_co_u32_e32 v151, vcc, 0, v125, vcc
	v_add_co_u32_e32 v124, vcc, 0x1c000, v124
	global_store_short v[150:151], v0, off
	v_cvt_pk_bf16_f32 v0, v133, s0
	v_addc_co_u32_e32 v125, vcc, 0, v125, vcc
	global_store_short v[124:125], v0, off
	s_mov_b64 s[0:1], 0

;     __device__ __forceinline__ void storeT(bf16_t* vt  , int d0, int s, f32x4 v0, f32x4 v1) const {
;         const int pos = (s & ~15) + vperm16(s & 15);
; #pragma unroll
;         for (int e = 0; e < 4; ++e) { vt[(size_t)(d0 + e) * SEQ + pos] = (bf16_t)(pk_bf16(v0[e], 0.f) & 0xffffu); vt[(size_t)(d0 + 4 + e) * SEQ + pos] = (bf16_t)(pk_bf16(v1[e], 0.f) & 0xffffu); }
;     }
;     __device__ __forceinline__ void operator()(const f32x4 (&acc)[2][2][4][2], const Unit& u, int wr, int wc, int fr, int fq) const {
;     ...
;                     f32x4 v0 = acc[ai][bj][m][0] * rs1, v1 = acc[ai][bj][m][1] * rs1;
;                     if (mode == EP_PLAIN) { store8(O + (size_t)row * ldc + col8, v0, v1); }
;                     else if (mode == EP_RELU2) {
; #pragma unroll
;                         for (int e = 0; e < 4; ++e) { float a = fmaxf(v0[e], 0.f), b = fmaxf(v1[e], 0.f); v0[e] = a * a; v1[e] = b * b; }
;                         store8(O + (size_t)row * ldc + col8, v0, v1);
;                     } else if (mode == EP_Z1) {
;                         const int grp = grp0 + bj * 4;
;                         if (grp >= 20 && grp < 24) {
;                             const int b = row / SEQ, s = row % SEQ, kvh = wc >> 1;
;                             storeT(O2 + (size_t)(b * 2 + kvh) * 64 * SEQ, (wc & 1) * 32 + 8 * fq, s, v0, v1);
;                         } else if (grp == 44) {
;                             rope8(v0, v1, cst[m], fq);
;                             bf16_t* kr = O3 + (size_t)row * NQB + 64 + 8 * fq;
; #pragma unroll
;                             for (int h = 0; h < 8; ++h) store8(kr + h * 96, v0, v1);
;                         } else if (grp < 44) {
;                             if (grp < 16) { v0 = v0 * QA_SCALE; v1 = v1 * QA_SCALE; }
;                             store8(O + (size_t)row * ldc + col8, v0, v1);
;                             if (grp >= 24) {
;                                 float q = (v0[0] * v0[0] + v0[1] * v0[1]) + (v0[2] * v0[2] + v0[3] * v0[3]) + (v1[0] * v1[0] + v1[1] * v1[1]) + (v1[2] * v1[2] + v1[3] * v1[3]);
;                                 q += __shfl_xor(q, 16); q += __shfl_xor(q, 32);
;                                 if (fq == 0) ss_out[(size_t)row * 32 + grp - 24] = q;
;                             }
;                         }
;                     } else if (mode == EP_QB) {
.LBB0_535:
	v_mov_b32_e32 v139, v138
	s_nop 0
	v_mov_b32_e32 v126, v138
	v_mov_b32_e32 v127, v138
	v_cndmask_b32_e64 v123, 0, 1, s[10:11]
	v_mul_f32_e32 v120, v120, v126
	v_mul_f32_e32 v121, v121, v127
	v_mul_f32_e32 v118, v118, v138
	v_mul_f32_e32 v119, v119, v139
	v_mul_f32_e32 v116, v116, v126
	v_mul_f32_e32 v117, v117, v127
	v_mul_f32_e32 v114, v114, v138
	v_mul_f32_e32 v115, v115, v139
	s_or_b32 s41, s46, 1
	v_cmp_ne_u32_e64 s[0:1], 1, v123
	s_andn2_b64 vcc, exec, s[10:11]
	s_mov_b64 s[16:17], -1
	s_cbranch_vccnz .LBB0_537
	v_add_u32_e32 v126, s41, v149
	v_ashrrev_i32_e32 v127, 31, v126
	v_lshlrev_b64 v[126:127], 20, v[126:127]
	v_lshl_add_u64 v[126:127], s[34:35], 0, v[126:127]
	v_lshl_add_u64 v[126:127], v[130:131], 1, v[126:127]
	v_mov_b32_e32 v123, v1
	v_cvt_pk_bf16_f32 v128, v118, s0
	v_lshl_add_u64 v[126:127], v[126:127], 0, v[122:123]
	global_store_short v[126:127], v128, off
	v_add_co_u32_e32 v128, vcc, 0x10000, v126
	v_cvt_pk_bf16_f32 v123, v114, s0
	s_nop 0
	v_addc_co_u32_e32 v129, vcc, 0, v127, vcc
	global_store_short v[128:129], v123, off
	v_add_co_u32_e32 v128, vcc, 0x4000, v126
	v_cvt_pk_bf16_f32 v123, v119, s0
	s_nop 0
	v_addc_co_u32_e32 v129, vcc, 0, v127, vcc
	global_store_short v[128:129], v123, off
	v_add_co_u32_e32 v128, vcc, 0x14000, v126
	v_cvt_pk_bf16_f32 v123, v115, s0
	s_nop 0
	v_addc_co_u32_e32 v129, vcc, 0, v127, vcc
	global_store_short v[128:129], v123, off
	v_add_co_u32_e32 v128, vcc, 0x8000, v126
	v_cvt_pk_bf16_f32 v123, v120, s0
	s_nop 0
	v_addc_co_u32_e32 v129, vcc, 0, v127, vcc
	global_store_short v[128:129], v123, off
	v_add_co_u32_e32 v128, vcc, 0x18000, v126
	v_cvt_pk_bf16_f32 v123, v116, s0
	s_nop 0
	v_addc_co_u32_e32 v129, vcc, 0, v127, vcc
	global_store_short v[128:129], v123, off
	v_add_co_u32_e32 v128, vcc, 0xc000, v126
	v_cvt_pk_bf16_f32 v123, v121, s0
	s_nop 0
	v_addc_co_u32_e32 v129, vcc, 0, v127, vcc
	v_add_co_u32_e32 v126, vcc, 0x1c000, v126
	global_store_short v[128:129], v123, off
	v_cvt_pk_bf16_f32 v123, v117, s0
	v_addc_co_u32_e32 v127, vcc, 0, v127, vcc
	s_mov_b64 s[16:17], 0
	global_store_short v[126:127], v123, off

;     __device__ __forceinline__ void storeT(bf16_t* vt  , int d0, int s, f32x4 v0, f32x4 v1) const {
;         const int pos = (s & ~15) + vperm16(s & 15);
; #pragma unroll
;         for (int e = 0; e < 4; ++e) { vt[(size_t)(d0 + e) * SEQ + pos] = (bf16_t)(pk_bf16(v0[e], 0.f) & 0xffffu); vt[(size_t)(d0 + 4 + e) * SEQ + pos] = (bf16_t)(pk_bf16(v1[e], 0.f) & 0xffffu); }
;     }
;     __device__ __forceinline__ void operator()(const f32x4 (&acc)[2][2][4][2], const Unit& u, int wr, int wc, int fr, int fq) const {
;     ...
;                     f32x4 v0 = acc[ai][bj][m][0] * rs1, v1 = acc[ai][bj][m][1] * rs1;
;                     if (mode == EP_PLAIN) { store8(O + (size_t)row * ldc + col8, v0, v1); }
;                     else if (mode == EP_RELU2) {
; #pragma unroll
;                         for (int e = 0; e < 4; ++e) { float a = fmaxf(v0[e], 0.f), b = fmaxf(v1[e], 0.f); v0[e] = a * a; v1[e] = b * b; }
;                         store8(O + (size_t)row * ldc + col8, v0, v1);
;                     } else if (mode == EP_Z1) {
;                         const int grp = grp0 + bj * 4;
;                         if (grp >= 20 && grp < 24) {
;                             const int b = row / SEQ, s = row % SEQ, kvh = wc >> 1;
;                             storeT(O2 + (size_t)(b * 2 + kvh) * 64 * SEQ, (wc & 1) * 32 + 8 * fq, s, v0, v1);
;                         } else if (grp == 44) {
;                             rope8(v0, v1, cst[m], fq);
;                             bf16_t* kr = O3 + (size_t)row * NQB + 64 + 8 * fq;
; #pragma unroll
;                             for (int h = 0; h < 8; ++h) store8(kr + h * 96, v0, v1);
;                         } else if (grp < 44) {
;                             if (grp < 16) { v0 = v0 * QA_SCALE; v1 = v1 * QA_SCALE; }
;                             store8(O + (size_t)row * ldc + col8, v0, v1);
;                             if (grp >= 24) {
;                                 float q = (v0[0] * v0[0] + v0[1] * v0[1]) + (v0[2] * v0[2] + v0[3] * v0[3]) + (v1[0] * v1[0] + v1[1] * v1[1]) + (v1[2] * v1[2] + v1[3] * v1[3]);
;                                 q += __shfl_xor(q, 16); q += __shfl_xor(q, 32);
;                                 if (fq == 0) ss_out[(size_t)row * 32 + grp - 24] = q;
;                             }
;                         }
;                     } else if (mode == EP_QB) {
.LBB0_539:
	v_add_f32_e32 v114, v181, v182
	v_fmamk_f32 v114, v114, 0x3b800000, v195
	v_rsq_f32_e32 v116, v114
	v_add_u32_e32 v114, v180, v148
	v_ashrrev_i32_e32 v114, 13, v114
	v_mul_i32_i24_e32 v115, 0x2000, v114
	v_sub_u32_e32 v115, v180, v115
	v_lshlrev_b32_e32 v120, 3, v114
	v_lshrrev_b32_e32 v114, 1, v115
	v_lshlrev_b32_e32 v117, 1, v115
	v_and_b32_e32 v114, 4, v114
	v_and_b32_e32 v117, 8, v117
	v_and_b32_e32 v115, 0xffffffd3, v115
	v_or3_b32 v114, v114, v115, v117
	v_ashrrev_i32_e32 v115, 31, v114
	v_mul_f32_e32 v112, v112, v116
	v_mul_f32_e32 v113, v113, v116
	v_mul_f32_e32 v110, v110, v116
	v_mul_f32_e32 v111, v111, v116
	v_mul_f32_e32 v108, v108, v116
	v_mul_f32_e32 v109, v109, v116
	v_mul_f32_e32 v118, v106, v116
	v_mul_f32_e32 v119, v107, v116
	s_and_b64 vcc, exec, s[0:1]
	s_mov_b64 s[16:17], -1
	s_cbranch_vccnz .LBB0_541
	v_add_u32_e32 v106, s46, v120
	v_ashrrev_i32_e32 v107, 31, v106
	v_lshlrev_b64 v[106:107], 20, v[106:107]
	v_lshl_add_u64 v[106:107], s[34:35], 0, v[106:107]
	v_lshl_add_u64 v[106:107], v[114:115], 1, v[106:107]
	v_mov_b32_e32 v123, v1
	v_lshl_add_u64 v[106:107], v[106:107], 0, v[122:123]
	v_cvt_pk_bf16_f32 v117, v110, s0
	v_add_co_u32_e32 v124, vcc, 0x10000, v106
	global_store_short v[106:107], v117, off
	v_cvt_pk_bf16_f32 v117, v118, s0
	v_addc_co_u32_e32 v125, vcc, 0, v107, vcc
	global_store_short v[124:125], v117, off
	v_add_co_u32_e32 v124, vcc, 0x4000, v106
	v_cvt_pk_bf16_f32 v117, v111, s0
	s_nop 0
	v_addc_co_u32_e32 v125, vcc, 0, v107, vcc
	global_store_short v[124:125], v117, off
	v_add_co_u32_e32 v124, vcc, 0x14000, v106
	v_cvt_pk_bf16_f32 v117, v119, s0
	s_nop 0
	v_addc_co_u32_e32 v125, vcc, 0, v107, vcc
	global_store_short v[124:125], v117, off
	v_add_co_u32_e32 v124, vcc, 0x8000, v106
	v_cvt_pk_bf16_f32 v117, v112, s0
	s_nop 0
	v_addc_co_u32_e32 v125, vcc, 0, v107, vcc
	global_store_short v[124:125], v117, off
	v_add_co_u32_e32 v124, vcc, 0x18000, v106
	v_cvt_pk_bf16_f32 v117, v108, s0
	s_nop 0
	v_addc_co_u32_e32 v125, vcc, 0, v107, vcc
	global_store_short v[124:125], v117, off
	v_add_co_u32_e32 v124, vcc, 0xc000, v106
	v_cvt_pk_bf16_f32 v117, v113, s0
	s_nop 0
	v_addc_co_u32_e32 v125, vcc, 0, v107, vcc
	v_add_co_u32_e32 v106, vcc, 0x1c000, v106
	global_store_short v[124:125], v117, off
	v_cvt_pk_bf16_f32 v117, v109, s0
	v_addc_co_u32_e32 v107, vcc, 0, v107, vcc
	s_mov_b64 s[16:17], 0
	global_store_short v[106:107], v117, off

;     __device__ __forceinline__ void storeT(bf16_t* vt  , int d0, int s, f32x4 v0, f32x4 v1) const {
;         const int pos = (s & ~15) + vperm16(s & 15);
; #pragma unroll
;         for (int e = 0; e < 4; ++e) { vt[(size_t)(d0 + e) * SEQ + pos] = (bf16_t)(pk_bf16(v0[e], 0.f) & 0xffffu); vt[(size_t)(d0 + 4 + e) * SEQ + pos] = (bf16_t)(pk_bf16(v1[e], 0.f) & 0xffffu); }
;     }
;     __device__ __forceinline__ void operator()(const f32x4 (&acc)[2][2][4][2], const Unit& u, int wr, int wc, int fr, int fq) const {
;     ...
;                     f32x4 v0 = acc[ai][bj][m][0] * rs1, v1 = acc[ai][bj][m][1] * rs1;
;                     if (mode == EP_PLAIN) { store8(O + (size_t)row * ldc + col8, v0, v1); }
;                     else if (mode == EP_RELU2) {
; #pragma unroll
;                         for (int e = 0; e < 4; ++e) { float a = fmaxf(v0[e], 0.f), b = fmaxf(v1[e], 0.f); v0[e] = a * a; v1[e] = b * b; }
;                         store8(O + (size_t)row * ldc + col8, v0, v1);
;                     } else if (mode == EP_Z1) {
;                         const int grp = grp0 + bj * 4;
;                         if (grp >= 20 && grp < 24) {
;                             const int b = row / SEQ, s = row % SEQ, kvh = wc >> 1;
;                             storeT(O2 + (size_t)(b * 2 + kvh) * 64 * SEQ, (wc & 1) * 32 + 8 * fq, s, v0, v1);
;                         } else if (grp == 44) {
;                             rope8(v0, v1, cst[m], fq);
;                             bf16_t* kr = O3 + (size_t)row * NQB + 64 + 8 * fq;
; #pragma unroll
;                             for (int h = 0; h < 8; ++h) store8(kr + h * 96, v0, v1);
;                         } else if (grp < 44) {
;                             if (grp < 16) { v0 = v0 * QA_SCALE; v1 = v1 * QA_SCALE; }
;                             store8(O + (size_t)row * ldc + col8, v0, v1);
;                             if (grp >= 24) {
;                                 float q = (v0[0] * v0[0] + v0[1] * v0[1]) + (v0[2] * v0[2] + v0[3] * v0[3]) + (v1[0] * v1[0] + v1[1] * v1[1]) + (v1[2] * v1[2] + v1[3] * v1[3]);
;                                 q += __shfl_xor(q, 16); q += __shfl_xor(q, 32);
;                                 if (fq == 0) ss_out[(size_t)row * 32 + grp - 24] = q;
;                             }
;                         }
;                     } else if (mode == EP_QB) {
.LBB0_543:
	v_mov_b32_e32 v117, v116
	v_mov_b32_e32 v108, v116
	v_mov_b32_e32 v109, v116
	v_mul_f32_e32 v104, v104, v108
	v_mul_f32_e32 v105, v105, v109
	v_mul_f32_e32 v102, v102, v116
	v_mul_f32_e32 v103, v103, v117
	v_mul_f32_e32 v100, v100, v108
	v_mul_f32_e32 v101, v101, v109
	v_mul_f32_e32 v98, v98, v116
	v_mul_f32_e32 v99, v99, v117
	s_and_b64 vcc, exec, s[0:1]
	s_mov_b64 s[16:17], -1
	s_cbranch_vccnz .LBB0_545
	v_add_u32_e32 v108, s41, v120
	v_ashrrev_i32_e32 v109, 31, v108
	v_lshlrev_b64 v[108:109], 20, v[108:109]
	v_lshl_add_u64 v[108:109], s[34:35], 0, v[108:109]
	v_lshl_add_u64 v[108:109], v[114:115], 1, v[108:109]
	v_mov_b32_e32 v123, v1
	v_cvt_pk_bf16_f32 v110, v102, s0
	v_lshl_add_u64 v[108:109], v[108:109], 0, v[122:123]
	global_store_short v[108:109], v110, off
	v_add_co_u32_e32 v110, vcc, 0x10000, v108
	v_cvt_pk_bf16_f32 v112, v98, s0
	s_nop 0
	v_addc_co_u32_e32 v111, vcc, 0, v109, vcc
	global_store_short v[110:111], v112, off
	v_add_co_u32_e32 v110, vcc, 0x4000, v108
	v_cvt_pk_bf16_f32 v112, v103, s0
	s_nop 0
	v_addc_co_u32_e32 v111, vcc, 0, v109, vcc
	global_store_short v[110:111], v112, off
	v_add_co_u32_e32 v110, vcc, 0x14000, v108
	v_cvt_pk_bf16_f32 v112, v99, s0
	s_nop 0
	v_addc_co_u32_e32 v111, vcc, 0, v109, vcc
	global_store_short v[110:111], v112, off
	v_add_co_u32_e32 v110, vcc, 0x8000, v108
	v_cvt_pk_bf16_f32 v112, v104, s0
	s_nop 0
	v_addc_co_u32_e32 v111, vcc, 0, v109, vcc
	global_store_short v[110:111], v112, off
	v_add_co_u32_e32 v110, vcc, 0x18000, v108
	v_cvt_pk_bf16_f32 v112, v100, s0
	s_nop 0
	v_addc_co_u32_e32 v111, vcc, 0, v109, vcc
	global_store_short v[110:111], v112, off
	v_add_co_u32_e32 v110, vcc, 0xc000, v108
	v_cvt_pk_bf16_f32 v112, v105, s0
	s_nop 0
	v_addc_co_u32_e32 v111, vcc, 0, v109, vcc
	v_add_co_u32_e32 v108, vcc, 0x1c000, v108
	global_store_short v[110:111], v112, off
	v_cvt_pk_bf16_f32 v110, v101, s0
	v_addc_co_u32_e32 v109, vcc, 0, v109, vcc
	s_mov_b64 s[16:17], 0
	global_store_short v[108:109], v110, off

;     __device__ __forceinline__ void storeT(bf16_t* vt  , int d0, int s, f32x4 v0, f32x4 v1) const {
;         const int pos = (s & ~15) + vperm16(s & 15);
; #pragma unroll
;         for (int e = 0; e < 4; ++e) { vt[(size_t)(d0 + e) * SEQ + pos] = (bf16_t)(pk_bf16(v0[e], 0.f) & 0xffffu); vt[(size_t)(d0 + 4 + e) * SEQ + pos] = (bf16_t)(pk_bf16(v1[e], 0.f) & 0xffffu); }
;     }
;     __device__ __forceinline__ void operator()(const f32x4 (&acc)[2][2][4][2], const Unit& u, int wr, int wc, int fr, int fq) const {
;     ...
;                     f32x4 v0 = acc[ai][bj][m][0] * rs1, v1 = acc[ai][bj][m][1] * rs1;
;                     if (mode == EP_PLAIN) { store8(O + (size_t)row * ldc + col8, v0, v1); }
;                     else if (mode == EP_RELU2) {
; #pragma unroll
;                         for (int e = 0; e < 4; ++e) { float a = fmaxf(v0[e], 0.f), b = fmaxf(v1[e], 0.f); v0[e] = a * a; v1[e] = b * b; }
;                         store8(O + (size_t)row * ldc + col8, v0, v1);
;                     } else if (mode == EP_Z1) {
;                         const int grp = grp0 + bj * 4;
;                         if (grp >= 20 && grp < 24) {
;                             const int b = row / SEQ, s = row % SEQ, kvh = wc >> 1;
;                             storeT(O2 + (size_t)(b * 2 + kvh) * 64 * SEQ, (wc & 1) * 32 + 8 * fq, s, v0, v1);
;                         } else if (grp == 44) {
;                             rope8(v0, v1, cst[m], fq);
;                             bf16_t* kr = O3 + (size_t)row * NQB + 64 + 8 * fq;
; #pragma unroll
;                             for (int h = 0; h < 8; ++h) store8(kr + h * 96, v0, v1);
;                         } else if (grp < 44) {
;                             if (grp < 16) { v0 = v0 * QA_SCALE; v1 = v1 * QA_SCALE; }
;                             store8(O + (size_t)row * ldc + col8, v0, v1);
;                             if (grp >= 24) {
;                                 float q = (v0[0] * v0[0] + v0[1] * v0[1]) + (v0[2] * v0[2] + v0[3] * v0[3]) + (v1[0] * v1[0] + v1[1] * v1[1]) + (v1[2] * v1[2] + v1[3] * v1[3]);
;                                 q += __shfl_xor(q, 16); q += __shfl_xor(q, 32);
;                                 if (fq == 0) ss_out[(size_t)row * 32 + grp - 24] = q;
;                             }
;                         }
;                     } else if (mode == EP_QB) {
.LBB0_547:
	v_add_f32_e32 v98, v177, v179
	v_fmamk_f32 v98, v98, 0x3b800000, v195
	v_rsq_f32_e32 v100, v98
	v_add_u32_e32 v98, v178, v148
	v_ashrrev_i32_e32 v98, 13, v98
	v_mul_i32_i24_e32 v99, 0x2000, v98
	v_sub_u32_e32 v99, v178, v99
	v_lshlrev_b32_e32 v104, 3, v98
	v_lshrrev_b32_e32 v98, 1, v99
	v_lshlrev_b32_e32 v101, 1, v99
	v_and_b32_e32 v98, 4, v98
	v_and_b32_e32 v101, 8, v101
	v_and_b32_e32 v99, 0xffffffe3, v99
	v_or3_b32 v98, v98, v99, v101
	v_ashrrev_i32_e32 v99, 31, v98
	v_mul_f32_e32 v96, v96, v100
	v_mul_f32_e32 v97, v97, v100
	v_mul_f32_e32 v94, v94, v100
	v_mul_f32_e32 v95, v95, v100
	v_mul_f32_e32 v92, v92, v100
	v_mul_f32_e32 v93, v93, v100
	v_mul_f32_e32 v102, v90, v100
	v_mul_f32_e32 v103, v91, v100
	s_and_b64 vcc, exec, s[0:1]
	s_mov_b64 s[16:17], -1
	s_cbranch_vccnz .LBB0_549
	v_add_u32_e32 v90, s46, v104
	v_ashrrev_i32_e32 v91, 31, v90
	v_lshlrev_b64 v[90:91], 20, v[90:91]
	v_lshl_add_u64 v[90:91], s[34:35], 0, v[90:91]
	v_lshl_add_u64 v[90:91], v[98:99], 1, v[90:91]
	v_mov_b32_e32 v123, v1
	v_lshl_add_u64 v[90:91], v[90:91], 0, v[122:123]
	v_cvt_pk_bf16_f32 v101, v94, s0
	v_add_co_u32_e32 v106, vcc, 0x10000, v90
	global_store_short v[90:91], v101, off
	v_cvt_pk_bf16_f32 v101, v102, s0
	v_addc_co_u32_e32 v107, vcc, 0, v91, vcc
	global_store_short v[106:107], v101, off
	v_add_co_u32_e32 v106, vcc, 0x4000, v90
	v_cvt_pk_bf16_f32 v101, v95, s0
	s_nop 0
	v_addc_co_u32_e32 v107, vcc, 0, v91, vcc
	global_store_short v[106:107], v101, off
	v_add_co_u32_e32 v106, vcc, 0x14000, v90
	v_cvt_pk_bf16_f32 v101, v103, s0
	s_nop 0
	v_addc_co_u32_e32 v107, vcc, 0, v91, vcc
	global_store_short v[106:107], v101, off
	v_add_co_u32_e32 v106, vcc, 0x8000, v90
	v_cvt_pk_bf16_f32 v101, v96, s0
	s_nop 0
	v_addc_co_u32_e32 v107, vcc, 0, v91, vcc
	global_store_short v[106:107], v101, off
	v_add_co_u32_e32 v106, vcc, 0x18000, v90
	v_cvt_pk_bf16_f32 v101, v92, s0
	s_nop 0
	v_addc_co_u32_e32 v107, vcc, 0, v91, vcc
	global_store_short v[106:107], v101, off
	v_add_co_u32_e32 v106, vcc, 0xc000, v90
	v_cvt_pk_bf16_f32 v101, v97, s0
	s_nop 0
	v_addc_co_u32_e32 v107, vcc, 0, v91, vcc
	v_add_co_u32_e32 v90, vcc, 0x1c000, v90
	global_store_short v[106:107], v101, off
	v_cvt_pk_bf16_f32 v101, v93, s0
	v_addc_co_u32_e32 v91, vcc, 0, v91, vcc
	s_mov_b64 s[16:17], 0
	global_store_short v[90:91], v101, off

;     __device__ __forceinline__ void storeT(bf16_t* vt  , int d0, int s, f32x4 v0, f32x4 v1) const {
;         const int pos = (s & ~15) + vperm16(s & 15);
; #pragma unroll
;         for (int e = 0; e < 4; ++e) { vt[(size_t)(d0 + e) * SEQ + pos] = (bf16_t)(pk_bf16(v0[e], 0.f) & 0xffffu); vt[(size_t)(d0 + 4 + e) * SEQ + pos] = (bf16_t)(pk_bf16(v1[e], 0.f) & 0xffffu); }
;     }
;     __device__ __forceinline__ void operator()(const f32x4 (&acc)[2][2][4][2], const Unit& u, int wr, int wc, int fr, int fq) const {
;     ...
;                     f32x4 v0 = acc[ai][bj][m][0] * rs1, v1 = acc[ai][bj][m][1] * rs1;
;                     if (mode == EP_PLAIN) { store8(O + (size_t)row * ldc + col8, v0, v1); }
;                     else if (mode == EP_RELU2) {
; #pragma unroll
;                         for (int e = 0; e < 4; ++e) { float a = fmaxf(v0[e], 0.f), b = fmaxf(v1[e], 0.f); v0[e] = a * a; v1[e] = b * b; }
;                         store8(O + (size_t)row * ldc + col8, v0, v1);
;                     } else if (mode == EP_Z1) {
;                         const int grp = grp0 + bj * 4;
;                         if (grp >= 20 && grp < 24) {
;                             const int b = row / SEQ, s = row % SEQ, kvh = wc >> 1;
;                             storeT(O2 + (size_t)(b * 2 + kvh) * 64 * SEQ, (wc & 1) * 32 + 8 * fq, s, v0, v1);
;                         } else if (grp == 44) {
;                             rope8(v0, v1, cst[m], fq);
;                             bf16_t* kr = O3 + (size_t)row * NQB + 64 + 8 * fq;
; #pragma unroll
;                             for (int h = 0; h < 8; ++h) store8(kr + h * 96, v0, v1);
;                         } else if (grp < 44) {
;                             if (grp < 16) { v0 = v0 * QA_SCALE; v1 = v1 * QA_SCALE; }
;                             store8(O + (size_t)row * ldc + col8, v0, v1);
;                             if (grp >= 24) {
;                                 float q = (v0[0] * v0[0] + v0[1] * v0[1]) + (v0[2] * v0[2] + v0[3] * v0[3]) + (v1[0] * v1[0] + v1[1] * v1[1]) + (v1[2] * v1[2] + v1[3] * v1[3]);
;                                 q += __shfl_xor(q, 16); q += __shfl_xor(q, 32);
;                                 if (fq == 0) ss_out[(size_t)row * 32 + grp - 24] = q;
;                             }
;                         }
;                     } else if (mode == EP_QB) {
.LBB0_551:
	v_mov_b32_e32 v101, v100
	v_mov_b32_e32 v92, v100
	v_mov_b32_e32 v93, v100
	v_mul_f32_e32 v88, v88, v92
	v_mul_f32_e32 v89, v89, v93
	v_mul_f32_e32 v86, v86, v100
	v_mul_f32_e32 v87, v87, v101
	v_mul_f32_e32 v84, v84, v92
	v_mul_f32_e32 v85, v85, v93
	v_mul_f32_e32 v82, v82, v100
	v_mul_f32_e32 v83, v83, v101
	s_and_b64 vcc, exec, s[0:1]
	s_mov_b64 s[16:17], -1
	s_cbranch_vccnz .LBB0_553
	v_add_u32_e32 v92, s41, v104
	v_ashrrev_i32_e32 v93, 31, v92
	v_lshlrev_b64 v[92:93], 20, v[92:93]
	v_lshl_add_u64 v[92:93], s[34:35], 0, v[92:93]
	v_lshl_add_u64 v[92:93], v[98:99], 1, v[92:93]
	v_mov_b32_e32 v123, v1
	v_cvt_pk_bf16_f32 v94, v86, s0
	v_lshl_add_u64 v[92:93], v[92:93], 0, v[122:123]
	global_store_short v[92:93], v94, off
	v_add_co_u32_e32 v94, vcc, 0x10000, v92
	v_cvt_pk_bf16_f32 v96, v82, s0
	s_nop 0
	v_addc_co_u32_e32 v95, vcc, 0, v93, vcc
	global_store_short v[94:95], v96, off
	v_add_co_u32_e32 v94, vcc, 0x4000, v92
	v_cvt_pk_bf16_f32 v96, v87, s0
	s_nop 0
	v_addc_co_u32_e32 v95, vcc, 0, v93, vcc
	global_store_short v[94:95], v96, off
	v_add_co_u32_e32 v94, vcc, 0x14000, v92
	v_cvt_pk_bf16_f32 v96, v83, s0
	s_nop 0
	v_addc_co_u32_e32 v95, vcc, 0, v93, vcc
	global_store_short v[94:95], v96, off
	v_add_co_u32_e32 v94, vcc, 0x8000, v92
	v_cvt_pk_bf16_f32 v96, v88, s0
	s_nop 0
	v_addc_co_u32_e32 v95, vcc, 0, v93, vcc
	global_store_short v[94:95], v96, off
	v_add_co_u32_e32 v94, vcc, 0x18000, v92
	v_cvt_pk_bf16_f32 v96, v84, s0
	s_nop 0
	v_addc_co_u32_e32 v95, vcc, 0, v93, vcc
	global_store_short v[94:95], v96, off
	v_add_co_u32_e32 v94, vcc, 0xc000, v92
	v_cvt_pk_bf16_f32 v96, v89, s0
	s_nop 0
	v_addc_co_u32_e32 v95, vcc, 0, v93, vcc
	v_add_co_u32_e32 v92, vcc, 0x1c000, v92
	global_store_short v[94:95], v96, off
	v_cvt_pk_bf16_f32 v94, v85, s0
	v_addc_co_u32_e32 v93, vcc, 0, v93, vcc
	s_mov_b64 s[16:17], 0
	global_store_short v[92:93], v94, off

;     __device__ __forceinline__ void storeT(bf16_t* vt  , int d0, int s, f32x4 v0, f32x4 v1) const {
;         const int pos = (s & ~15) + vperm16(s & 15);
; #pragma unroll
;         for (int e = 0; e < 4; ++e) { vt[(size_t)(d0 + e) * SEQ + pos] = (bf16_t)(pk_bf16(v0[e], 0.f) & 0xffffu); vt[(size_t)(d0 + 4 + e) * SEQ + pos] = (bf16_t)(pk_bf16(v1[e], 0.f) & 0xffffu); }
;     }
;     __device__ __forceinline__ void operator()(const f32x4 (&acc)[2][2][4][2], const Unit& u, int wr, int wc, int fr, int fq) const {
;     ...
;                     f32x4 v0 = acc[ai][bj][m][0] * rs1, v1 = acc[ai][bj][m][1] * rs1;
;                     if (mode == EP_PLAIN) { store8(O + (size_t)row * ldc + col8, v0, v1); }
;                     else if (mode == EP_RELU2) {
; #pragma unroll
;                         for (int e = 0; e < 4; ++e) { float a = fmaxf(v0[e], 0.f), b = fmaxf(v1[e], 0.f); v0[e] = a * a; v1[e] = b * b; }
;                         store8(O + (size_t)row * ldc + col8, v0, v1);
;                     } else if (mode == EP_Z1) {
;                         const int grp = grp0 + bj * 4;
;                         if (grp >= 20 && grp < 24) {
;                             const int b = row / SEQ, s = row % SEQ, kvh = wc >> 1;
;                             storeT(O2 + (size_t)(b * 2 + kvh) * 64 * SEQ, (wc & 1) * 32 + 8 * fq, s, v0, v1);
;                         } else if (grp == 44) {
;                             rope8(v0, v1, cst[m], fq);
;                             bf16_t* kr = O3 + (size_t)row * NQB + 64 + 8 * fq;
; #pragma unroll
;                             for (int h = 0; h < 8; ++h) store8(kr + h * 96, v0, v1);
;                         } else if (grp < 44) {
;                             if (grp < 16) { v0 = v0 * QA_SCALE; v1 = v1 * QA_SCALE; }
;                             store8(O + (size_t)row * ldc + col8, v0, v1);
;                             if (grp >= 24) {
;                                 float q = (v0[0] * v0[0] + v0[1] * v0[1]) + (v0[2] * v0[2] + v0[3] * v0[3]) + (v1[0] * v1[0] + v1[1] * v1[1]) + (v1[2] * v1[2] + v1[3] * v1[3]);
;                                 q += __shfl_xor(q, 16); q += __shfl_xor(q, 32);
;                                 if (fq == 0) ss_out[(size_t)row * 32 + grp - 24] = q;
;                             }
;                         }
;                     } else if (mode == EP_QB) {
.LBB0_555:
	v_add_f32_e32 v82, v146, v147
	v_fmamk_f32 v82, v82, 0x3b800000, v195
	v_rsq_f32_e32 v84, v82
	v_add_u32_e32 v82, v176, v148
	v_ashrrev_i32_e32 v82, 13, v82
	v_mul_i32_i24_e32 v83, 0x2000, v82
	v_sub_u32_e32 v83, v176, v83
	v_lshlrev_b32_e32 v88, 3, v82
	v_lshrrev_b32_e32 v82, 1, v83
	v_lshlrev_b32_e32 v85, 1, v83
	v_and_b32_e32 v82, 4, v82
	v_and_b32_e32 v85, 8, v85
	v_and_b32_e32 v83, -13, v83
	v_or3_b32 v82, v82, v83, v85
	v_ashrrev_i32_e32 v83, 31, v82
	v_mul_f32_e32 v80, v80, v84
	v_mul_f32_e32 v81, v81, v84
	v_mul_f32_e32 v78, v78, v84
	v_mul_f32_e32 v79, v79, v84
	v_mul_f32_e32 v76, v76, v84
	v_mul_f32_e32 v77, v77, v84
	v_mul_f32_e32 v86, v74, v84
	v_mul_f32_e32 v87, v75, v84
	s_and_b64 vcc, exec, s[0:1]
	s_mov_b64 s[16:17], -1
	s_cbranch_vccnz .LBB0_557
	v_add_u32_e32 v74, s46, v88
	v_ashrrev_i32_e32 v75, 31, v74
	v_lshlrev_b64 v[74:75], 20, v[74:75]
	v_lshl_add_u64 v[74:75], s[34:35], 0, v[74:75]
	v_lshl_add_u64 v[74:75], v[82:83], 1, v[74:75]
	v_mov_b32_e32 v123, v1
	v_lshl_add_u64 v[74:75], v[74:75], 0, v[122:123]
	v_cvt_pk_bf16_f32 v85, v78, s0
	v_add_co_u32_e32 v90, vcc, 0x10000, v74
	global_store_short v[74:75], v85, off
	v_cvt_pk_bf16_f32 v85, v86, s0
	v_addc_co_u32_e32 v91, vcc, 0, v75, vcc
	global_store_short v[90:91], v85, off
	v_add_co_u32_e32 v90, vcc, 0x4000, v74
	v_cvt_pk_bf16_f32 v85, v79, s0
	s_nop 0
	v_addc_co_u32_e32 v91, vcc, 0, v75, vcc
	global_store_short v[90:91], v85, off
	v_add_co_u32_e32 v90, vcc, 0x14000, v74
	v_cvt_pk_bf16_f32 v85, v87, s0
	s_nop 0
	v_addc_co_u32_e32 v91, vcc, 0, v75, vcc
	global_store_short v[90:91], v85, off
	v_add_co_u32_e32 v90, vcc, 0x8000, v74
	v_cvt_pk_bf16_f32 v85, v80, s0
	s_nop 0
	v_addc_co_u32_e32 v91, vcc, 0, v75, vcc
	global_store_short v[90:91], v85, off
	v_add_co_u32_e32 v90, vcc, 0x18000, v74
	v_cvt_pk_bf16_f32 v85, v76, s0
	s_nop 0
	v_addc_co_u32_e32 v91, vcc, 0, v75, vcc
	global_store_short v[90:91], v85, off
	v_add_co_u32_e32 v90, vcc, 0xc000, v74
	v_cvt_pk_bf16_f32 v85, v81, s0
	s_nop 0
	v_addc_co_u32_e32 v91, vcc, 0, v75, vcc
	v_add_co_u32_e32 v74, vcc, 0x1c000, v74
	global_store_short v[90:91], v85, off
	v_cvt_pk_bf16_f32 v85, v77, s0
	v_addc_co_u32_e32 v75, vcc, 0, v75, vcc
	s_mov_b64 s[16:17], 0
	global_store_short v[74:75], v85, off

;     __device__ __forceinline__ void storeT(bf16_t* vt  , int d0, int s, f32x4 v0, f32x4 v1) const {
;         const int pos = (s & ~15) + vperm16(s & 15);
; #pragma unroll
;         for (int e = 0; e < 4; ++e) { vt[(size_t)(d0 + e) * SEQ + pos] = (bf16_t)(pk_bf16(v0[e], 0.f) & 0xffffu); vt[(size_t)(d0 + 4 + e) * SEQ + pos] = (bf16_t)(pk_bf16(v1[e], 0.f) & 0xffffu); }
;     }
;     __device__ __forceinline__ void operator()(const f32x4 (&acc)[2][2][4][2], const Unit& u, int wr, int wc, int fr, int fq) const {
;     ...
;                     f32x4 v0 = acc[ai][bj][m][0] * rs1, v1 = acc[ai][bj][m][1] * rs1;
;                     if (mode == EP_PLAIN) { store8(O + (size_t)row * ldc + col8, v0, v1); }
;                     else if (mode == EP_RELU2) {
; #pragma unroll
;                         for (int e = 0; e < 4; ++e) { float a = fmaxf(v0[e], 0.f), b = fmaxf(v1[e], 0.f); v0[e] = a * a; v1[e] = b * b; }
;                         store8(O + (size_t)row * ldc + col8, v0, v1);
;                     } else if (mode == EP_Z1) {
;                         const int grp = grp0 + bj * 4;
;                         if (grp >= 20 && grp < 24) {
;                             const int b = row / SEQ, s = row % SEQ, kvh = wc >> 1;
;                             storeT(O2 + (size_t)(b * 2 + kvh) * 64 * SEQ, (wc & 1) * 32 + 8 * fq, s, v0, v1);
;                         } else if (grp == 44) {
;                             rope8(v0, v1, cst[m], fq);
;                             bf16_t* kr = O3 + (size_t)row * NQB + 64 + 8 * fq;
; #pragma unroll
;                             for (int h = 0; h < 8; ++h) store8(kr + h * 96, v0, v1);
;                         } else if (grp < 44) {
;                             if (grp < 16) { v0 = v0 * QA_SCALE; v1 = v1 * QA_SCALE; }
;                             store8(O + (size_t)row * ldc + col8, v0, v1);
;                             if (grp >= 24) {
;                                 float q = (v0[0] * v0[0] + v0[1] * v0[1]) + (v0[2] * v0[2] + v0[3] * v0[3]) + (v1[0] * v1[0] + v1[1] * v1[1]) + (v1[2] * v1[2] + v1[3] * v1[3]);
;                                 q += __shfl_xor(q, 16); q += __shfl_xor(q, 32);
;                                 if (fq == 0) ss_out[(size_t)row * 32 + grp - 24] = q;
;                             }
;                         }
;                     } else if (mode == EP_QB) {
.LBB0_559:
	v_mov_b32_e32 v85, v84
	v_mov_b32_e32 v76, v84
	v_mov_b32_e32 v77, v84
	v_mul_f32_e32 v72, v72, v76
	v_mul_f32_e32 v73, v73, v77
	v_mul_f32_e32 v70, v70, v84
	v_mul_f32_e32 v71, v71, v85
	v_mul_f32_e32 v68, v68, v76
	v_mul_f32_e32 v69, v69, v77
	v_mul_f32_e32 v66, v66, v84
	v_mul_f32_e32 v67, v67, v85
	s_and_b64 vcc, exec, s[0:1]
	s_mov_b64 s[16:17], -1
	s_cbranch_vccnz .LBB0_561
	v_add_u32_e32 v76, s41, v88
	v_ashrrev_i32_e32 v77, 31, v76
	v_lshlrev_b64 v[76:77], 20, v[76:77]
	v_lshl_add_u64 v[76:77], s[34:35], 0, v[76:77]
	v_lshl_add_u64 v[76:77], v[82:83], 1, v[76:77]
	v_mov_b32_e32 v123, v1
	v_cvt_pk_bf16_f32 v78, v70, s0
	v_lshl_add_u64 v[76:77], v[76:77], 0, v[122:123]
	global_store_short v[76:77], v78, off
	v_add_co_u32_e32 v78, vcc, 0x10000, v76
	v_cvt_pk_bf16_f32 v80, v66, s0
	s_nop 0
	v_addc_co_u32_e32 v79, vcc, 0, v77, vcc
	global_store_short v[78:79], v80, off
	v_add_co_u32_e32 v78, vcc, 0x4000, v76
	v_cvt_pk_bf16_f32 v80, v71, s0
	s_nop 0
	v_addc_co_u32_e32 v79, vcc, 0, v77, vcc
	global_store_short v[78:79], v80, off
	v_add_co_u32_e32 v78, vcc, 0x14000, v76
	v_cvt_pk_bf16_f32 v80, v67, s0
	s_nop 0
	v_addc_co_u32_e32 v79, vcc, 0, v77, vcc
	global_store_short v[78:79], v80, off
	v_add_co_u32_e32 v78, vcc, 0x8000, v76
	v_cvt_pk_bf16_f32 v80, v72, s0
	s_nop 0
	v_addc_co_u32_e32 v79, vcc, 0, v77, vcc
	global_store_short v[78:79], v80, off
	v_add_co_u32_e32 v78, vcc, 0x18000, v76
	v_cvt_pk_bf16_f32 v80, v68, s0
	s_nop 0
	v_addc_co_u32_e32 v79, vcc, 0, v77, vcc
	global_store_short v[78:79], v80, off
	v_add_co_u32_e32 v78, vcc, 0xc000, v76
	v_cvt_pk_bf16_f32 v80, v73, s0
	s_nop 0
	v_addc_co_u32_e32 v79, vcc, 0, v77, vcc
	v_add_co_u32_e32 v76, vcc, 0x1c000, v76
	global_store_short v[78:79], v80, off
	v_cvt_pk_bf16_f32 v78, v69, s0
	v_addc_co_u32_e32 v77, vcc, 0, v77, vcc
	s_mov_b64 s[16:17], 0
	global_store_short v[76:77], v78, off

;     __device__ __forceinline__ void storeT(bf16_t* vt  , int d0, int s, f32x4 v0, f32x4 v1) const {
;         const int pos = (s & ~15) + vperm16(s & 15);
; #pragma unroll
;         for (int e = 0; e < 4; ++e) { vt[(size_t)(d0 + e) * SEQ + pos] = (bf16_t)(pk_bf16(v0[e], 0.f) & 0xffffu); vt[(size_t)(d0 + 4 + e) * SEQ + pos] = (bf16_t)(pk_bf16(v1[e], 0.f) & 0xffffu); }
;     }
;     __device__ __forceinline__ void operator()(const f32x4 (&acc)[2][2][4][2], const Unit& u, int wr, int wc, int fr, int fq) const {
;     ...
;                     f32x4 v0 = acc[ai][bj][m][0] * rs1, v1 = acc[ai][bj][m][1] * rs1;
;                     if (mode == EP_PLAIN) { store8(O + (size_t)row * ldc + col8, v0, v1); }
;                     else if (mode == EP_RELU2) {
; #pragma unroll
;                         for (int e = 0; e < 4; ++e) { float a = fmaxf(v0[e], 0.f), b = fmaxf(v1[e], 0.f); v0[e] = a * a; v1[e] = b * b; }
;                         store8(O + (size_t)row * ldc + col8, v0, v1);
;                     } else if (mode == EP_Z1) {
;                         const int grp = grp0 + bj * 4;
;                         if (grp >= 20 && grp < 24) {
;                             const int b = row / SEQ, s = row % SEQ, kvh = wc >> 1;
;                             storeT(O2 + (size_t)(b * 2 + kvh) * 64 * SEQ, (wc & 1) * 32 + 8 * fq, s, v0, v1);
;                         } else if (grp == 44) {
;                             rope8(v0, v1, cst[m], fq);
;                             bf16_t* kr = O3 + (size_t)row * NQB + 64 + 8 * fq;
; #pragma unroll
;                             for (int h = 0; h < 8; ++h) store8(kr + h * 96, v0, v1);
;                         } else if (grp < 44) {
;                             if (grp < 16) { v0 = v0 * QA_SCALE; v1 = v1 * QA_SCALE; }
;                             store8(O + (size_t)row * ldc + col8, v0, v1);
;                             if (grp >= 24) {
;                                 float q = (v0[0] * v0[0] + v0[1] * v0[1]) + (v0[2] * v0[2] + v0[3] * v0[3]) + (v1[0] * v1[0] + v1[1] * v1[1]) + (v1[2] * v1[2] + v1[3] * v1[3]);
;                                 q += __shfl_xor(q, 16); q += __shfl_xor(q, 32);
;                                 if (fq == 0) ss_out[(size_t)row * 32 + grp - 24] = q;
;                             }
;                         }
;                     } else if (mode == EP_QB) {
.LBB0_563:
	v_add_f32_e32 v66, v144, v145
	v_fmamk_f32 v66, v66, 0x3b800000, v195
	v_add_u32_e32 v69, 0x80, v174
	v_rsq_f32_e32 v68, v66
	v_ashrrev_i32_e32 v66, 31, v69
	v_lshrrev_b32_e32 v66, 19, v66
	v_add_u32_e32 v66, v69, v66
	v_ashrrev_i32_e32 v66, 13, v66
	v_mul_i32_i24_e32 v67, 0x2000, v66
	v_sub_u32_e32 v67, v69, v67
	v_lshlrev_b32_e32 v72, 3, v66
	v_lshrrev_b32_e32 v66, 1, v67
	v_lshlrev_b32_e32 v70, 1, v67
	v_and_b32_e32 v66, 4, v66
	v_and_b32_e32 v70, 8, v70
	v_and_b32_e32 v67, 0xffffffc3, v67
	v_or3_b32 v66, v66, v67, v70
	v_ashrrev_i32_e32 v67, 31, v66
	v_mul_f32_e32 v64, v64, v68
	v_mul_f32_e32 v65, v65, v68
	v_mul_f32_e32 v62, v62, v68
	v_mul_f32_e32 v63, v63, v68
	v_mul_f32_e32 v60, v60, v68
	v_mul_f32_e32 v61, v61, v68
	v_mul_f32_e32 v70, v58, v68
	v_mul_f32_e32 v71, v59, v68
	s_and_b64 vcc, exec, s[0:1]
	s_mov_b64 s[16:17], -1
	s_cbranch_vccnz .LBB0_565
	v_add_u32_e32 v58, s46, v72
	v_ashrrev_i32_e32 v59, 31, v58
	v_lshlrev_b64 v[58:59], 20, v[58:59]
	v_lshl_add_u64 v[58:59], s[34:35], 0, v[58:59]
	v_lshl_add_u64 v[58:59], v[66:67], 1, v[58:59]
	v_mov_b32_e32 v123, v1
	v_lshl_add_u64 v[58:59], v[58:59], 0, v[122:123]
	v_cvt_pk_bf16_f32 v73, v62, s0
	v_add_co_u32_e32 v74, vcc, 0x10000, v58
	global_store_short v[58:59], v73, off
	v_cvt_pk_bf16_f32 v73, v70, s0
	v_addc_co_u32_e32 v75, vcc, 0, v59, vcc
	global_store_short v[74:75], v73, off
	v_add_co_u32_e32 v74, vcc, 0x4000, v58
	v_cvt_pk_bf16_f32 v73, v63, s0
	s_nop 0
	v_addc_co_u32_e32 v75, vcc, 0, v59, vcc
	global_store_short v[74:75], v73, off
	v_add_co_u32_e32 v74, vcc, 0x14000, v58
	v_cvt_pk_bf16_f32 v73, v71, s0
	s_nop 0
	v_addc_co_u32_e32 v75, vcc, 0, v59, vcc
	global_store_short v[74:75], v73, off
	v_add_co_u32_e32 v74, vcc, 0x8000, v58
	v_cvt_pk_bf16_f32 v73, v64, s0
	s_nop 0
	v_addc_co_u32_e32 v75, vcc, 0, v59, vcc
	global_store_short v[74:75], v73, off
	v_add_co_u32_e32 v74, vcc, 0x18000, v58
	v_cvt_pk_bf16_f32 v73, v60, s0
	s_nop 0
	v_addc_co_u32_e32 v75, vcc, 0, v59, vcc
	global_store_short v[74:75], v73, off
	v_add_co_u32_e32 v74, vcc, 0xc000, v58
	v_cvt_pk_bf16_f32 v73, v65, s0
	s_nop 0
	v_addc_co_u32_e32 v75, vcc, 0, v59, vcc
	v_add_co_u32_e32 v58, vcc, 0x1c000, v58
	global_store_short v[74:75], v73, off
	v_cvt_pk_bf16_f32 v73, v61, s0
	v_addc_co_u32_e32 v59, vcc, 0, v59, vcc
	s_mov_b64 s[16:17], 0
	global_store_short v[58:59], v73, off

;     __device__ __forceinline__ void storeT(bf16_t* vt  , int d0, int s, f32x4 v0, f32x4 v1) const {
;         const int pos = (s & ~15) + vperm16(s & 15);
; #pragma unroll
;         for (int e = 0; e < 4; ++e) { vt[(size_t)(d0 + e) * SEQ + pos] = (bf16_t)(pk_bf16(v0[e], 0.f) & 0xffffu); vt[(size_t)(d0 + 4 + e) * SEQ + pos] = (bf16_t)(pk_bf16(v1[e], 0.f) & 0xffffu); }
;     }
;     __device__ __forceinline__ void operator()(const f32x4 (&acc)[2][2][4][2], const Unit& u, int wr, int wc, int fr, int fq) const {
;     ...
;                     f32x4 v0 = acc[ai][bj][m][0] * rs1, v1 = acc[ai][bj][m][1] * rs1;
;                     if (mode == EP_PLAIN) { store8(O + (size_t)row * ldc + col8, v0, v1); }
;                     else if (mode == EP_RELU2) {
; #pragma unroll
;                         for (int e = 0; e < 4; ++e) { float a = fmaxf(v0[e], 0.f), b = fmaxf(v1[e], 0.f); v0[e] = a * a; v1[e] = b * b; }
;                         store8(O + (size_t)row * ldc + col8, v0, v1);
;                     } else if (mode == EP_Z1) {
;                         const int grp = grp0 + bj * 4;
;                         if (grp >= 20 && grp < 24) {
;                             const int b = row / SEQ, s = row % SEQ, kvh = wc >> 1;
;                             storeT(O2 + (size_t)(b * 2 + kvh) * 64 * SEQ, (wc & 1) * 32 + 8 * fq, s, v0, v1);
;                         } else if (grp == 44) {
;                             rope8(v0, v1, cst[m], fq);
;                             bf16_t* kr = O3 + (size_t)row * NQB + 64 + 8 * fq;
; #pragma unroll
;                             for (int h = 0; h < 8; ++h) store8(kr + h * 96, v0, v1);
;                         } else if (grp < 44) {
;                             if (grp < 16) { v0 = v0 * QA_SCALE; v1 = v1 * QA_SCALE; }
;                             store8(O + (size_t)row * ldc + col8, v0, v1);
;                             if (grp >= 24) {
;                                 float q = (v0[0] * v0[0] + v0[1] * v0[1]) + (v0[2] * v0[2] + v0[3] * v0[3]) + (v1[0] * v1[0] + v1[1] * v1[1]) + (v1[2] * v1[2] + v1[3] * v1[3]);
;                                 q += __shfl_xor(q, 16); q += __shfl_xor(q, 32);
;                                 if (fq == 0) ss_out[(size_t)row * 32 + grp - 24] = q;
;                             }
;                         }
;                     } else if (mode == EP_QB) {
.LBB0_567:
	v_mov_b32_e32 v69, v68
	v_mov_b32_e32 v60, v68
	v_mov_b32_e32 v61, v68
	v_mul_f32_e32 v56, v56, v60
	v_mul_f32_e32 v57, v57, v61
	v_mul_f32_e32 v54, v54, v68
	v_mul_f32_e32 v55, v55, v69
	v_mul_f32_e32 v52, v52, v60
	v_mul_f32_e32 v53, v53, v61
	v_mul_f32_e32 v50, v50, v68
	v_mul_f32_e32 v51, v51, v69
	s_and_b64 vcc, exec, s[0:1]
	s_mov_b64 s[16:17], -1
	s_cbranch_vccnz .LBB0_569
	v_add_u32_e32 v60, s41, v72
	v_ashrrev_i32_e32 v61, 31, v60
	v_lshlrev_b64 v[60:61], 20, v[60:61]
	v_lshl_add_u64 v[60:61], s[34:35], 0, v[60:61]
	v_lshl_add_u64 v[60:61], v[66:67], 1, v[60:61]
	v_mov_b32_e32 v123, v1
	v_cvt_pk_bf16_f32 v62, v54, s0
	v_lshl_add_u64 v[60:61], v[60:61], 0, v[122:123]
	global_store_short v[60:61], v62, off
	v_add_co_u32_e32 v62, vcc, 0x10000, v60
	v_cvt_pk_bf16_f32 v64, v50, s0
	s_nop 0
	v_addc_co_u32_e32 v63, vcc, 0, v61, vcc
	global_store_short v[62:63], v64, off
	v_add_co_u32_e32 v62, vcc, 0x4000, v60
	v_cvt_pk_bf16_f32 v64, v55, s0
	s_nop 0
	v_addc_co_u32_e32 v63, vcc, 0, v61, vcc
	global_store_short v[62:63], v64, off
	v_add_co_u32_e32 v62, vcc, 0x14000, v60
	v_cvt_pk_bf16_f32 v64, v51, s0
	s_nop 0
	v_addc_co_u32_e32 v63, vcc, 0, v61, vcc
	global_store_short v[62:63], v64, off
	v_add_co_u32_e32 v62, vcc, 0x8000, v60
	v_cvt_pk_bf16_f32 v64, v56, s0
	s_nop 0
	v_addc_co_u32_e32 v63, vcc, 0, v61, vcc
	global_store_short v[62:63], v64, off
	v_add_co_u32_e32 v62, vcc, 0x18000, v60
	v_cvt_pk_bf16_f32 v64, v52, s0
	s_nop 0
	v_addc_co_u32_e32 v63, vcc, 0, v61, vcc
	global_store_short v[62:63], v64, off
	v_add_co_u32_e32 v62, vcc, 0xc000, v60
	v_cvt_pk_bf16_f32 v64, v57, s0
	s_nop 0
	v_addc_co_u32_e32 v63, vcc, 0, v61, vcc
	v_add_co_u32_e32 v60, vcc, 0x1c000, v60
	global_store_short v[62:63], v64, off
	v_cvt_pk_bf16_f32 v62, v53, s0
	v_addc_co_u32_e32 v61, vcc, 0, v61, vcc
	s_mov_b64 s[16:17], 0
	global_store_short v[60:61], v62, off

;     __device__ __forceinline__ void storeT(bf16_t* vt  , int d0, int s, f32x4 v0, f32x4 v1) const {
;         const int pos = (s & ~15) + vperm16(s & 15);
; #pragma unroll
;         for (int e = 0; e < 4; ++e) { vt[(size_t)(d0 + e) * SEQ + pos] = (bf16_t)(pk_bf16(v0[e], 0.f) & 0xffffu); vt[(size_t)(d0 + 4 + e) * SEQ + pos] = (bf16_t)(pk_bf16(v1[e], 0.f) & 0xffffu); }
;     }
;     __device__ __forceinline__ void operator()(const f32x4 (&acc)[2][2][4][2], const Unit& u, int wr, int wc, int fr, int fq) const {
;     ...
;                     f32x4 v0 = acc[ai][bj][m][0] * rs1, v1 = acc[ai][bj][m][1] * rs1;
;                     if (mode == EP_PLAIN) { store8(O + (size_t)row * ldc + col8, v0, v1); }
;                     else if (mode == EP_RELU2) {
; #pragma unroll
;                         for (int e = 0; e < 4; ++e) { float a = fmaxf(v0[e], 0.f), b = fmaxf(v1[e], 0.f); v0[e] = a * a; v1[e] = b * b; }
;                         store8(O + (size_t)row * ldc + col8, v0, v1);
;                     } else if (mode == EP_Z1) {
;                         const int grp = grp0 + bj * 4;
;                         if (grp >= 20 && grp < 24) {
;                             const int b = row / SEQ, s = row % SEQ, kvh = wc >> 1;
;                             storeT(O2 + (size_t)(b * 2 + kvh) * 64 * SEQ, (wc & 1) * 32 + 8 * fq, s, v0, v1);
;                         } else if (grp == 44) {
;                             rope8(v0, v1, cst[m], fq);
;                             bf16_t* kr = O3 + (size_t)row * NQB + 64 + 8 * fq;
; #pragma unroll
;                             for (int h = 0; h < 8; ++h) store8(kr + h * 96, v0, v1);
;                         } else if (grp < 44) {
;                             if (grp < 16) { v0 = v0 * QA_SCALE; v1 = v1 * QA_SCALE; }
;                             store8(O + (size_t)row * ldc + col8, v0, v1);
;                             if (grp >= 24) {
;                                 float q = (v0[0] * v0[0] + v0[1] * v0[1]) + (v0[2] * v0[2] + v0[3] * v0[3]) + (v1[0] * v1[0] + v1[1] * v1[1]) + (v1[2] * v1[2] + v1[3] * v1[3]);
;                                 q += __shfl_xor(q, 16); q += __shfl_xor(q, 32);
;                                 if (fq == 0) ss_out[(size_t)row * 32 + grp - 24] = q;
;                             }
;                         }
;                     } else if (mode == EP_QB) {
.LBB0_571:
	v_add_f32_e32 v50, v142, v143
	v_fmamk_f32 v50, v50, 0x3b800000, v195
	v_add_u32_e32 v53, 0x90, v174
	v_rsq_f32_e32 v52, v50
	v_ashrrev_i32_e32 v50, 31, v53
	v_lshrrev_b32_e32 v50, 19, v50
	v_add_u32_e32 v50, v53, v50
	v_ashrrev_i32_e32 v50, 13, v50
	v_mul_i32_i24_e32 v51, 0x2000, v50
	v_sub_u32_e32 v51, v53, v51
	v_lshlrev_b32_e32 v56, 3, v50
	v_lshrrev_b32_e32 v50, 1, v51
	v_lshlrev_b32_e32 v54, 1, v51
	v_and_b32_e32 v50, 4, v50
	v_and_b32_e32 v54, 8, v54
	v_and_b32_e32 v51, 0xffffffd3, v51
	v_or3_b32 v50, v50, v51, v54
	v_ashrrev_i32_e32 v51, 31, v50
	v_mul_f32_e32 v48, v48, v52
	v_mul_f32_e32 v49, v49, v52
	v_mul_f32_e32 v46, v46, v52
	v_mul_f32_e32 v47, v47, v52
	v_mul_f32_e32 v44, v44, v52
	v_mul_f32_e32 v45, v45, v52
	v_mul_f32_e32 v54, v42, v52
	v_mul_f32_e32 v55, v43, v52
	s_and_b64 vcc, exec, s[0:1]
	s_mov_b64 s[16:17], -1
	s_cbranch_vccnz .LBB0_573
	v_add_u32_e32 v42, s46, v56
	v_ashrrev_i32_e32 v43, 31, v42
	v_lshlrev_b64 v[42:43], 20, v[42:43]
	v_lshl_add_u64 v[42:43], s[34:35], 0, v[42:43]
	v_lshl_add_u64 v[42:43], v[50:51], 1, v[42:43]
	v_mov_b32_e32 v123, v1
	v_lshl_add_u64 v[42:43], v[42:43], 0, v[122:123]
	v_cvt_pk_bf16_f32 v57, v46, s0
	v_add_co_u32_e32 v58, vcc, 0x10000, v42
	global_store_short v[42:43], v57, off
	v_cvt_pk_bf16_f32 v57, v54, s0
	v_addc_co_u32_e32 v59, vcc, 0, v43, vcc
	global_store_short v[58:59], v57, off
	v_add_co_u32_e32 v58, vcc, 0x4000, v42
	v_cvt_pk_bf16_f32 v57, v47, s0
	s_nop 0
	v_addc_co_u32_e32 v59, vcc, 0, v43, vcc
	global_store_short v[58:59], v57, off
	v_add_co_u32_e32 v58, vcc, 0x14000, v42
	v_cvt_pk_bf16_f32 v57, v55, s0
	s_nop 0
	v_addc_co_u32_e32 v59, vcc, 0, v43, vcc
	global_store_short v[58:59], v57, off
	v_add_co_u32_e32 v58, vcc, 0x8000, v42
	v_cvt_pk_bf16_f32 v57, v48, s0
	s_nop 0
	v_addc_co_u32_e32 v59, vcc, 0, v43, vcc
	global_store_short v[58:59], v57, off
	v_add_co_u32_e32 v58, vcc, 0x18000, v42
	v_cvt_pk_bf16_f32 v57, v44, s0
	s_nop 0
	v_addc_co_u32_e32 v59, vcc, 0, v43, vcc
	global_store_short v[58:59], v57, off
	v_add_co_u32_e32 v58, vcc, 0xc000, v42
	v_cvt_pk_bf16_f32 v57, v49, s0
	s_nop 0
	v_addc_co_u32_e32 v59, vcc, 0, v43, vcc
	v_add_co_u32_e32 v42, vcc, 0x1c000, v42
	global_store_short v[58:59], v57, off
	v_cvt_pk_bf16_f32 v57, v45, s0
	v_addc_co_u32_e32 v43, vcc, 0, v43, vcc
	s_mov_b64 s[16:17], 0
	global_store_short v[42:43], v57, off

;     __device__ __forceinline__ void storeT(bf16_t* vt  , int d0, int s, f32x4 v0, f32x4 v1) const {
;         const int pos = (s & ~15) + vperm16(s & 15);
; #pragma unroll
;         for (int e = 0; e < 4; ++e) { vt[(size_t)(d0 + e) * SEQ + pos] = (bf16_t)(pk_bf16(v0[e], 0.f) & 0xffffu); vt[(size_t)(d0 + 4 + e) * SEQ + pos] = (bf16_t)(pk_bf16(v1[e], 0.f) & 0xffffu); }
;     }
;     __device__ __forceinline__ void operator()(const f32x4 (&acc)[2][2][4][2], const Unit& u, int wr, int wc, int fr, int fq) const {
;     ...
;                     f32x4 v0 = acc[ai][bj][m][0] * rs1, v1 = acc[ai][bj][m][1] * rs1;
;                     if (mode == EP_PLAIN) { store8(O + (size_t)row * ldc + col8, v0, v1); }
;                     else if (mode == EP_RELU2) {
; #pragma unroll
;                         for (int e = 0; e < 4; ++e) { float a = fmaxf(v0[e], 0.f), b = fmaxf(v1[e], 0.f); v0[e] = a * a; v1[e] = b * b; }
;                         store8(O + (size_t)row * ldc + col8, v0, v1);
;                     } else if (mode == EP_Z1) {
;                         const int grp = grp0 + bj * 4;
;                         if (grp >= 20 && grp < 24) {
;                             const int b = row / SEQ, s = row % SEQ, kvh = wc >> 1;
;                             storeT(O2 + (size_t)(b * 2 + kvh) * 64 * SEQ, (wc & 1) * 32 + 8 * fq, s, v0, v1);
;                         } else if (grp == 44) {
;                             rope8(v0, v1, cst[m], fq);
;                             bf16_t* kr = O3 + (size_t)row * NQB + 64 + 8 * fq;
; #pragma unroll
;                             for (int h = 0; h < 8; ++h) store8(kr + h * 96, v0, v1);
;                         } else if (grp < 44) {
;                             if (grp < 16) { v0 = v0 * QA_SCALE; v1 = v1 * QA_SCALE; }
;                             store8(O + (size_t)row * ldc + col8, v0, v1);
;                             if (grp >= 24) {
;                                 float q = (v0[0] * v0[0] + v0[1] * v0[1]) + (v0[2] * v0[2] + v0[3] * v0[3]) + (v1[0] * v1[0] + v1[1] * v1[1]) + (v1[2] * v1[2] + v1[3] * v1[3]);
;                                 q += __shfl_xor(q, 16); q += __shfl_xor(q, 32);
;                                 if (fq == 0) ss_out[(size_t)row * 32 + grp - 24] = q;
;                             }
;                         }
;                     } else if (mode == EP_QB) {
.LBB0_575:
	v_mov_b32_e32 v53, v52
	v_mov_b32_e32 v44, v52
	v_mov_b32_e32 v45, v52
	v_mul_f32_e32 v40, v40, v44
	v_mul_f32_e32 v41, v41, v45
	v_mul_f32_e32 v38, v38, v52
	v_mul_f32_e32 v39, v39, v53
	v_mul_f32_e32 v36, v36, v44
	v_mul_f32_e32 v37, v37, v45
	v_mul_f32_e32 v34, v34, v52
	v_mul_f32_e32 v35, v35, v53
	s_and_b64 vcc, exec, s[0:1]
	s_mov_b64 s[16:17], -1
	s_cbranch_vccnz .LBB0_577
	v_add_u32_e32 v44, s41, v56
	v_ashrrev_i32_e32 v45, 31, v44
	v_lshlrev_b64 v[44:45], 20, v[44:45]
	v_lshl_add_u64 v[44:45], s[34:35], 0, v[44:45]
	v_lshl_add_u64 v[44:45], v[50:51], 1, v[44:45]
	v_mov_b32_e32 v123, v1
	v_cvt_pk_bf16_f32 v46, v38, s0
	v_lshl_add_u64 v[44:45], v[44:45], 0, v[122:123]
	global_store_short v[44:45], v46, off
	v_add_co_u32_e32 v46, vcc, 0x10000, v44
	v_cvt_pk_bf16_f32 v48, v34, s0
	s_nop 0
	v_addc_co_u32_e32 v47, vcc, 0, v45, vcc
	global_store_short v[46:47], v48, off
	v_add_co_u32_e32 v46, vcc, 0x4000, v44
	v_cvt_pk_bf16_f32 v48, v39, s0
	s_nop 0
	v_addc_co_u32_e32 v47, vcc, 0, v45, vcc
	global_store_short v[46:47], v48, off
	v_add_co_u32_e32 v46, vcc, 0x14000, v44
	v_cvt_pk_bf16_f32 v48, v35, s0
	s_nop 0
	v_addc_co_u32_e32 v47, vcc, 0, v45, vcc
	global_store_short v[46:47], v48, off
	v_add_co_u32_e32 v46, vcc, 0x8000, v44
	v_cvt_pk_bf16_f32 v48, v40, s0
	s_nop 0
	v_addc_co_u32_e32 v47, vcc, 0, v45, vcc
	global_store_short v[46:47], v48, off
	v_add_co_u32_e32 v46, vcc, 0x18000, v44
	v_cvt_pk_bf16_f32 v48, v36, s0
	s_nop 0
	v_addc_co_u32_e32 v47, vcc, 0, v45, vcc
	global_store_short v[46:47], v48, off
	v_add_co_u32_e32 v46, vcc, 0xc000, v44
	v_cvt_pk_bf16_f32 v48, v41, s0
	s_nop 0
	v_addc_co_u32_e32 v47, vcc, 0, v45, vcc
	v_add_co_u32_e32 v44, vcc, 0x1c000, v44
	global_store_short v[46:47], v48, off
	v_cvt_pk_bf16_f32 v46, v37, s0
	v_addc_co_u32_e32 v45, vcc, 0, v45, vcc
	s_mov_b64 s[16:17], 0
	global_store_short v[44:45], v46, off

;     __device__ __forceinline__ void storeT(bf16_t* vt  , int d0, int s, f32x4 v0, f32x4 v1) const {
;         const int pos = (s & ~15) + vperm16(s & 15);
; #pragma unroll
;         for (int e = 0; e < 4; ++e) { vt[(size_t)(d0 + e) * SEQ + pos] = (bf16_t)(pk_bf16(v0[e], 0.f) & 0xffffu); vt[(size_t)(d0 + 4 + e) * SEQ + pos] = (bf16_t)(pk_bf16(v1[e], 0.f) & 0xffffu); }
;     }
;     __device__ __forceinline__ void operator()(const f32x4 (&acc)[2][2][4][2], const Unit& u, int wr, int wc, int fr, int fq) const {
;     ...
;                     f32x4 v0 = acc[ai][bj][m][0] * rs1, v1 = acc[ai][bj][m][1] * rs1;
;                     if (mode == EP_PLAIN) { store8(O + (size_t)row * ldc + col8, v0, v1); }
;                     else if (mode == EP_RELU2) {
; #pragma unroll
;                         for (int e = 0; e < 4; ++e) { float a = fmaxf(v0[e], 0.f), b = fmaxf(v1[e], 0.f); v0[e] = a * a; v1[e] = b * b; }
;                         store8(O + (size_t)row * ldc + col8, v0, v1);
;                     } else if (mode == EP_Z1) {
;                         const int grp = grp0 + bj * 4;
;                         if (grp >= 20 && grp < 24) {
;                             const int b = row / SEQ, s = row % SEQ, kvh = wc >> 1;
;                             storeT(O2 + (size_t)(b * 2 + kvh) * 64 * SEQ, (wc & 1) * 32 + 8 * fq, s, v0, v1);
;                         } else if (grp == 44) {
;                             rope8(v0, v1, cst[m], fq);
;                             bf16_t* kr = O3 + (size_t)row * NQB + 64 + 8 * fq;
; #pragma unroll
;                             for (int h = 0; h < 8; ++h) store8(kr + h * 96, v0, v1);
;                         } else if (grp < 44) {
;                             if (grp < 16) { v0 = v0 * QA_SCALE; v1 = v1 * QA_SCALE; }
;                             store8(O + (size_t)row * ldc + col8, v0, v1);
;                             if (grp >= 24) {
;                                 float q = (v0[0] * v0[0] + v0[1] * v0[1]) + (v0[2] * v0[2] + v0[3] * v0[3]) + (v1[0] * v1[0] + v1[1] * v1[1]) + (v1[2] * v1[2] + v1[3] * v1[3]);
;                                 q += __shfl_xor(q, 16); q += __shfl_xor(q, 32);
;                                 if (fq == 0) ss_out[(size_t)row * 32 + grp - 24] = q;
;                             }
;                         }
;                     } else if (mode == EP_QB) {
.LBB0_579:
	s_waitcnt lgkmcnt(1)
	v_add_f32_e32 v34, v140, v141
	v_fmamk_f32 v34, v34, 0x3b800000, v195
	v_add_u32_e32 v37, 0xa0, v174
	v_rsq_f32_e32 v36, v34
	v_ashrrev_i32_e32 v34, 31, v37
	v_lshrrev_b32_e32 v34, 19, v34
	v_add_u32_e32 v34, v37, v34
	v_ashrrev_i32_e32 v34, 13, v34
	v_mul_i32_i24_e32 v35, 0x2000, v34
	v_sub_u32_e32 v35, v37, v35
	v_lshlrev_b32_e32 v40, 3, v34
	v_lshrrev_b32_e32 v34, 1, v35
	v_lshlrev_b32_e32 v38, 1, v35
	v_and_b32_e32 v34, 4, v34
	v_and_b32_e32 v38, 8, v38
	v_and_b32_e32 v35, 0xffffffe3, v35
	v_or3_b32 v34, v34, v35, v38
	v_ashrrev_i32_e32 v35, 31, v34
	v_mul_f32_e32 v32, v32, v36
	v_mul_f32_e32 v33, v33, v36
	v_mul_f32_e32 v30, v30, v36
	v_mul_f32_e32 v31, v31, v36
	v_mul_f32_e32 v28, v28, v36
	v_mul_f32_e32 v29, v29, v36
	v_mul_f32_e32 v38, v26, v36
	v_mul_f32_e32 v39, v27, v36
	s_and_b64 vcc, exec, s[0:1]
	s_mov_b64 s[16:17], -1
	s_cbranch_vccnz .LBB0_581
	v_add_u32_e32 v26, s46, v40
	v_ashrrev_i32_e32 v27, 31, v26
	v_lshlrev_b64 v[26:27], 20, v[26:27]
	v_lshl_add_u64 v[26:27], s[34:35], 0, v[26:27]
	v_lshl_add_u64 v[26:27], v[34:35], 1, v[26:27]
	v_mov_b32_e32 v123, v1
	v_lshl_add_u64 v[26:27], v[26:27], 0, v[122:123]
	v_cvt_pk_bf16_f32 v41, v30, s0
	v_add_co_u32_e32 v42, vcc, 0x10000, v26
	global_store_short v[26:27], v41, off
	v_cvt_pk_bf16_f32 v41, v38, s0
	v_addc_co_u32_e32 v43, vcc, 0, v27, vcc
	global_store_short v[42:43], v41, off
	v_add_co_u32_e32 v42, vcc, 0x4000, v26
	v_cvt_pk_bf16_f32 v41, v31, s0
	s_nop 0
	v_addc_co_u32_e32 v43, vcc, 0, v27, vcc
	global_store_short v[42:43], v41, off
	v_add_co_u32_e32 v42, vcc, 0x14000, v26
	v_cvt_pk_bf16_f32 v41, v39, s0
	s_nop 0
	v_addc_co_u32_e32 v43, vcc, 0, v27, vcc
	global_store_short v[42:43], v41, off
	v_add_co_u32_e32 v42, vcc, 0x8000, v26
	v_cvt_pk_bf16_f32 v41, v32, s0
	s_nop 0
	v_addc_co_u32_e32 v43, vcc, 0, v27, vcc
	global_store_short v[42:43], v41, off
	v_add_co_u32_e32 v42, vcc, 0x18000, v26
	v_cvt_pk_bf16_f32 v41, v28, s0
	s_nop 0
	v_addc_co_u32_e32 v43, vcc, 0, v27, vcc
	global_store_short v[42:43], v41, off
	v_add_co_u32_e32 v42, vcc, 0xc000, v26
	v_cvt_pk_bf16_f32 v41, v33, s0
	s_nop 0
	v_addc_co_u32_e32 v43, vcc, 0, v27, vcc
	v_add_co_u32_e32 v26, vcc, 0x1c000, v26
	global_store_short v[42:43], v41, off
	v_cvt_pk_bf16_f32 v41, v29, s0
	v_addc_co_u32_e32 v27, vcc, 0, v27, vcc
	s_mov_b64 s[16:17], 0
	global_store_short v[26:27], v41, off

;     __device__ __forceinline__ void operator()(const f32x4 (&acc)[2][2][4][2], const Unit& u, int wr, int wc, int fr, int fq) const {
;     ...
;                     f32x4 v0 = acc[ai][bj][m][0] * rs1, v1 = acc[ai][bj][m][1] * rs1;
;                     if (mode == EP_PLAIN) { store8(O + (size_t)row * ldc + col8, v0, v1); }
;                     else if (mode == EP_RELU2) {
; #pragma unroll
;                         for (int e = 0; e < 4; ++e) { float a = fmaxf(v0[e], 0.f), b = fmaxf(v1[e], 0.f); v0[e] = a * a; v1[e] = b * b; }
;                         store8(O + (size_t)row * ldc + col8, v0, v1);
;                     } else if (mode == EP_Z1) {
;                         const int grp = grp0 + bj * 4;
;                         if (grp >= 20 && grp < 24) {
;                             const int b = row / SEQ, s = row % SEQ, kvh = wc >> 1;
;                             storeT(O2 + (size_t)(b * 2 + kvh) * 64 * SEQ, (wc & 1) * 32 + 8 * fq, s, v0, v1);
;                         } else if (grp == 44) {
;                             rope8(v0, v1, cst[m], fq);
;                             bf16_t* kr = O3 + (size_t)row * NQB + 64 + 8 * fq;
; #pragma unroll
;                             for (int h = 0; h < 8; ++h) store8(kr + h * 96, v0, v1);
;                         } else if (grp < 44) {
;                             if (grp < 16) { v0 = v0 * QA_SCALE; v1 = v1 * QA_SCALE; }
;                             store8(O + (size_t)row * ldc + col8, v0, v1);
;                             if (grp >= 24) {
;                                 float q = (v0[0] * v0[0] + v0[1] * v0[1]) + (v0[2] * v0[2] + v0[3] * v0[3]) + (v1[0] * v1[0] + v1[1] * v1[1]) + (v1[2] * v1[2] + v1[3] * v1[3]);
;                                 q += __shfl_xor(q, 16); q += __shfl_xor(q, 32);
;                                 if (fq == 0) ss_out[(size_t)row * 32 + grp - 24] = q;
;                             }
;                         }
;                     } else if (mode == EP_QB) {
;                         if (bj == 0 ? rope0 : rope1) rope8(v0, v1, cst[m], fq);
;                         v0 = v0 * QB_SCALE; v1 = v1 * QB_SCALE;
;                         store8(O + (size_t)row * ldc + col8, v0, v1);
;                     } else if (mode == EP_KVB) {
;                         const int head = u.pn * 2 + bj;
.LBB0_583:
	v_mov_b32_e32 v37, v36
	v_mov_b32_e32 v28, v36
	v_mov_b32_e32 v29, v36
	v_readlane_b32 s48, v254, 36
	v_mul_f32_e32 v24, v24, v28
	v_mul_f32_e32 v25, v25, v29
	v_mul_f32_e32 v22, v22, v36
	v_mul_f32_e32 v23, v23, v37
	v_mul_f32_e32 v20, v20, v28
	v_mul_f32_e32 v21, v21, v29
	v_mul_f32_e32 v18, v18, v36
	v_mul_f32_e32 v19, v19, v37
	s_and_b64 vcc, exec, s[0:1]
	s_mov_b64 s[16:17], -1
	v_readlane_b32 s49, v254, 37
	s_cbranch_vccnz .LBB0_585
	v_add_u32_e32 v28, s41, v40
	v_ashrrev_i32_e32 v29, 31, v28
	v_lshlrev_b64 v[28:29], 20, v[28:29]
	v_lshl_add_u64 v[28:29], s[34:35], 0, v[28:29]
	v_lshl_add_u64 v[28:29], v[34:35], 1, v[28:29]
	v_mov_b32_e32 v123, v1
	v_cvt_pk_bf16_f32 v30, v22, s0
	v_lshl_add_u64 v[28:29], v[28:29], 0, v[122:123]
	global_store_short v[28:29], v30, off
	v_add_co_u32_e32 v30, vcc, 0x10000, v28
	v_cvt_pk_bf16_f32 v32, v18, s0
	s_nop 0
	v_addc_co_u32_e32 v31, vcc, 0, v29, vcc
	global_store_short v[30:31], v32, off
	v_add_co_u32_e32 v30, vcc, 0x4000, v28
	v_cvt_pk_bf16_f32 v32, v23, s0
	s_nop 0
	v_addc_co_u32_e32 v31, vcc, 0, v29, vcc
	global_store_short v[30:31], v32, off
	v_add_co_u32_e32 v30, vcc, 0x14000, v28
	v_cvt_pk_bf16_f32 v32, v19, s0
	s_nop 0
	v_addc_co_u32_e32 v31, vcc, 0, v29, vcc
	global_store_short v[30:31], v32, off
	v_add_co_u32_e32 v30, vcc, 0x8000, v28
	v_cvt_pk_bf16_f32 v32, v24, s0
	s_nop 0
	v_addc_co_u32_e32 v31, vcc, 0, v29, vcc
	global_store_short v[30:31], v32, off
	v_add_co_u32_e32 v30, vcc, 0x18000, v28
	v_cvt_pk_bf16_f32 v32, v20, s0
	s_nop 0
	v_addc_co_u32_e32 v31, vcc, 0, v29, vcc
	global_store_short v[30:31], v32, off
	v_add_co_u32_e32 v30, vcc, 0xc000, v28
	v_cvt_pk_bf16_f32 v32, v25, s0
	s_nop 0
	v_addc_co_u32_e32 v31, vcc, 0, v29, vcc
	v_add_co_u32_e32 v28, vcc, 0x1c000, v28
	global_store_short v[30:31], v32, off
	v_cvt_pk_bf16_f32 v30, v21, s0
	v_addc_co_u32_e32 v29, vcc, 0, v29, vcc
	s_mov_b64 s[16:17], 0
	global_store_short v[28:29], v30, off

;     __device__ __forceinline__ void operator()(const f32x4 (&acc)[2][2][4][2], const Unit& u, int wr, int wc, int fr, int fq) const {
;     ...
;                     f32x4 v0 = acc[ai][bj][m][0] * rs1, v1 = acc[ai][bj][m][1] * rs1;
;                     if (mode == EP_PLAIN) { store8(O + (size_t)row * ldc + col8, v0, v1); }
;                     else if (mode == EP_RELU2) {
; #pragma unroll
;                         for (int e = 0; e < 4; ++e) { float a = fmaxf(v0[e], 0.f), b = fmaxf(v1[e], 0.f); v0[e] = a * a; v1[e] = b * b; }
;                         store8(O + (size_t)row * ldc + col8, v0, v1);
;                     } else if (mode == EP_Z1) {
;                         const int grp = grp0 + bj * 4;
;                         if (grp >= 20 && grp < 24) {
;                             const int b = row / SEQ, s = row % SEQ, kvh = wc >> 1;
;                             storeT(O2 + (size_t)(b * 2 + kvh) * 64 * SEQ, (wc & 1) * 32 + 8 * fq, s, v0, v1);
;                         } else if (grp == 44) {
;                             rope8(v0, v1, cst[m], fq);
;                             bf16_t* kr = O3 + (size_t)row * NQB + 64 + 8 * fq;
; #pragma unroll
;                             for (int h = 0; h < 8; ++h) store8(kr + h * 96, v0, v1);
;                         } else if (grp < 44) {
;                             if (grp < 16) { v0 = v0 * QA_SCALE; v1 = v1 * QA_SCALE; }
;                             store8(O + (size_t)row * ldc + col8, v0, v1);
;                             if (grp >= 24) {
;                                 float q = (v0[0] * v0[0] + v0[1] * v0[1]) + (v0[2] * v0[2] + v0[3] * v0[3]) + (v1[0] * v1[0] + v1[1] * v1[1]) + (v1[2] * v1[2] + v1[3] * v1[3]);
;                                 q += __shfl_xor(q, 16); q += __shfl_xor(q, 32);
;                                 if (fq == 0) ss_out[(size_t)row * 32 + grp - 24] = q;
;                             }
;                         }
;                     } else if (mode == EP_QB) {
;                         if (bj == 0 ? rope0 : rope1) rope8(v0, v1, cst[m], fq);
;                         v0 = v0 * QB_SCALE; v1 = v1 * QB_SCALE;
;                         store8(O + (size_t)row * ldc + col8, v0, v1);
;                     } else if (mode == EP_KVB) {
;                         const int head = u.pn * 2 + bj;
.LBB0_587:
	s_waitcnt lgkmcnt(0)
	v_add_f32_e32 v18, v136, v137
	v_fmamk_f32 v18, v18, 0x3b800000, v195
	v_add_u32_e32 v21, 0xb0, v174
	v_rsq_f32_e32 v20, v18
	v_ashrrev_i32_e32 v18, 31, v21
	v_lshrrev_b32_e32 v18, 19, v18
	v_add_u32_e32 v18, v21, v18
	v_ashrrev_i32_e32 v18, 13, v18
	v_mul_i32_i24_e32 v19, 0x2000, v18
	v_sub_u32_e32 v19, v21, v19
	v_lshlrev_b32_e32 v24, 3, v18
	v_lshrrev_b32_e32 v18, 1, v19
	v_lshlrev_b32_e32 v22, 1, v19
	v_and_b32_e32 v18, 4, v18
	v_and_b32_e32 v22, 8, v22
	v_and_b32_e32 v19, -13, v19
	v_or3_b32 v18, v18, v19, v22
	v_ashrrev_i32_e32 v19, 31, v18
	v_mul_f32_e32 v16, v16, v20
	v_mul_f32_e32 v17, v17, v20
	v_mul_f32_e32 v14, v14, v20
	v_mul_f32_e32 v15, v15, v20
	v_mul_f32_e32 v12, v12, v20
	v_mul_f32_e32 v13, v13, v20
	v_mul_f32_e32 v22, v10, v20
	v_mul_f32_e32 v23, v11, v20
	s_and_b64 vcc, exec, s[0:1]
	s_mov_b64 s[16:17], -1
	s_cbranch_vccnz .LBB0_589
	v_add_u32_e32 v10, s46, v24
	v_ashrrev_i32_e32 v11, 31, v10
	v_lshlrev_b64 v[10:11], 20, v[10:11]
	v_lshl_add_u64 v[10:11], s[34:35], 0, v[10:11]
	v_lshl_add_u64 v[10:11], v[18:19], 1, v[10:11]
	v_mov_b32_e32 v123, v1
	v_lshl_add_u64 v[10:11], v[10:11], 0, v[122:123]
	v_cvt_pk_bf16_f32 v25, v14, s0
	v_add_co_u32_e32 v26, vcc, 0x10000, v10
	global_store_short v[10:11], v25, off
	v_cvt_pk_bf16_f32 v25, v22, s0
	v_addc_co_u32_e32 v27, vcc, 0, v11, vcc
	global_store_short v[26:27], v25, off
	v_add_co_u32_e32 v26, vcc, 0x4000, v10
	v_cvt_pk_bf16_f32 v25, v15, s0
	s_nop 0
	v_addc_co_u32_e32 v27, vcc, 0, v11, vcc
	global_store_short v[26:27], v25, off
	v_add_co_u32_e32 v26, vcc, 0x14000, v10
	v_cvt_pk_bf16_f32 v25, v23, s0
	s_nop 0
	v_addc_co_u32_e32 v27, vcc, 0, v11, vcc
	global_store_short v[26:27], v25, off
	v_add_co_u32_e32 v26, vcc, 0x8000, v10
	v_cvt_pk_bf16_f32 v25, v16, s0
	s_nop 0
	v_addc_co_u32_e32 v27, vcc, 0, v11, vcc
	global_store_short v[26:27], v25, off
	v_add_co_u32_e32 v26, vcc, 0x18000, v10
	v_cvt_pk_bf16_f32 v25, v12, s0
	s_nop 0
	v_addc_co_u32_e32 v27, vcc, 0, v11, vcc
	global_store_short v[26:27], v25, off
	v_add_co_u32_e32 v26, vcc, 0xc000, v10
	v_cvt_pk_bf16_f32 v25, v17, s0
	s_nop 0
	v_addc_co_u32_e32 v27, vcc, 0, v11, vcc
	v_add_co_u32_e32 v10, vcc, 0x1c000, v10
	global_store_short v[26:27], v25, off
	v_cvt_pk_bf16_f32 v25, v13, s0
	v_addc_co_u32_e32 v11, vcc, 0, v11, vcc
	s_mov_b64 s[16:17], 0
	global_store_short v[10:11], v25, off

;     __device__ __forceinline__ void operator()(const f32x4 (&acc)[2][2][4][2], const Unit& u, int wr, int wc, int fr, int fq) const {
;     ...
;                     f32x4 v0 = acc[ai][bj][m][0] * rs1, v1 = acc[ai][bj][m][1] * rs1;
;                     if (mode == EP_PLAIN) { store8(O + (size_t)row * ldc + col8, v0, v1); }
;                     else if (mode == EP_RELU2) {
; #pragma unroll
;                         for (int e = 0; e < 4; ++e) { float a = fmaxf(v0[e], 0.f), b = fmaxf(v1[e], 0.f); v0[e] = a * a; v1[e] = b * b; }
;                         store8(O + (size_t)row * ldc + col8, v0, v1);
;                     } else if (mode == EP_Z1) {
;                         const int grp = grp0 + bj * 4;
;                         if (grp >= 20 && grp < 24) {
;                             const int b = row / SEQ, s = row % SEQ, kvh = wc >> 1;
;                             storeT(O2 + (size_t)(b * 2 + kvh) * 64 * SEQ, (wc & 1) * 32 + 8 * fq, s, v0, v1);
;                         } else if (grp == 44) {
;                             rope8(v0, v1, cst[m], fq);
;                             bf16_t* kr = O3 + (size_t)row * NQB + 64 + 8 * fq;
; #pragma unroll
;                             for (int h = 0; h < 8; ++h) store8(kr + h * 96, v0, v1);
;                         } else if (grp < 44) {
;                             if (grp < 16) { v0 = v0 * QA_SCALE; v1 = v1 * QA_SCALE; }
;                             store8(O + (size_t)row * ldc + col8, v0, v1);
;                             if (grp >= 24) {
;                                 float q = (v0[0] * v0[0] + v0[1] * v0[1]) + (v0[2] * v0[2] + v0[3] * v0[3]) + (v1[0] * v1[0] + v1[1] * v1[1]) + (v1[2] * v1[2] + v1[3] * v1[3]);
;                                 q += __shfl_xor(q, 16); q += __shfl_xor(q, 32);
;                                 if (fq == 0) ss_out[(size_t)row * 32 + grp - 24] = q;
;                             }
;                         }
;                     } else if (mode == EP_QB) {
;                         if (bj == 0 ? rope0 : rope1) rope8(v0, v1, cst[m], fq);
;                         v0 = v0 * QB_SCALE; v1 = v1 * QB_SCALE;
;                         store8(O + (size_t)row * ldc + col8, v0, v1);
;                     } else if (mode == EP_KVB) {
;                         const int head = u.pn * 2 + bj;
.LBB0_591:
	v_mov_b32_e32 v21, v20
	v_mov_b32_e32 v12, v20
	v_mov_b32_e32 v13, v20
	v_readlane_b32 s46, v254, 34
	v_mul_f32_e32 v8, v8, v12
	v_mul_f32_e32 v9, v9, v13
	v_mul_f32_e32 v6, v6, v20
	v_mul_f32_e32 v7, v7, v21
	v_mul_f32_e32 v4, v4, v12
	v_mul_f32_e32 v5, v5, v13
	v_mul_f32_e32 v2, v2, v20
	v_mul_f32_e32 v3, v3, v21
	s_and_b64 vcc, exec, s[0:1]
	s_mov_b64 s[0:1], -1
	v_readlane_b32 s47, v254, 35
	s_cbranch_vccz .LBB0_594
	s_andn2_b64 vcc, exec, s[0:1]
	s_cbranch_vccz .LBB0_595

; __device__ __forceinline__ float sigmoidf_(float x) { return __builtin_amdgcn_rcpf(1.0f + __builtin_amdgcn_exp2f(-1.4426950408889634f * x)); }
;     __device__ __forceinline__ void operator()(const f32x4 (&acc)[2][2][4][2], const Unit& u, int wr, int wc, int fr, int fq) const {
;     ...
;                     if (4 * fq < rs_n) part[ai][m] = *(const f32x4*)(rs + (size_t)(row0 + ai * HALF + m * 16) * rs_ld + rs_off + 4 * fq);
;                 }
; #pragma unroll
;             for (int ai = 0; ai < 2; ++ai)
; #pragma unroll
;                 for (int m = 0; m < 4; ++m) {
;                     float t = (part[ai][m][0] + part[ai][m][1]) + (part[ai][m][2] + part[ai][m][3]);
;                     t += __shfl_xor(t, 16); t += __shfl_xor(t, 32);
;                     rsc[ai][m] = __builtin_amdgcn_rsqf(t * rs_inv + EPS);
;     ...
;                 if (mode == EP_GATE) {
;                     const size_t off = (size_t)row * DM + u.pn * 128 + wc * 32 + 8 * fq;
;                     const f32x4 a0 = acc[ai][0][m][0] * rs1, a1 = acc[ai][0][m][1] * rs1, b0 = acc[ai][1][m][0] * rs1, b1 = acc[ai][1][m][1] * rs1;
;                     const u32x4 y1 = yall[ai][m][0], y2 = yall[ai][m][1];
;                     f32x4 r0, r1;
;                     r0[0] = sigmoidf_(a0[0]) * bf_lo(y1.x) + sigmoidf_(b0[0]) * bf_lo(y2.x); r0[1] = sigmoidf_(a0[1]) * bf_hi(y1.x) + sigmoidf_(b0[1]) * bf_hi(y2.x);
;                     r0[2] = sigmoidf_(a0[2]) * bf_lo(y1.y) + sigmoidf_(b0[2]) * bf_lo(y2.y); r0[3] = sigmoidf_(a0[3]) * bf_hi(y1.y) + sigmoidf_(b0[3]) * bf_hi(y2.y);
;                     r1[0] = sigmoidf_(a1[0]) * bf_lo(y1.z) + sigmoidf_(b1[0]) * bf_lo(y2.z); r1[1] = sigmoidf_(a1[1]) * bf_hi(y1.z) + sigmoidf_(b1[1]) * bf_hi(y2.z);
;                     r1[2] = sigmoidf_(a1[2]) * bf_lo(y1.w) + sigmoidf_(b1[2]) * bf_lo(y2.w); r1[3] = sigmoidf_(a1[3]) * bf_hi(y1.w) + sigmoidf_(b1[3]) * bf_hi(y2.w);
.LBB0_1082:
	v_lshl_add_u32 v210, s22, 8, v171
	v_ashrrev_i32_e32 v211, 31, v210
	v_lshlrev_b64 v[130:131], 6, v[210:211]
	v_lshl_add_u64 v[130:131], v[172:173], 0, v[130:131]
	global_load_dwordx4 v[130:133], v[130:131], off
	v_or_b32_e32 v206, 16, v210
	v_ashrrev_i32_e32 v207, 31, v206
	v_lshlrev_b64 v[134:135], 6, v[206:207]
	v_lshl_add_u64 v[134:135], v[172:173], 0, v[134:135]
	global_load_dwordx4 v[134:137], v[134:135], off
	v_or_b32_e32 v204, 32, v210
	v_ashrrev_i32_e32 v205, 31, v204
	v_lshlrev_b64 v[138:139], 6, v[204:205]
	v_lshl_add_u64 v[138:139], v[172:173], 0, v[138:139]
	global_load_dwordx4 v[138:141], v[138:139], off
	v_or_b32_e32 v198, 48, v210
	v_ashrrev_i32_e32 v199, 31, v198
	v_lshlrev_b64 v[142:143], 6, v[198:199]
	v_lshl_add_u64 v[142:143], v[172:173], 0, v[142:143]
	global_load_dwordx4 v[142:145], v[142:143], off
	v_add_u32_e32 v188, 0x80, v210
	v_ashrrev_i32_e32 v189, 31, v188
	v_lshlrev_b64 v[146:147], 6, v[188:189]
	v_lshl_add_u64 v[146:147], v[172:173], 0, v[146:147]
	global_load_dwordx4 v[146:149], v[146:147], off
	v_add_u32_e32 v184, 0x90, v210
	v_ashrrev_i32_e32 v185, 31, v184
	v_lshlrev_b64 v[150:151], 6, v[184:185]
	v_lshl_add_u64 v[150:151], v[172:173], 0, v[150:151]
	global_load_dwordx4 v[150:153], v[150:151], off
	v_add_u32_e32 v182, 0xa0, v210
	v_ashrrev_i32_e32 v183, 31, v182
	v_lshlrev_b64 v[154:155], 6, v[182:183]
	v_lshl_add_u64 v[154:155], v[172:173], 0, v[154:155]
	global_load_dwordx4 v[154:157], v[154:155], off
	v_add_u32_e32 v178, 0xb0, v210
	v_ashrrev_i32_e32 v179, 31, v178
	v_lshlrev_b64 v[158:159], 6, v[178:179]
	v_lshl_add_u64 v[158:159], v[172:173], 0, v[158:159]
	global_load_dwordx4 v[158:161], v[158:159], off
	s_lshl_b32 s4, s21, 7
	s_ashr_i32 s5, s4, 31
	v_mov_b32_e32 v201, s5
	v_or_b32_e32 v200, s4, v170
	s_lshl_b64 s[4:5], s[4:5], 1
	s_andn2_b64 vcc, exec, s[36:37]
	s_waitcnt vmcnt(0)
	v_mov_b32_e32 v190, v131
	v_mov_b32_e32 v191, v132
	v_mov_b32_e32 v131, v133
	v_add_f32_e32 v130, v190, v130
	v_add_f32_e32 v131, v191, v131
	v_mov_b32_e32 v132, v195
	v_add_f32_e32 v130, v130, v131
	ds_bpermute_b32 v131, v216, v130
	s_waitcnt lgkmcnt(0)
	v_add_f32_e32 v130, v130, v131
	ds_bpermute_b32 v131, v217, v130
	s_waitcnt lgkmcnt(0)
	v_add_f32_e32 v130, v130, v131
	v_fmamk_f32 v130, v130, 0x3a800000, v195
	v_rsq_f32_e32 v214, v130
	v_mov_b32_e32 v130, v135
	v_mov_b32_e32 v131, v136
	v_mov_b32_e32 v135, v137
	v_add_f32_e32 v130, v130, v134
	v_add_f32_e32 v131, v131, v135
	v_mul_f32_e32 v118, v118, v214
	v_mul_f32_e32 v119, v119, v214
	v_add_f32_e32 v130, v130, v131
	ds_bpermute_b32 v131, v216, v130
	v_mul_f32_e32 v126, v126, v214
	v_mul_f32_e32 v127, v127, v214
	v_mul_f32_e32 v118, 0xbfb8aa3b, v118
	v_mul_f32_e32 v119, 0xbfb8aa3b, v119
	v_mul_f32_e32 v126, 0xbfb8aa3b, v126
	s_waitcnt lgkmcnt(0)
	v_add_f32_e32 v130, v130, v131
	ds_bpermute_b32 v131, v217, v130
	v_exp_f32_e32 v118, v118
	v_mul_f32_e32 v127, 0xbfb8aa3b, v127
	v_exp_f32_e32 v119, v119
	v_exp_f32_e32 v126, v126
	s_waitcnt lgkmcnt(0)
	v_add_f32_e32 v130, v130, v131
	v_fmamk_f32 v130, v130, 0x3a800000, v132
	v_rsq_f32_e32 v212, v130
	v_mov_b32_e32 v130, v139
	v_mov_b32_e32 v131, v140
	v_mov_b32_e32 v139, v141
	v_add_f32_e32 v130, v130, v138
	v_add_f32_e32 v131, v131, v139
	v_exp_f32_e32 v127, v127
	v_add_f32_e32 v130, v130, v131
	ds_bpermute_b32 v131, v216, v130
	v_add_f32_e32 v118, 1.0, v118
	v_add_f32_e32 v119, 1.0, v119
	v_add_f32_e32 v126, 1.0, v126
	v_rcp_f32_e32 v118, v118
	s_waitcnt lgkmcnt(0)
	v_add_f32_e32 v130, v130, v131
	ds_bpermute_b32 v131, v217, v130
	v_add_f32_e32 v127, 1.0, v127
	v_rcp_f32_e32 v119, v119
	v_rcp_f32_e32 v126, v126
	v_rcp_f32_e32 v127, v127
	s_waitcnt lgkmcnt(0)
	v_add_f32_e32 v130, v130, v131
	v_fmamk_f32 v130, v130, 0x3a800000, v132
	v_rsq_f32_e32 v208, v130
	v_mov_b32_e32 v130, v143
	v_mov_b32_e32 v131, v144
	v_mov_b32_e32 v143, v145
	v_add_f32_e32 v130, v130, v142
	v_add_f32_e32 v131, v131, v143
	v_mul_f32_e32 v120, v120, v214
	v_mul_f32_e32 v121, v121, v214
	v_add_f32_e32 v130, v130, v131
	ds_bpermute_b32 v131, v216, v130
	v_mul_f32_e32 v128, v128, v214
	v_mul_f32_e32 v129, v129, v214
	v_mul_f32_e32 v120, 0xbfb8aa3b, v120
	v_mul_f32_e32 v121, 0xbfb8aa3b, v121
	v_mul_f32_e32 v114, v114, v214
	v_mul_f32_e32 v115, v115, v214
	s_waitcnt lgkmcnt(0)
	v_add_f32_e32 v130, v130, v131
	ds_bpermute_b32 v131, v217, v130
	v_exp_f32_e32 v120, v120
	v_exp_f32_e32 v121, v121
	v_mul_f32_e32 v122, v122, v214
	v_mul_f32_e32 v123, v123, v214
	v_mul_f32_e32 v114, 0xbfb8aa3b, v114
	s_waitcnt lgkmcnt(0)
	v_add_f32_e32 v130, v130, v131
	v_fmamk_f32 v130, v130, 0x3a800000, v132
	v_rsq_f32_e32 v202, v130
	v_mov_b32_e32 v130, v147
	v_mov_b32_e32 v131, v148
	v_mov_b32_e32 v147, v149
	v_add_f32_e32 v130, v130, v146
	v_add_f32_e32 v131, v131, v147
	v_mul_f32_e32 v115, 0xbfb8aa3b, v115
	v_add_f32_e32 v130, v130, v131
	ds_bpermute_b32 v131, v216, v130
	v_mul_f32_e32 v122, 0xbfb8aa3b, v122
	v_exp_f32_e32 v114, v114
	v_mul_f32_e32 v123, 0xbfb8aa3b, v123
	v_exp_f32_e32 v115, v115
	s_waitcnt lgkmcnt(0)
	v_add_f32_e32 v130, v130, v131
	ds_bpermute_b32 v131, v217, v130
	v_exp_f32_e32 v122, v122
	v_exp_f32_e32 v123, v123
	v_add_f32_e32 v120, 1.0, v120
	v_add_f32_e32 v121, 1.0, v121
	s_waitcnt lgkmcnt(0)
	v_add_f32_e32 v130, v130, v131
	v_fmamk_f32 v130, v130, 0x3a800000, v132
	v_rsq_f32_e32 v196, v130
	v_mov_b32_e32 v130, v151
	v_mov_b32_e32 v131, v152
	v_mov_b32_e32 v151, v153
	v_add_f32_e32 v130, v130, v150
	v_add_f32_e32 v131, v131, v151
	v_rcp_f32_e32 v120, v120
	v_add_f32_e32 v130, v130, v131
	ds_bpermute_b32 v131, v216, v130
	v_rcp_f32_e32 v121, v121
	v_add_f32_e32 v114, 1.0, v114
	v_add_f32_e32 v115, 1.0, v115
	v_add_f32_e32 v122, 1.0, v122
	s_waitcnt lgkmcnt(0)
;     __device__ __forceinline__ void operator()(const f32x4 (&acc)[2][2][4][2], const Unit& u, int wr, int wc, int fr, int fq) const {
;     ...
;                     for (int m = 0; m < 4; ++m) { const size_t off = (size_t)(row0 + ai * HALF + m * 16) * DM + u.pn * 128 + wc * 32 + 8 * fq; yall[ai][m][0] = *(const u32x4*)(Y1 + off); yall[ai][m][1] = *(const u32x4*)(Y2 + off); }
;                 }
;                 if (mode == EP_RESID) {
; #pragma unroll
;                     for (int m = 0; m < 4; ++m)
; #pragma unroll
;                         for (int bj = 0; bj < 2; ++bj) yall[ai][m][bj] = *(const u32x4*)(xb + (size_t)(row0 + ai * HALF + m * 16) * DM + u.pn * BM + bj * HALF + wc * 32 + 8 * fq);
;                 }
;             }
;             f32x4 cst[4][4];
;             if (rope0 || rope1) {
; #pragma unroll
;                 for (int m = mb; m < mb + 2; ++m) { const float* c = cs + (size_t)(row0 + ai * HALF + m * 16) * 32 + 8 * (fq & 1);
;                     cst[m][0] = *(const f32x4*)c; cst[m][1] = *(const f32x4*)(c + 4); cst[m][2] = *(const f32x4*)(c + 16); cst[m][3] = *(const f32x4*)(c + 20); }
;             }
; #pragma unroll
;             for (int m = mb; m < mb + 2; ++m) {
;                 const int row = row0 + ai * HALF + m * 16;
;                 const float rs1 = rsc[ai][m];
;                 if (mode == EP_GATE) {
;                     const size_t off = (size_t)row * DM + u.pn * 128 + wc * 32 + 8 * fq;
;                     const f32x4 a0 = acc[ai][0][m][0] * rs1, a1 = acc[ai][0][m][1] * rs1, b0 = acc[ai][1][m][0] * rs1, b1 = acc[ai][1][m][1] * rs1;
;                     const u32x4 y1 = yall[ai][m][0], y2 = yall[ai][m][1];
;                     f32x4 r0, r1;
;                     r0[0] = sigmoidf_(a0[0]) * bf_lo(y1.x) + sigmoidf_(b0[0]) * bf_lo(y2.x); r0[1] = sigmoidf_(a0[1]) * bf_hi(y1.x) + sigmoidf_(b0[1]) * bf_hi(y2.x);
;                     r0[2] = sigmoidf_(a0[2]) * bf_lo(y1.y) + sigmoidf_(b0[2]) * bf_lo(y2.y); r0[3] = sigmoidf_(a0[3]) * bf_hi(y1.y) + sigmoidf_(b0[3]) * bf_hi(y2.y);
;                     r1[0] = sigmoidf_(a1[0]) * bf_lo(y1.z) + sigmoidf_(b1[0]) * bf_lo(y2.z); r1[1] = sigmoidf_(a1[1]) * bf_hi(y1.z) + sigmoidf_(b1[1]) * bf_hi(y2.z);
;                     r1[2] = sigmoidf_(a1[2]) * bf_lo(y1.w) + sigmoidf_(b1[2]) * bf_lo(y2.w); r1[3] = sigmoidf_(a1[3]) * bf_hi(y1.w) + sigmoidf_(b1[3]) * bf_hi(y2.w);
	v_add_f32_e32 v130, v130, v131
	ds_bpermute_b32 v131, v217, v130
	v_rcp_f32_e32 v114, v114
	v_add_f32_e32 v123, 1.0, v123
	v_rcp_f32_e32 v115, v115
	v_rcp_f32_e32 v122, v122
	s_waitcnt lgkmcnt(0)
	v_add_f32_e32 v130, v130, v131
	v_fmamk_f32 v130, v130, 0x3a800000, v132
	v_rsq_f32_e32 v190, v130
	v_mov_b32_e32 v130, v155
	v_mov_b32_e32 v131, v156
	v_mov_b32_e32 v155, v157
	v_add_f32_e32 v130, v130, v154
	v_add_f32_e32 v131, v131, v155
	v_rcp_f32_e32 v123, v123
	v_add_f32_e32 v130, v130, v131
	ds_bpermute_b32 v131, v216, v130
	v_mul_f32_e32 v116, v116, v214
	v_mul_f32_e32 v117, v117, v214
	v_mul_f32_e32 v124, v124, v214
	v_mul_f32_e32 v125, v125, v214
	v_mul_f32_e32 v117, 0xbfb8aa3b, v117
	v_exp_f32_e32 v117, v117
	s_waitcnt lgkmcnt(0)
	v_add_f32_e32 v130, v130, v131
	ds_bpermute_b32 v131, v217, v130
	v_mul_f32_e32 v102, v102, v212
	v_mul_f32_e32 v103, v103, v212
	v_add_f32_e32 v117, 1.0, v117
	v_rcp_f32_e32 v117, v117
	v_mul_f32_e32 v110, v110, v212
	v_mul_f32_e32 v111, v111, v212
	s_waitcnt lgkmcnt(0)
	v_add_f32_e32 v130, v130, v131
	v_fmamk_f32 v130, v130, 0x3a800000, v132
	v_rsq_f32_e32 v186, v130
	v_mov_b32_e32 v130, v159
	v_mov_b32_e32 v131, v160
	v_mov_b32_e32 v159, v161
	v_add_f32_e32 v130, v130, v158
	v_add_f32_e32 v131, v131, v159
	v_mul_f32_e32 v102, 0xbfb8aa3b, v102
	v_add_f32_e32 v130, v130, v131
	ds_bpermute_b32 v131, v216, v130
	v_mul_f32_e32 v103, 0xbfb8aa3b, v103
	v_mul_f32_e32 v110, 0xbfb8aa3b, v110
	v_exp_f32_e32 v102, v102
	v_mul_f32_e32 v111, 0xbfb8aa3b, v111
	s_waitcnt lgkmcnt(0)
	v_add_f32_e32 v130, v130, v131
	ds_bpermute_b32 v131, v217, v130
	v_exp_f32_e32 v103, v103
	v_exp_f32_e32 v110, v110
	v_exp_f32_e32 v111, v111
	v_add_f32_e32 v102, 1.0, v102
	s_waitcnt lgkmcnt(0)
	v_add_f32_e32 v130, v130, v131
	v_fmamk_f32 v130, v130, 0x3a800000, v132
	v_rsq_f32_e32 v180, v130
	v_lshlrev_b64 v[130:131], 10, v[210:211]
	v_lshl_add_u64 v[130:131], v[130:131], 0, v[200:201]
	v_lshlrev_b64 v[130:131], 1, v[130:131]
	v_lshl_add_u64 v[132:133], s[38:39], 0, v[130:131]
	v_lshl_add_u64 v[130:131], s[42:43], 0, v[130:131]
	global_load_dwordx4 v[154:157], v[132:133], off
	global_load_dwordx4 v[158:161], v[130:131], off
	v_lshlrev_b64 v[130:131], 10, v[206:207]
	v_lshl_add_u64 v[130:131], v[130:131], 0, v[200:201]
	v_lshlrev_b64 v[130:131], 1, v[130:131]
	v_lshl_add_u64 v[132:133], s[38:39], 0, v[130:131]
	v_lshl_add_u64 v[130:131], s[42:43], 0, v[130:131]
	global_load_dwordx4 v[146:149], v[132:133], off
	global_load_dwordx4 v[150:153], v[130:131], off
	v_lshlrev_b64 v[130:131], 10, v[204:205]
	v_lshl_add_u64 v[130:131], v[130:131], 0, v[200:201]
	v_lshlrev_b64 v[130:131], 1, v[130:131]
	v_lshl_add_u64 v[132:133], s[38:39], 0, v[130:131]
	v_lshl_add_u64 v[130:131], s[42:43], 0, v[130:131]
	global_load_dwordx4 v[138:141], v[132:133], off
	global_load_dwordx4 v[142:145], v[130:131], off
	v_lshlrev_b64 v[130:131], 10, v[198:199]
	v_lshl_add_u64 v[130:131], v[130:131], 0, v[200:201]
	v_lshlrev_b64 v[134:135], 1, v[130:131]
	v_lshl_add_u64 v[130:131], s[38:39], 0, v[134:135]
	v_lshl_add_u64 v[134:135], s[42:43], 0, v[134:135]
	global_load_dwordx4 v[130:133], v[130:131], off
	v_add_f32_e32 v103, 1.0, v103
	global_load_dwordx4 v[134:137], v[134:135], off
	v_add_f32_e32 v110, 1.0, v110
	v_rcp_f32_e32 v102, v102
	v_add_f32_e32 v111, 1.0, v111
	v_rcp_f32_e32 v103, v103
	v_rcp_f32_e32 v110, v110
	v_rcp_f32_e32 v111, v111
	v_mul_f32_e32 v104, v104, v212
	v_mul_f32_e32 v105, v105, v212
	v_mul_f32_e32 v112, v112, v212
	v_mul_f32_e32 v113, v113, v212
	v_mul_f32_e32 v104, 0xbfb8aa3b, v104
	v_mul_f32_e32 v105, 0xbfb8aa3b, v105
	v_mul_f32_e32 v98, v98, v212
	v_mul_f32_e32 v99, v99, v212
	v_exp_f32_e32 v104, v104
	v_exp_f32_e32 v105, v105
	v_mul_f32_e32 v106, v106, v212
	v_mul_f32_e32 v107, v107, v212
	v_mul_f32_e32 v98, 0xbfb8aa3b, v98
	v_mul_f32_e32 v99, 0xbfb8aa3b, v99
	v_mul_f32_e32 v106, 0xbfb8aa3b, v106
	v_exp_f32_e32 v98, v98
	v_mul_f32_e32 v107, 0xbfb8aa3b, v107
	v_exp_f32_e32 v99, v99
	v_exp_f32_e32 v106, v106
	v_exp_f32_e32 v107, v107
	v_add_f32_e32 v104, 1.0, v104
	v_add_f32_e32 v105, 1.0, v105
	v_rcp_f32_e32 v104, v104
	v_rcp_f32_e32 v105, v105
	v_add_f32_e32 v98, 1.0, v98
	v_add_f32_e32 v99, 1.0, v99
	v_add_f32_e32 v106, 1.0, v106
	v_rcp_f32_e32 v98, v98
	v_add_f32_e32 v107, 1.0, v107
	v_rcp_f32_e32 v99, v99
	v_rcp_f32_e32 v106, v106
	v_rcp_f32_e32 v107, v107
	v_mul_f32_e32 v100, v100, v212
	v_mul_f32_e32 v101, v101, v212
	v_mul_f32_e32 v108, v108, v212
	v_mul_f32_e32 v109, v109, v212
	v_mul_f32_e32 v101, 0xbfb8aa3b, v101
	v_exp_f32_e32 v101, v101
	v_mul_f32_e32 v86, v86, v208
	v_mul_f32_e32 v87, v87, v208
	v_mul_f32_e32 v94, v94, v208
	v_mul_f32_e32 v95, v95, v208
	v_mul_f32_e32 v86, 0xbfb8aa3b, v86
	v_add_f32_e32 v101, 1.0, v101
	v_rcp_f32_e32 v101, v101
	v_mul_f32_e32 v87, 0xbfb8aa3b, v87
	v_mul_f32_e32 v94, 0xbfb8aa3b, v94
	v_exp_f32_e32 v86, v86
	v_mul_f32_e32 v95, 0xbfb8aa3b, v95
	v_exp_f32_e32 v87, v87
	v_exp_f32_e32 v94, v94
	v_exp_f32_e32 v95, v95
	v_add_f32_e32 v86, 1.0, v86
	v_add_f32_e32 v87, 1.0, v87
	v_add_f32_e32 v94, 1.0, v94
	v_rcp_f32_e32 v86, v86
	v_add_f32_e32 v95, 1.0, v95
	v_rcp_f32_e32 v87, v87
	s_waitcnt vmcnt(7)
	v_lshlrev_b32_e32 v192, 16, v154
	s_waitcnt vmcnt(6)
; __device__ __forceinline__ float sigmoidf_(float x) { return __builtin_amdgcn_rcpf(1.0f + __builtin_amdgcn_exp2f(-1.4426950408889634f * x)); }
;     __device__ __forceinline__ void operator()(const f32x4 (&acc)[2][2][4][2], const Unit& u, int wr, int wc, int fr, int fq) const {
;     ...
;                 if (mode == EP_GATE) {
;                     const size_t off = (size_t)row * DM + u.pn * 128 + wc * 32 + 8 * fq;
;                     const f32x4 a0 = acc[ai][0][m][0] * rs1, a1 = acc[ai][0][m][1] * rs1, b0 = acc[ai][1][m][0] * rs1, b1 = acc[ai][1][m][1] * rs1;
;                     const u32x4 y1 = yall[ai][m][0], y2 = yall[ai][m][1];
;                     f32x4 r0, r1;
;                     r0[0] = sigmoidf_(a0[0]) * bf_lo(y1.x) + sigmoidf_(b0[0]) * bf_lo(y2.x); r0[1] = sigmoidf_(a0[1]) * bf_hi(y1.x) + sigmoidf_(b0[1]) * bf_hi(y2.x);
;                     r0[2] = sigmoidf_(a0[2]) * bf_lo(y1.y) + sigmoidf_(b0[2]) * bf_lo(y2.y); r0[3] = sigmoidf_(a0[3]) * bf_hi(y1.y) + sigmoidf_(b0[3]) * bf_hi(y2.y);
;                     r1[0] = sigmoidf_(a1[0]) * bf_lo(y1.z) + sigmoidf_(b1[0]) * bf_lo(y2.z); r1[1] = sigmoidf_(a1[1]) * bf_hi(y1.z) + sigmoidf_(b1[1]) * bf_hi(y2.z);
;                     r1[2] = sigmoidf_(a1[2]) * bf_lo(y1.w) + sigmoidf_(b1[2]) * bf_lo(y2.w); r1[3] = sigmoidf_(a1[3]) * bf_hi(y1.w) + sigmoidf_(b1[3]) * bf_hi(y2.w);
;                     store8(O + off, r0, r1);
	v_lshlrev_b32_e32 v222, 16, v158
	v_and_b32_e32 v223, 0xffff0000, v158
	v_and_b32_e32 v193, 0xffff0000, v154
	v_mul_f32_e32 v118, v118, v222
	v_mul_f32_e32 v119, v119, v223
	v_lshlrev_b32_e32 v154, 16, v159
	v_fma_f32 v118, v126, v192, v118
	v_fma_f32 v119, v127, v193, v119
	v_mul_f32_e32 v126, 0xbfb8aa3b, v128
	v_mul_f32_e32 v127, 0xbfb8aa3b, v129
	v_exp_f32_e32 v126, v126
	v_exp_f32_e32 v127, v127
	v_lshlrev_b32_e32 v128, 16, v155
	v_and_b32_e32 v129, 0xffff0000, v155
	v_add_f32_e32 v126, 1.0, v126
	v_add_f32_e32 v127, 1.0, v127
	v_rcp_f32_e32 v126, v126
	v_rcp_f32_e32 v127, v127
	v_and_b32_e32 v155, 0xffff0000, v159
	v_mul_f32_e32 v120, v120, v154
	v_mul_f32_e32 v121, v121, v155
	v_rcp_f32_e32 v94, v94
	v_fma_f32 v120, v126, v128, v120
	v_fma_f32 v121, v127, v129, v121
	v_lshlrev_b32_e32 v128, 16, v160
	v_and_b32_e32 v129, 0xffff0000, v160
	v_lshlrev_b32_e32 v126, 16, v156
	v_and_b32_e32 v127, 0xffff0000, v156
	v_mul_f32_e32 v114, v114, v128
	v_mul_f32_e32 v115, v115, v129
	v_rcp_f32_e32 v95, v95
	v_fma_f32 v122, v122, v126, v114
	v_fma_f32 v123, v123, v127, v115
	v_mul_f32_e32 v115, 0xbfb8aa3b, v116
	v_exp_f32_e32 v115, v115
	v_mul_f32_e32 v114, 0xbfb8aa3b, v124
	v_exp_f32_e32 v114, v114
	v_lshlrev_b32_e32 v126, 16, v161
	v_add_f32_e32 v115, 1.0, v115
	v_rcp_f32_e32 v116, v115
	v_mul_f32_e32 v115, 0xbfb8aa3b, v125
	v_exp_f32_e32 v115, v115
	v_add_f32_e32 v114, 1.0, v114
	v_rcp_f32_e32 v114, v114
	v_and_b32_e32 v127, 0xffff0000, v161
	v_add_f32_e32 v115, 1.0, v115
	v_rcp_f32_e32 v115, v115
	v_lshlrev_b32_e32 v124, 16, v157
	v_and_b32_e32 v125, 0xffff0000, v157
	v_mul_f32_e32 v116, v116, v126
	v_mul_f32_e32 v117, v117, v127
	v_mul_f32_e32 v88, v88, v208
	v_mul_f32_e32 v89, v89, v208
	v_fma_f32 v124, v114, v124, v116
	v_fma_f32 v125, v115, v125, v117
	v_lshlrev_b64 v[114:115], 11, v[210:211]
	v_lshl_add_u64 v[114:115], s[40:41], 0, v[114:115]
	v_lshl_add_u64 v[114:115], v[114:115], 0, s[4:5]
	v_lshl_add_u64 v[114:115], v[114:115], 0, s[12:13]
	v_lshl_add_u64 v[126:127], v[114:115], 0, v[0:1]
	v_cvt_pk_bf16_f32 v114, v118, v119
	v_cvt_pk_bf16_f32 v115, v120, v121
	v_cvt_pk_bf16_f32 v116, v122, v123
	v_cvt_pk_bf16_f32 v117, v124, v125
	global_store_dwordx4 v[126:127], v[114:117], off
	v_mul_f32_e32 v96, v96, v208
	v_mul_f32_e32 v97, v97, v208
	v_mul_f32_e32 v88, 0xbfb8aa3b, v88
	s_waitcnt vmcnt(5)
	v_lshlrev_b32_e32 v116, 16, v150
	v_and_b32_e32 v117, 0xffff0000, v150
	v_lshlrev_b32_e32 v114, 16, v146
	v_and_b32_e32 v115, 0xffff0000, v146
	v_mul_f32_e32 v102, v102, v116
	v_mul_f32_e32 v103, v103, v117
	v_mul_f32_e32 v89, 0xbfb8aa3b, v89
	v_fma_f32 v102, v110, v114, v102
	v_fma_f32 v103, v111, v115, v103
	v_mul_f32_e32 v110, 0xbfb8aa3b, v112
	v_mul_f32_e32 v111, 0xbfb8aa3b, v113
	v_exp_f32_e32 v110, v110
	v_exp_f32_e32 v111, v111
	v_lshlrev_b32_e32 v114, 16, v151
	v_and_b32_e32 v115, 0xffff0000, v151
	v_add_f32_e32 v110, 1.0, v110
	v_add_f32_e32 v111, 1.0, v111
	v_rcp_f32_e32 v110, v110
	v_rcp_f32_e32 v111, v111
	v_lshlrev_b32_e32 v112, 16, v147
	v_and_b32_e32 v113, 0xffff0000, v147
	v_mul_f32_e32 v104, v104, v114
	v_mul_f32_e32 v105, v105, v115
	v_mul_f32_e32 v82, v82, v208
	v_mul_f32_e32 v83, v83, v208
	v_fma_f32 v104, v110, v112, v104
	v_fma_f32 v105, v111, v113, v105
	v_lshlrev_b32_e32 v112, 16, v152
	v_and_b32_e32 v113, 0xffff0000, v152
	v_lshlrev_b32_e32 v110, 16, v148
	v_and_b32_e32 v111, 0xffff0000, v148
	v_mul_f32_e32 v98, v98, v112
	v_mul_f32_e32 v99, v99, v113
	v_exp_f32_e32 v88, v88
	v_fma_f32 v106, v106, v110, v98
	v_fma_f32 v107, v107, v111, v99
	v_mul_f32_e32 v99, 0xbfb8aa3b, v100
	v_exp_f32_e32 v99, v99
	v_mul_f32_e32 v98, 0xbfb8aa3b, v108
	v_exp_f32_e32 v98, v98
	v_lshlrev_b32_e32 v110, 16, v153
	v_add_f32_e32 v99, 1.0, v99
	v_rcp_f32_e32 v100, v99
	v_mul_f32_e32 v99, 0xbfb8aa3b, v109
	v_exp_f32_e32 v99, v99
	v_add_f32_e32 v98, 1.0, v98
	v_rcp_f32_e32 v98, v98
	v_and_b32_e32 v111, 0xffff0000, v153
	v_add_f32_e32 v99, 1.0, v99
	v_rcp_f32_e32 v99, v99
	v_lshlrev_b32_e32 v108, 16, v149
	v_and_b32_e32 v109, 0xffff0000, v149
	v_mul_f32_e32 v100, v100, v110
	v_mul_f32_e32 v101, v101, v111
	v_exp_f32_e32 v89, v89
	v_fma_f32 v108, v98, v108, v100
	v_fma_f32 v109, v99, v109, v101
	v_lshlrev_b64 v[98:99], 11, v[206:207]
	v_lshl_add_u64 v[98:99], s[40:41], 0, v[98:99]
	v_lshl_add_u64 v[98:99], v[98:99], 0, s[4:5]
	v_lshl_add_u64 v[98:99], v[98:99], 0, s[12:13]
	v_lshl_add_u64 v[110:111], v[98:99], 0, v[0:1]
	v_cvt_pk_bf16_f32 v98, v102, v103
	v_cvt_pk_bf16_f32 v99, v104, v105
	v_cvt_pk_bf16_f32 v100, v106, v107
	v_cvt_pk_bf16_f32 v101, v108, v109
	s_waitcnt vmcnt(3)
; __device__ __forceinline__ float sigmoidf_(float x) { return __builtin_amdgcn_rcpf(1.0f + __builtin_amdgcn_exp2f(-1.4426950408889634f * x)); }
;     __device__ __forceinline__ void operator()(const f32x4 (&acc)[2][2][4][2], const Unit& u, int wr, int wc, int fr, int fq) const {
;     ...
;                 if (mode == EP_GATE) {
;                     const size_t off = (size_t)row * DM + u.pn * 128 + wc * 32 + 8 * fq;
;                     const f32x4 a0 = acc[ai][0][m][0] * rs1, a1 = acc[ai][0][m][1] * rs1, b0 = acc[ai][1][m][0] * rs1, b1 = acc[ai][1][m][1] * rs1;
;                     const u32x4 y1 = yall[ai][m][0], y2 = yall[ai][m][1];
;                     f32x4 r0, r1;
;                     r0[0] = sigmoidf_(a0[0]) * bf_lo(y1.x) + sigmoidf_(b0[0]) * bf_lo(y2.x); r0[1] = sigmoidf_(a0[1]) * bf_hi(y1.x) + sigmoidf_(b0[1]) * bf_hi(y2.x);
;                     r0[2] = sigmoidf_(a0[2]) * bf_lo(y1.y) + sigmoidf_(b0[2]) * bf_lo(y2.y); r0[3] = sigmoidf_(a0[3]) * bf_hi(y1.y) + sigmoidf_(b0[3]) * bf_hi(y2.y);
;                     r1[0] = sigmoidf_(a1[0]) * bf_lo(y1.z) + sigmoidf_(b1[0]) * bf_lo(y2.z); r1[1] = sigmoidf_(a1[1]) * bf_hi(y1.z) + sigmoidf_(b1[1]) * bf_hi(y2.z);
;                     r1[2] = sigmoidf_(a1[2]) * bf_lo(y1.w) + sigmoidf_(b1[2]) * bf_lo(y2.w); r1[3] = sigmoidf_(a1[3]) * bf_hi(y1.w) + sigmoidf_(b1[3]) * bf_hi(y2.w);
;                     store8(O + off, r0, r1);
	v_lshlrev_b32_e32 v102, 16, v142
	v_and_b32_e32 v103, 0xffff0000, v142
	global_store_dwordx4 v[110:111], v[98:101], off
	v_mul_f32_e32 v86, v86, v102
	v_mul_f32_e32 v87, v87, v103
	v_mul_f32_e32 v90, v90, v208
	v_mul_f32_e32 v91, v91, v208
	v_lshlrev_b32_e32 v100, 16, v138
	v_and_b32_e32 v101, 0xffff0000, v138
	v_fma_f32 v86, v94, v100, v86
	v_fma_f32 v87, v95, v101, v87
	v_mul_f32_e32 v94, 0xbfb8aa3b, v96
	v_mul_f32_e32 v95, 0xbfb8aa3b, v97
	v_exp_f32_e32 v94, v94
	v_exp_f32_e32 v95, v95
	v_mul_f32_e32 v82, 0xbfb8aa3b, v82
	v_mul_f32_e32 v83, 0xbfb8aa3b, v83
	v_mul_f32_e32 v90, 0xbfb8aa3b, v90
	v_exp_f32_e32 v82, v82
	v_mul_f32_e32 v91, 0xbfb8aa3b, v91
	v_exp_f32_e32 v83, v83
	v_exp_f32_e32 v90, v90
	v_exp_f32_e32 v91, v91
	v_add_f32_e32 v88, 1.0, v88
	v_add_f32_e32 v89, 1.0, v89
	v_add_f32_e32 v94, 1.0, v94
	v_rcp_f32_e32 v88, v88
	v_add_f32_e32 v95, 1.0, v95
	v_rcp_f32_e32 v89, v89
	v_rcp_f32_e32 v94, v94
	v_rcp_f32_e32 v95, v95
	v_add_f32_e32 v82, 1.0, v82
	v_add_f32_e32 v83, 1.0, v83
	v_add_f32_e32 v90, 1.0, v90
	v_rcp_f32_e32 v82, v82
	v_add_f32_e32 v91, 1.0, v91
	v_rcp_f32_e32 v83, v83
	v_lshlrev_b32_e32 v100, 16, v143
	v_and_b32_e32 v101, 0xffff0000, v143
	v_rcp_f32_e32 v90, v90
	v_rcp_f32_e32 v91, v91
	v_lshlrev_b32_e32 v96, 16, v139
	v_and_b32_e32 v97, 0xffff0000, v139
	v_mul_f32_e32 v88, v88, v100
	v_mul_f32_e32 v89, v89, v101
	v_mul_f32_e32 v84, v84, v208
	v_mul_f32_e32 v85, v85, v208
	v_fma_f32 v88, v94, v96, v88
	v_fma_f32 v89, v95, v97, v89
	v_lshlrev_b32_e32 v96, 16, v144
	v_and_b32_e32 v97, 0xffff0000, v144
	v_lshlrev_b32_e32 v94, 16, v140
	v_and_b32_e32 v95, 0xffff0000, v140
	v_mul_f32_e32 v82, v82, v96
	v_mul_f32_e32 v83, v83, v97
	v_mul_f32_e32 v92, v92, v208
	v_mul_f32_e32 v93, v93, v208
	v_fma_f32 v90, v90, v94, v82
	v_fma_f32 v91, v91, v95, v83
	v_mul_f32_e32 v83, 0xbfb8aa3b, v84
	v_exp_f32_e32 v83, v83
	v_mul_f32_e32 v85, 0xbfb8aa3b, v85
	v_mul_f32_e32 v82, 0xbfb8aa3b, v92
	v_exp_f32_e32 v85, v85
	v_add_f32_e32 v83, 1.0, v83
	v_rcp_f32_e32 v84, v83
	v_mul_f32_e32 v83, 0xbfb8aa3b, v93
	v_exp_f32_e32 v82, v82
	v_exp_f32_e32 v83, v83
	v_add_f32_e32 v85, 1.0, v85
	v_mul_f32_e32 v70, v70, v202
	v_mul_f32_e32 v71, v71, v202
	v_add_f32_e32 v82, 1.0, v82
	v_add_f32_e32 v83, 1.0, v83
	v_rcp_f32_e32 v85, v85
	v_mul_f32_e32 v78, v78, v202
	v_mul_f32_e32 v79, v79, v202
	v_mul_f32_e32 v70, 0xbfb8aa3b, v70
	v_mul_f32_e32 v71, 0xbfb8aa3b, v71
	v_rcp_f32_e32 v82, v82
	v_rcp_f32_e32 v83, v83
	v_mul_f32_e32 v78, 0xbfb8aa3b, v78
	v_exp_f32_e32 v70, v70
	v_mul_f32_e32 v79, 0xbfb8aa3b, v79
	v_exp_f32_e32 v71, v71
	v_exp_f32_e32 v78, v78
	v_exp_f32_e32 v79, v79
	v_lshlrev_b32_e32 v94, 16, v145
	v_and_b32_e32 v95, 0xffff0000, v145
	v_lshlrev_b64 v[98:99], 11, v[204:205]
	v_lshlrev_b32_e32 v92, 16, v141
	v_and_b32_e32 v93, 0xffff0000, v141
	v_mul_f32_e32 v84, v84, v94
	v_mul_f32_e32 v85, v85, v95
	v_add_f32_e32 v70, 1.0, v70
	v_fma_f32 v92, v82, v92, v84
	v_fma_f32 v93, v83, v93, v85
	v_lshl_add_u64 v[82:83], s[40:41], 0, v[98:99]
	v_add_f32_e32 v71, 1.0, v71
	v_lshl_add_u64 v[82:83], v[82:83], 0, s[4:5]
	v_add_f32_e32 v78, 1.0, v78
	v_rcp_f32_e32 v70, v70
	v_add_f32_e32 v79, 1.0, v79
	v_rcp_f32_e32 v71, v71
	v_lshl_add_u64 v[82:83], v[82:83], 0, s[12:13]
	v_rcp_f32_e32 v78, v78
	v_rcp_f32_e32 v79, v79
	v_lshl_add_u64 v[94:95], v[82:83], 0, v[0:1]
	v_cvt_pk_bf16_f32 v82, v86, v87
	v_cvt_pk_bf16_f32 v83, v88, v89
	v_cvt_pk_bf16_f32 v84, v90, v91
	v_cvt_pk_bf16_f32 v85, v92, v93
	global_store_dwordx4 v[94:95], v[82:85], off
	v_mul_f32_e32 v72, v72, v202
	v_mul_f32_e32 v73, v73, v202
	v_mul_f32_e32 v80, v80, v202
	v_mul_f32_e32 v81, v81, v202
	s_waitcnt vmcnt(3)
	v_lshlrev_b32_e32 v84, 16, v134
	v_and_b32_e32 v85, 0xffff0000, v134
	v_lshlrev_b32_e32 v82, 16, v130
	v_and_b32_e32 v83, 0xffff0000, v130
	v_mul_f32_e32 v70, v70, v84
	v_mul_f32_e32 v71, v71, v85
	v_mul_f32_e32 v72, 0xbfb8aa3b, v72
	v_mul_f32_e32 v73, 0xbfb8aa3b, v73
	v_mul_f32_e32 v66, v66, v202
	v_mul_f32_e32 v67, v67, v202
	v_fma_f32 v70, v78, v82, v70
	v_fma_f32 v71, v79, v83, v71
	v_mul_f32_e32 v78, 0xbfb8aa3b, v80
	v_exp_f32_e32 v72, v72
	v_mul_f32_e32 v79, 0xbfb8aa3b, v81
	v_exp_f32_e32 v73, v73
	v_mul_f32_e32 v74, v74, v202
	v_mul_f32_e32 v75, v75, v202
	v_exp_f32_e32 v78, v78
	v_exp_f32_e32 v79, v79
	v_mul_f32_e32 v66, 0xbfb8aa3b, v66
	v_mul_f32_e32 v67, 0xbfb8aa3b, v67
	v_mul_f32_e32 v74, 0xbfb8aa3b, v74
	v_exp_f32_e32 v66, v66
	v_mul_f32_e32 v75, 0xbfb8aa3b, v75
	v_exp_f32_e32 v67, v67
	v_exp_f32_e32 v74, v74
	v_exp_f32_e32 v75, v75
	v_add_f32_e32 v72, 1.0, v72
	v_add_f32_e32 v73, 1.0, v73
	v_add_f32_e32 v78, 1.0, v78
	v_rcp_f32_e32 v72, v72
	v_add_f32_e32 v79, 1.0, v79
	v_rcp_f32_e32 v73, v73
	v_rcp_f32_e32 v78, v78
	v_rcp_f32_e32 v79, v79
	v_add_f32_e32 v66, 1.0, v66
	v_add_f32_e32 v67, 1.0, v67
	v_add_f32_e32 v74, 1.0, v74
	v_rcp_f32_e32 v66, v66
	v_add_f32_e32 v75, 1.0, v75
	v_rcp_f32_e32 v67, v67
	v_lshlrev_b32_e32 v82, 16, v135
	v_and_b32_e32 v83, 0xffff0000, v135
	v_rcp_f32_e32 v74, v74
	v_rcp_f32_e32 v75, v75
	v_lshlrev_b32_e32 v80, 16, v131
	v_and_b32_e32 v81, 0xffff0000, v131
	v_mul_f32_e32 v72, v72, v82
	v_mul_f32_e32 v73, v73, v83
	v_mul_f32_e32 v68, v68, v202
	v_mul_f32_e32 v69, v69, v202
	v_fma_f32 v72, v78, v80, v72
	v_fma_f32 v73, v79, v81, v73
	v_lshlrev_b32_e32 v80, 16, v136
	v_and_b32_e32 v81, 0xffff0000, v136
	v_lshlrev_b32_e32 v78, 16, v132
	v_and_b32_e32 v79, 0xffff0000, v132
	v_mul_f32_e32 v66, v66, v80
	v_mul_f32_e32 v67, v67, v81
	v_mul_f32_e32 v76, v76, v202
	v_mul_f32_e32 v77, v77, v202
	v_fma_f32 v74, v74, v78, v66
	v_fma_f32 v75, v75, v79, v67
	v_mul_f32_e32 v67, 0xbfb8aa3b, v68
	v_exp_f32_e32 v67, v67
	v_mul_f32_e32 v69, 0xbfb8aa3b, v69
;     __device__ __forceinline__ void operator()(const f32x4 (&acc)[2][2][4][2], const Unit& u, int wr, int wc, int fr, int fq) const {
;     ...
;                     for (int m = 0; m < 4; ++m) { const size_t off = (size_t)(row0 + ai * HALF + m * 16) * DM + u.pn * 128 + wc * 32 + 8 * fq; yall[ai][m][0] = *(const u32x4*)(Y1 + off); yall[ai][m][1] = *(const u32x4*)(Y2 + off); }
;                 }
;                 if (mode == EP_RESID) {
; #pragma unroll
;                     for (int m = 0; m < 4; ++m)
; #pragma unroll
;                         for (int bj = 0; bj < 2; ++bj) yall[ai][m][bj] = *(const u32x4*)(xb + (size_t)(row0 + ai * HALF + m * 16) * DM + u.pn * BM + bj * HALF + wc * 32 + 8 * fq);
;                 }
;             }
;             f32x4 cst[4][4];
;             if (rope0 || rope1) {
; #pragma unroll
;                 for (int m = mb; m < mb + 2; ++m) { const float* c = cs + (size_t)(row0 + ai * HALF + m * 16) * 32 + 8 * (fq & 1);
;                     cst[m][0] = *(const f32x4*)c; cst[m][1] = *(const f32x4*)(c + 4); cst[m][2] = *(const f32x4*)(c + 16); cst[m][3] = *(const f32x4*)(c + 20); }
;             }
; #pragma unroll
;             for (int m = mb; m < mb + 2; ++m) {
;                 const int row = row0 + ai * HALF + m * 16;
;                 const float rs1 = rsc[ai][m];
;                 if (mode == EP_GATE) {
;                     const size_t off = (size_t)row * DM + u.pn * 128 + wc * 32 + 8 * fq;
;                     const f32x4 a0 = acc[ai][0][m][0] * rs1, a1 = acc[ai][0][m][1] * rs1, b0 = acc[ai][1][m][0] * rs1, b1 = acc[ai][1][m][1] * rs1;
;                     const u32x4 y1 = yall[ai][m][0], y2 = yall[ai][m][1];
;                     f32x4 r0, r1;
;                     r0[0] = sigmoidf_(a0[0]) * bf_lo(y1.x) + sigmoidf_(b0[0]) * bf_lo(y2.x); r0[1] = sigmoidf_(a0[1]) * bf_hi(y1.x) + sigmoidf_(b0[1]) * bf_hi(y2.x);
;                     r0[2] = sigmoidf_(a0[2]) * bf_lo(y1.y) + sigmoidf_(b0[2]) * bf_lo(y2.y); r0[3] = sigmoidf_(a0[3]) * bf_hi(y1.y) + sigmoidf_(b0[3]) * bf_hi(y2.y);
;                     r1[0] = sigmoidf_(a1[0]) * bf_lo(y1.z) + sigmoidf_(b1[0]) * bf_lo(y2.z); r1[1] = sigmoidf_(a1[1]) * bf_hi(y1.z) + sigmoidf_(b1[1]) * bf_hi(y2.z);
;                     r1[2] = sigmoidf_(a1[2]) * bf_lo(y1.w) + sigmoidf_(b1[2]) * bf_lo(y2.w); r1[3] = sigmoidf_(a1[3]) * bf_hi(y1.w) + sigmoidf_(b1[3]) * bf_hi(y2.w);
	v_mul_f32_e32 v66, 0xbfb8aa3b, v76
	v_exp_f32_e32 v69, v69
	v_add_f32_e32 v67, 1.0, v67
	v_rcp_f32_e32 v68, v67
	v_mul_f32_e32 v67, 0xbfb8aa3b, v77
	v_exp_f32_e32 v66, v66
	v_exp_f32_e32 v67, v67
	v_add_f32_e32 v69, 1.0, v69
	v_rcp_f32_e32 v69, v69
	v_add_f32_e32 v66, 1.0, v66
	v_add_f32_e32 v67, 1.0, v67
	v_rcp_f32_e32 v66, v66
	v_rcp_f32_e32 v67, v67
	v_lshlrev_b32_e32 v78, 16, v137
	v_and_b32_e32 v79, 0xffff0000, v137
	v_lshlrev_b32_e32 v76, 16, v133
	v_and_b32_e32 v77, 0xffff0000, v133
	v_mul_f32_e32 v68, v68, v78
	v_mul_f32_e32 v69, v69, v79
	v_mul_f32_e32 v54, v54, v196
	v_mul_f32_e32 v55, v55, v196
	v_fma_f32 v76, v66, v76, v68
	v_fma_f32 v77, v67, v77, v69
	v_lshlrev_b64 v[66:67], 11, v[198:199]
	v_lshl_add_u64 v[66:67], s[40:41], 0, v[66:67]
	v_lshl_add_u64 v[66:67], v[66:67], 0, s[4:5]
	v_lshl_add_u64 v[66:67], v[66:67], 0, s[12:13]
	v_lshl_add_u64 v[78:79], v[66:67], 0, v[0:1]
	v_cvt_pk_bf16_f32 v66, v70, v71
	v_cvt_pk_bf16_f32 v67, v72, v73
	v_cvt_pk_bf16_f32 v68, v74, v75
	v_cvt_pk_bf16_f32 v69, v76, v77
	global_store_dwordx4 v[78:79], v[66:69], off
	v_mul_f32_e32 v62, v62, v196
	v_mul_f32_e32 v63, v63, v196
	v_mul_f32_e32 v54, 0xbfb8aa3b, v54
	v_lshlrev_b64 v[66:67], 10, v[188:189]
	v_lshl_add_u64 v[66:67], v[66:67], 0, v[200:201]
	v_lshlrev_b64 v[66:67], 1, v[66:67]
	v_lshl_add_u64 v[68:69], s[38:39], 0, v[66:67]
	v_lshl_add_u64 v[66:67], s[42:43], 0, v[66:67]
	global_load_dwordx4 v[94:97], v[68:69], off
	global_load_dwordx4 v[90:93], v[66:67], off
	v_lshlrev_b64 v[66:67], 10, v[184:185]
	v_lshl_add_u64 v[66:67], v[66:67], 0, v[200:201]
	v_lshlrev_b64 v[66:67], 1, v[66:67]
	v_lshl_add_u64 v[68:69], s[38:39], 0, v[66:67]
	v_lshl_add_u64 v[66:67], s[42:43], 0, v[66:67]
	global_load_dwordx4 v[82:85], v[68:69], off
	global_load_dwordx4 v[86:89], v[66:67], off
	v_lshlrev_b64 v[66:67], 10, v[182:183]
	v_lshl_add_u64 v[66:67], v[66:67], 0, v[200:201]
	v_lshlrev_b64 v[66:67], 1, v[66:67]
	v_lshl_add_u64 v[68:69], s[38:39], 0, v[66:67]
	v_lshl_add_u64 v[66:67], s[42:43], 0, v[66:67]
	global_load_dwordx4 v[74:77], v[68:69], off
	global_load_dwordx4 v[78:81], v[66:67], off
	v_mul_f32_e32 v55, 0xbfb8aa3b, v55
	v_mul_f32_e32 v62, 0xbfb8aa3b, v62
	v_exp_f32_e32 v54, v54
	v_mul_f32_e32 v63, 0xbfb8aa3b, v63
	v_exp_f32_e32 v55, v55
	v_exp_f32_e32 v62, v62
	v_exp_f32_e32 v63, v63
	v_add_f32_e32 v54, 1.0, v54
	v_add_f32_e32 v55, 1.0, v55
	v_add_f32_e32 v62, 1.0, v62
	v_rcp_f32_e32 v54, v54
	v_add_f32_e32 v63, 1.0, v63
	v_rcp_f32_e32 v55, v55
	v_rcp_f32_e32 v62, v62
	v_rcp_f32_e32 v63, v63
	v_mul_f32_e32 v56, v56, v196
	v_mul_f32_e32 v57, v57, v196
	v_mul_f32_e32 v64, v64, v196
	v_mul_f32_e32 v65, v65, v196
	v_mul_f32_e32 v56, 0xbfb8aa3b, v56
	v_mul_f32_e32 v57, 0xbfb8aa3b, v57
	v_mul_f32_e32 v50, v50, v196
	v_mul_f32_e32 v51, v51, v196
	v_exp_f32_e32 v56, v56
	v_exp_f32_e32 v57, v57
	v_mul_f32_e32 v58, v58, v196
	v_mul_f32_e32 v59, v59, v196
	v_mul_f32_e32 v50, 0xbfb8aa3b, v50
	v_mul_f32_e32 v51, 0xbfb8aa3b, v51
	v_mul_f32_e32 v58, 0xbfb8aa3b, v58
	v_exp_f32_e32 v50, v50
	v_mul_f32_e32 v59, 0xbfb8aa3b, v59
	v_exp_f32_e32 v51, v51
	v_exp_f32_e32 v58, v58
	v_exp_f32_e32 v59, v59
	v_add_f32_e32 v56, 1.0, v56
	v_add_f32_e32 v57, 1.0, v57
	v_rcp_f32_e32 v56, v56
	v_rcp_f32_e32 v57, v57
	v_add_f32_e32 v50, 1.0, v50
	v_add_f32_e32 v51, 1.0, v51
	v_add_f32_e32 v58, 1.0, v58
	v_rcp_f32_e32 v50, v50
	v_add_f32_e32 v59, 1.0, v59
	v_rcp_f32_e32 v51, v51
	v_rcp_f32_e32 v58, v58
	v_rcp_f32_e32 v59, v59
	v_mul_f32_e32 v52, v52, v196
	v_mul_f32_e32 v53, v53, v196
	v_lshlrev_b64 v[66:67], 10, v[178:179]
	v_mul_f32_e32 v60, v60, v196
	v_mul_f32_e32 v61, v61, v196
	v_mul_f32_e32 v53, 0xbfb8aa3b, v53
	v_lshl_add_u64 v[66:67], v[66:67], 0, v[200:201]
	v_exp_f32_e32 v53, v53
	v_lshlrev_b64 v[70:71], 1, v[66:67]
	v_lshl_add_u64 v[66:67], s[38:39], 0, v[70:71]
	v_lshl_add_u64 v[70:71], s[42:43], 0, v[70:71]
	global_load_dwordx4 v[66:69], v[66:67], off
	v_add_f32_e32 v53, 1.0, v53
	global_load_dwordx4 v[70:73], v[70:71], off
	v_rcp_f32_e32 v53, v53
	v_mul_f32_e32 v38, v38, v190
	v_mul_f32_e32 v39, v39, v190
	v_mul_f32_e32 v46, v46, v190
	v_mul_f32_e32 v47, v47, v190
	v_mul_f32_e32 v38, 0xbfb8aa3b, v38
	v_mul_f32_e32 v39, 0xbfb8aa3b, v39
	v_mul_f32_e32 v46, 0xbfb8aa3b, v46
	v_exp_f32_e32 v38, v38
	v_mul_f32_e32 v47, 0xbfb8aa3b, v47
	v_exp_f32_e32 v39, v39
	s_waitcnt vmcnt(7)
	v_lshlrev_b32_e32 v98, 16, v94
	s_waitcnt vmcnt(6)
	v_lshlrev_b32_e32 v100, 16, v90
	v_and_b32_e32 v101, 0xffff0000, v90
	v_and_b32_e32 v99, 0xffff0000, v94
	v_mul_f32_e32 v54, v54, v100
	v_mul_f32_e32 v55, v55, v101
	v_lshlrev_b32_e32 v90, 16, v91
	v_fma_f32 v54, v62, v98, v54
	v_fma_f32 v55, v63, v99, v55
	v_mul_f32_e32 v62, 0xbfb8aa3b, v64
	v_mul_f32_e32 v63, 0xbfb8aa3b, v65
	v_exp_f32_e32 v62, v62
	v_exp_f32_e32 v63, v63
	v_and_b32_e32 v91, 0xffff0000, v91
	v_lshlrev_b32_e32 v64, 16, v95
	v_add_f32_e32 v62, 1.0, v62
	v_add_f32_e32 v63, 1.0, v63
	v_rcp_f32_e32 v62, v62
	v_rcp_f32_e32 v63, v63
	v_and_b32_e32 v65, 0xffff0000, v95
	v_mul_f32_e32 v56, v56, v90
	v_mul_f32_e32 v57, v57, v91
	v_exp_f32_e32 v46, v46
	v_fma_f32 v56, v62, v64, v56
	v_fma_f32 v57, v63, v65, v57
	v_lshlrev_b32_e32 v64, 16, v92
	v_and_b32_e32 v65, 0xffff0000, v92
	v_lshlrev_b32_e32 v62, 16, v96
	v_and_b32_e32 v63, 0xffff0000, v96
	v_mul_f32_e32 v50, v50, v64
	v_mul_f32_e32 v51, v51, v65
	v_exp_f32_e32 v47, v47
	v_fma_f32 v58, v58, v62, v50
	v_fma_f32 v59, v59, v63, v51
	v_mul_f32_e32 v51, 0xbfb8aa3b, v52
	v_exp_f32_e32 v51, v51
	v_mul_f32_e32 v50, 0xbfb8aa3b, v60
	v_exp_f32_e32 v50, v50
	v_lshlrev_b32_e32 v62, 16, v93
	v_add_f32_e32 v51, 1.0, v51
	v_rcp_f32_e32 v52, v51
	v_mul_f32_e32 v51, 0xbfb8aa3b, v61
	v_exp_f32_e32 v51, v51
	v_add_f32_e32 v50, 1.0, v50
	v_rcp_f32_e32 v50, v50
	v_and_b32_e32 v63, 0xffff0000, v93
	v_add_f32_e32 v51, 1.0, v51
	v_rcp_f32_e32 v51, v51
	v_lshlrev_b32_e32 v60, 16, v97
	v_and_b32_e32 v61, 0xffff0000, v97
	v_mul_f32_e32 v52, v52, v62
	v_mul_f32_e32 v53, v53, v63
	v_add_f32_e32 v38, 1.0, v38
	v_fma_f32 v60, v50, v60, v52
	v_fma_f32 v61, v51, v61, v53
	v_lshlrev_b64 v[50:51], 11, v[188:189]
	v_lshl_add_u64 v[50:51], s[40:41], 0, v[50:51]
	v_add_f32_e32 v39, 1.0, v39
	v_lshl_add_u64 v[50:51], v[50:51], 0, s[4:5]
	v_add_f32_e32 v46, 1.0, v46
	v_rcp_f32_e32 v38, v38
	v_add_f32_e32 v47, 1.0, v47
	v_rcp_f32_e32 v39, v39
	v_lshl_add_u64 v[50:51], v[50:51], 0, s[12:13]
	v_rcp_f32_e32 v46, v46
	v_rcp_f32_e32 v47, v47
	v_lshl_add_u64 v[62:63], v[50:51], 0, v[0:1]
	v_cvt_pk_bf16_f32 v50, v54, v55
	v_cvt_pk_bf16_f32 v51, v56, v57
	v_cvt_pk_bf16_f32 v52, v58, v59
	v_cvt_pk_bf16_f32 v53, v60, v61
	global_store_dwordx4 v[62:63], v[50:53], off
	v_mul_f32_e32 v40, v40, v190
	v_mul_f32_e32 v41, v41, v190
	v_mul_f32_e32 v48, v48, v190
	v_mul_f32_e32 v49, v49, v190
	s_waitcnt vmcnt(5)
; __device__ __forceinline__ float sigmoidf_(float x) { return __builtin_amdgcn_rcpf(1.0f + __builtin_amdgcn_exp2f(-1.4426950408889634f * x)); }
;     __device__ __forceinline__ void operator()(const f32x4 (&acc)[2][2][4][2], const Unit& u, int wr, int wc, int fr, int fq) const {
;     ...
;                 if (mode == EP_GATE) {
;                     const size_t off = (size_t)row * DM + u.pn * 128 + wc * 32 + 8 * fq;
;                     const f32x4 a0 = acc[ai][0][m][0] * rs1, a1 = acc[ai][0][m][1] * rs1, b0 = acc[ai][1][m][0] * rs1, b1 = acc[ai][1][m][1] * rs1;
;                     const u32x4 y1 = yall[ai][m][0], y2 = yall[ai][m][1];
;                     f32x4 r0, r1;
;                     r0[0] = sigmoidf_(a0[0]) * bf_lo(y1.x) + sigmoidf_(b0[0]) * bf_lo(y2.x); r0[1] = sigmoidf_(a0[1]) * bf_hi(y1.x) + sigmoidf_(b0[1]) * bf_hi(y2.x);
;                     r0[2] = sigmoidf_(a0[2]) * bf_lo(y1.y) + sigmoidf_(b0[2]) * bf_lo(y2.y); r0[3] = sigmoidf_(a0[3]) * bf_hi(y1.y) + sigmoidf_(b0[3]) * bf_hi(y2.y);
;                     r1[0] = sigmoidf_(a1[0]) * bf_lo(y1.z) + sigmoidf_(b1[0]) * bf_lo(y2.z); r1[1] = sigmoidf_(a1[1]) * bf_hi(y1.z) + sigmoidf_(b1[1]) * bf_hi(y2.z);
;                     r1[2] = sigmoidf_(a1[2]) * bf_lo(y1.w) + sigmoidf_(b1[2]) * bf_lo(y2.w); r1[3] = sigmoidf_(a1[3]) * bf_hi(y1.w) + sigmoidf_(b1[3]) * bf_hi(y2.w);
;                     store8(O + off, r0, r1);
	v_lshlrev_b32_e32 v52, 16, v86
	v_and_b32_e32 v53, 0xffff0000, v86
	v_lshlrev_b32_e32 v50, 16, v82
	v_and_b32_e32 v51, 0xffff0000, v82
	v_mul_f32_e32 v38, v38, v52
	v_mul_f32_e32 v39, v39, v53
	v_mul_f32_e32 v40, 0xbfb8aa3b, v40
	v_mul_f32_e32 v41, 0xbfb8aa3b, v41
	v_mul_f32_e32 v34, v34, v190
	v_mul_f32_e32 v35, v35, v190
	v_fma_f32 v38, v46, v50, v38
	v_fma_f32 v39, v47, v51, v39
	v_mul_f32_e32 v46, 0xbfb8aa3b, v48
	v_exp_f32_e32 v40, v40
	v_mul_f32_e32 v47, 0xbfb8aa3b, v49
	v_exp_f32_e32 v41, v41
	v_mul_f32_e32 v42, v42, v190
	v_mul_f32_e32 v43, v43, v190
	v_exp_f32_e32 v46, v46
	v_exp_f32_e32 v47, v47
	v_mul_f32_e32 v34, 0xbfb8aa3b, v34
	v_mul_f32_e32 v35, 0xbfb8aa3b, v35
	v_mul_f32_e32 v42, 0xbfb8aa3b, v42
	v_exp_f32_e32 v34, v34
	v_mul_f32_e32 v43, 0xbfb8aa3b, v43
	v_exp_f32_e32 v35, v35
	v_exp_f32_e32 v42, v42
	v_exp_f32_e32 v43, v43
	v_add_f32_e32 v40, 1.0, v40
	v_add_f32_e32 v41, 1.0, v41
	v_add_f32_e32 v46, 1.0, v46
	v_rcp_f32_e32 v40, v40
	v_add_f32_e32 v47, 1.0, v47
	v_rcp_f32_e32 v41, v41
	v_rcp_f32_e32 v46, v46
	v_rcp_f32_e32 v47, v47
	v_add_f32_e32 v34, 1.0, v34
	v_add_f32_e32 v35, 1.0, v35
	v_add_f32_e32 v42, 1.0, v42
	v_rcp_f32_e32 v34, v34
	v_add_f32_e32 v43, 1.0, v43
	v_rcp_f32_e32 v35, v35
	v_lshlrev_b32_e32 v50, 16, v87
	v_and_b32_e32 v51, 0xffff0000, v87
	v_rcp_f32_e32 v42, v42
	v_rcp_f32_e32 v43, v43
	v_lshlrev_b32_e32 v48, 16, v83
	v_and_b32_e32 v49, 0xffff0000, v83
	v_mul_f32_e32 v40, v40, v50
	v_mul_f32_e32 v41, v41, v51
	v_mul_f32_e32 v36, v36, v190
	v_mul_f32_e32 v37, v37, v190
	v_fma_f32 v40, v46, v48, v40
	v_fma_f32 v41, v47, v49, v41
	v_lshlrev_b32_e32 v48, 16, v88
	v_and_b32_e32 v49, 0xffff0000, v88
	v_lshlrev_b32_e32 v46, 16, v84
	v_and_b32_e32 v47, 0xffff0000, v84
	v_mul_f32_e32 v34, v34, v48
	v_mul_f32_e32 v35, v35, v49
	v_mul_f32_e32 v44, v44, v190
	v_mul_f32_e32 v45, v45, v190
	v_fma_f32 v42, v42, v46, v34
	v_fma_f32 v43, v43, v47, v35
	v_mul_f32_e32 v35, 0xbfb8aa3b, v36
	v_exp_f32_e32 v35, v35
	v_mul_f32_e32 v37, 0xbfb8aa3b, v37
	v_mul_f32_e32 v34, 0xbfb8aa3b, v44
	v_exp_f32_e32 v37, v37
	v_add_f32_e32 v35, 1.0, v35
	v_rcp_f32_e32 v36, v35
	v_mul_f32_e32 v35, 0xbfb8aa3b, v45
	v_exp_f32_e32 v34, v34
	v_exp_f32_e32 v35, v35
	v_add_f32_e32 v37, 1.0, v37
	v_mul_f32_e32 v22, v22, v186
	v_mul_f32_e32 v23, v23, v186
	v_add_f32_e32 v34, 1.0, v34
	v_add_f32_e32 v35, 1.0, v35
	v_rcp_f32_e32 v37, v37
	v_mul_f32_e32 v30, v30, v186
	v_mul_f32_e32 v31, v31, v186
	v_mul_f32_e32 v22, 0xbfb8aa3b, v22
	v_mul_f32_e32 v23, 0xbfb8aa3b, v23
	v_rcp_f32_e32 v34, v34
	v_rcp_f32_e32 v35, v35
	v_mul_f32_e32 v30, 0xbfb8aa3b, v30
	v_exp_f32_e32 v22, v22
	v_mul_f32_e32 v31, 0xbfb8aa3b, v31
	v_exp_f32_e32 v23, v23
	v_exp_f32_e32 v30, v30
	v_exp_f32_e32 v31, v31
	v_lshlrev_b32_e32 v46, 16, v89
	v_and_b32_e32 v47, 0xffff0000, v89
	v_lshlrev_b32_e32 v44, 16, v85
	v_and_b32_e32 v45, 0xffff0000, v85
	v_mul_f32_e32 v36, v36, v46
	v_mul_f32_e32 v37, v37, v47
	v_add_f32_e32 v22, 1.0, v22
	v_fma_f32 v44, v34, v44, v36
	v_fma_f32 v45, v35, v45, v37
	v_lshlrev_b64 v[34:35], 11, v[184:185]
	v_add_f32_e32 v23, 1.0, v23
	v_lshl_add_u64 v[34:35], s[40:41], 0, v[34:35]
	v_add_f32_e32 v30, 1.0, v30
	v_rcp_f32_e32 v22, v22
	v_add_f32_e32 v31, 1.0, v31
	v_rcp_f32_e32 v23, v23
	v_lshl_add_u64 v[34:35], v[34:35], 0, s[4:5]
	v_rcp_f32_e32 v30, v30
	v_rcp_f32_e32 v31, v31
	v_lshl_add_u64 v[34:35], v[34:35], 0, s[12:13]
	v_lshl_add_u64 v[46:47], v[34:35], 0, v[0:1]
	v_cvt_pk_bf16_f32 v34, v38, v39
	v_cvt_pk_bf16_f32 v35, v40, v41
	v_cvt_pk_bf16_f32 v36, v42, v43
	v_cvt_pk_bf16_f32 v37, v44, v45
	v_mul_f32_e32 v24, v24, v186
	v_mul_f32_e32 v25, v25, v186
	s_waitcnt vmcnt(3)
; __device__ __forceinline__ float sigmoidf_(float x) { return __builtin_amdgcn_rcpf(1.0f + __builtin_amdgcn_exp2f(-1.4426950408889634f * x)); }
; #define PG8_BAR __builtin_amdgcn_s_barrier()
;     __device__ __forceinline__ void operator()(const f32x4 (&acc)[2][2][4][2], const Unit& u, int wr, int wc, int fr, int fq) const {
;     ...
;                 if (mode == EP_GATE) {
;                     const size_t off = (size_t)row * DM + u.pn * 128 + wc * 32 + 8 * fq;
;                     const f32x4 a0 = acc[ai][0][m][0] * rs1, a1 = acc[ai][0][m][1] * rs1, b0 = acc[ai][1][m][0] * rs1, b1 = acc[ai][1][m][1] * rs1;
;                     const u32x4 y1 = yall[ai][m][0], y2 = yall[ai][m][1];
;                     f32x4 r0, r1;
;                     r0[0] = sigmoidf_(a0[0]) * bf_lo(y1.x) + sigmoidf_(b0[0]) * bf_lo(y2.x); r0[1] = sigmoidf_(a0[1]) * bf_hi(y1.x) + sigmoidf_(b0[1]) * bf_hi(y2.x);
;                     r0[2] = sigmoidf_(a0[2]) * bf_lo(y1.y) + sigmoidf_(b0[2]) * bf_lo(y2.y); r0[3] = sigmoidf_(a0[3]) * bf_hi(y1.y) + sigmoidf_(b0[3]) * bf_hi(y2.y);
;                     r1[0] = sigmoidf_(a1[0]) * bf_lo(y1.z) + sigmoidf_(b1[0]) * bf_lo(y2.z); r1[1] = sigmoidf_(a1[1]) * bf_hi(y1.z) + sigmoidf_(b1[1]) * bf_hi(y2.z);
;                     r1[2] = sigmoidf_(a1[2]) * bf_lo(y1.w) + sigmoidf_(b1[2]) * bf_lo(y2.w); r1[3] = sigmoidf_(a1[3]) * bf_hi(y1.w) + sigmoidf_(b1[3]) * bf_hi(y2.w);
;                     store8(O + off, r0, r1);
; template <class Epi, class Sched, bool ALIGN_EPI = false, bool SP2 = false>
; __device__ __forceinline__ void gemm_phase(PG8_LAS unsigned char* lds, const Gemm g, const Sched& S, const Epi& E, int wv) {
;     ...
;                     for (int n = 0; n < 2; ++n) acc[a][b][m][n] = (f32x4){0.f, 0.f, 0.f, 0.f};
;         cur = nxt; cA = nA; cB = nB; ++ui;
;         if constexpr (ALIGN_EPI) { if (wr == 1) PG8_BAR; }
	v_lshlrev_b32_e32 v38, 16, v78
	v_and_b32_e32 v39, 0xffff0000, v78
	global_store_dwordx4 v[46:47], v[34:37], off
	v_mul_f32_e32 v32, v32, v186
	v_mul_f32_e32 v33, v33, v186
	v_mul_f32_e32 v22, v22, v38
	v_mul_f32_e32 v23, v23, v39
	v_lshlrev_b32_e32 v36, 16, v74
	v_and_b32_e32 v37, 0xffff0000, v74
	v_mul_f32_e32 v24, 0xbfb8aa3b, v24
	v_mul_f32_e32 v25, 0xbfb8aa3b, v25
	v_mul_f32_e32 v18, v18, v186
	v_mul_f32_e32 v19, v19, v186
	v_fma_f32 v22, v30, v36, v22
	v_fma_f32 v23, v31, v37, v23
	v_mul_f32_e32 v30, 0xbfb8aa3b, v32
	v_exp_f32_e32 v24, v24
	v_mul_f32_e32 v31, 0xbfb8aa3b, v33
	v_exp_f32_e32 v25, v25
	v_mul_f32_e32 v26, v26, v186
	v_mul_f32_e32 v27, v27, v186
	v_exp_f32_e32 v30, v30
	v_exp_f32_e32 v31, v31
	v_mul_f32_e32 v18, 0xbfb8aa3b, v18
	v_mul_f32_e32 v19, 0xbfb8aa3b, v19
	v_mul_f32_e32 v26, 0xbfb8aa3b, v26
	v_exp_f32_e32 v18, v18
	v_mul_f32_e32 v27, 0xbfb8aa3b, v27
	v_exp_f32_e32 v19, v19
	v_exp_f32_e32 v26, v26
	v_exp_f32_e32 v27, v27
	v_add_f32_e32 v24, 1.0, v24
	v_add_f32_e32 v25, 1.0, v25
	v_add_f32_e32 v30, 1.0, v30
	v_rcp_f32_e32 v24, v24
	v_add_f32_e32 v31, 1.0, v31
	v_rcp_f32_e32 v25, v25
	v_rcp_f32_e32 v30, v30
	v_rcp_f32_e32 v31, v31
	v_add_f32_e32 v18, 1.0, v18
	v_add_f32_e32 v19, 1.0, v19
	v_add_f32_e32 v26, 1.0, v26
	v_rcp_f32_e32 v18, v18
	v_add_f32_e32 v27, 1.0, v27
	v_rcp_f32_e32 v19, v19
	v_lshlrev_b32_e32 v36, 16, v79
	v_and_b32_e32 v37, 0xffff0000, v79
	v_rcp_f32_e32 v26, v26
	v_rcp_f32_e32 v27, v27
	v_lshlrev_b32_e32 v32, 16, v75
	v_and_b32_e32 v33, 0xffff0000, v75
	v_mul_f32_e32 v24, v24, v36
	v_mul_f32_e32 v25, v25, v37
	v_mul_f32_e32 v20, v20, v186
	v_mul_f32_e32 v21, v21, v186
	v_fma_f32 v24, v30, v32, v24
	v_fma_f32 v25, v31, v33, v25
	v_lshlrev_b32_e32 v32, 16, v80
	v_and_b32_e32 v33, 0xffff0000, v80
	v_lshlrev_b32_e32 v30, 16, v76
	v_and_b32_e32 v31, 0xffff0000, v76
	v_mul_f32_e32 v18, v18, v32
	v_mul_f32_e32 v19, v19, v33
	v_mul_f32_e32 v28, v28, v186
	v_mul_f32_e32 v29, v29, v186
	v_fma_f32 v26, v26, v30, v18
	v_fma_f32 v27, v27, v31, v19
	v_mul_f32_e32 v19, 0xbfb8aa3b, v20
	v_exp_f32_e32 v19, v19
	v_mul_f32_e32 v21, 0xbfb8aa3b, v21
	v_mul_f32_e32 v18, 0xbfb8aa3b, v28
	v_exp_f32_e32 v21, v21
	v_add_f32_e32 v19, 1.0, v19
	v_rcp_f32_e32 v20, v19
	v_mul_f32_e32 v19, 0xbfb8aa3b, v29
	v_exp_f32_e32 v18, v18
	v_exp_f32_e32 v19, v19
	v_add_f32_e32 v21, 1.0, v21
	v_mul_f32_e32 v6, v6, v180
	v_mul_f32_e32 v7, v7, v180
	v_add_f32_e32 v18, 1.0, v18
	v_add_f32_e32 v19, 1.0, v19
	v_rcp_f32_e32 v21, v21
	v_mul_f32_e32 v14, v14, v180
	v_mul_f32_e32 v15, v15, v180
	v_mul_f32_e32 v6, 0xbfb8aa3b, v6
	v_mul_f32_e32 v7, 0xbfb8aa3b, v7
	v_rcp_f32_e32 v18, v18
	v_rcp_f32_e32 v19, v19
	v_mul_f32_e32 v14, 0xbfb8aa3b, v14
	v_exp_f32_e32 v6, v6
	v_mul_f32_e32 v15, 0xbfb8aa3b, v15
	v_exp_f32_e32 v7, v7
	v_exp_f32_e32 v14, v14
	v_exp_f32_e32 v15, v15
	v_lshlrev_b32_e32 v30, 16, v81
	v_and_b32_e32 v31, 0xffff0000, v81
	v_lshlrev_b64 v[34:35], 11, v[182:183]
	v_lshlrev_b32_e32 v28, 16, v77
	v_and_b32_e32 v29, 0xffff0000, v77
	v_mul_f32_e32 v20, v20, v30
	v_mul_f32_e32 v21, v21, v31
	v_add_f32_e32 v6, 1.0, v6
	v_fma_f32 v28, v18, v28, v20
	v_fma_f32 v29, v19, v29, v21
	v_lshl_add_u64 v[18:19], s[40:41], 0, v[34:35]
	v_add_f32_e32 v7, 1.0, v7
	v_lshl_add_u64 v[18:19], v[18:19], 0, s[4:5]
	v_add_f32_e32 v14, 1.0, v14
	v_rcp_f32_e32 v6, v6
	v_add_f32_e32 v15, 1.0, v15
	v_rcp_f32_e32 v7, v7
	v_lshl_add_u64 v[18:19], v[18:19], 0, s[12:13]
	v_rcp_f32_e32 v14, v14
	v_rcp_f32_e32 v15, v15
	v_lshl_add_u64 v[30:31], v[18:19], 0, v[0:1]
	v_cvt_pk_bf16_f32 v18, v22, v23
	v_cvt_pk_bf16_f32 v19, v24, v25
	v_cvt_pk_bf16_f32 v20, v26, v27
	v_cvt_pk_bf16_f32 v21, v28, v29
	global_store_dwordx4 v[30:31], v[18:21], off
	v_mul_f32_e32 v8, v8, v180
	v_mul_f32_e32 v9, v9, v180
	v_mul_f32_e32 v16, v16, v180
	v_mul_f32_e32 v17, v17, v180
	s_waitcnt vmcnt(3)
	v_lshlrev_b32_e32 v20, 16, v70
	v_and_b32_e32 v21, 0xffff0000, v70
	v_lshlrev_b32_e32 v18, 16, v66
	v_and_b32_e32 v19, 0xffff0000, v66
	v_mul_f32_e32 v6, v6, v20
	v_mul_f32_e32 v7, v7, v21
	v_mul_f32_e32 v8, 0xbfb8aa3b, v8
	v_mul_f32_e32 v9, 0xbfb8aa3b, v9
	v_mul_f32_e32 v2, v2, v180
	v_mul_f32_e32 v3, v3, v180
	v_fma_f32 v6, v14, v18, v6
	v_fma_f32 v7, v15, v19, v7
	v_mul_f32_e32 v14, 0xbfb8aa3b, v16
	v_exp_f32_e32 v8, v8
	v_mul_f32_e32 v15, 0xbfb8aa3b, v17
	v_exp_f32_e32 v9, v9
	v_mul_f32_e32 v10, v10, v180
	v_mul_f32_e32 v11, v11, v180
	v_exp_f32_e32 v14, v14
	v_exp_f32_e32 v15, v15
	v_mul_f32_e32 v2, 0xbfb8aa3b, v2
	v_mul_f32_e32 v3, 0xbfb8aa3b, v3
	v_mul_f32_e32 v10, 0xbfb8aa3b, v10
	v_exp_f32_e32 v2, v2
	v_mul_f32_e32 v11, 0xbfb8aa3b, v11
	v_exp_f32_e32 v3, v3
	v_exp_f32_e32 v10, v10
	v_exp_f32_e32 v11, v11
	v_add_f32_e32 v8, 1.0, v8
	v_add_f32_e32 v9, 1.0, v9
	v_add_f32_e32 v14, 1.0, v14
	v_rcp_f32_e32 v8, v8
	v_add_f32_e32 v15, 1.0, v15
	v_rcp_f32_e32 v9, v9
	v_rcp_f32_e32 v14, v14
	v_rcp_f32_e32 v15, v15
	v_add_f32_e32 v2, 1.0, v2
	v_add_f32_e32 v3, 1.0, v3
	v_add_f32_e32 v10, 1.0, v10
	v_rcp_f32_e32 v2, v2
	v_add_f32_e32 v11, 1.0, v11
	v_rcp_f32_e32 v3, v3
	v_lshlrev_b32_e32 v18, 16, v71
	v_and_b32_e32 v19, 0xffff0000, v71
	v_rcp_f32_e32 v10, v10
	v_rcp_f32_e32 v11, v11
	v_lshlrev_b32_e32 v16, 16, v67
	v_and_b32_e32 v17, 0xffff0000, v67
	v_mul_f32_e32 v8, v8, v18
	v_mul_f32_e32 v9, v9, v19
	v_mul_f32_e32 v4, v4, v180
	v_mul_f32_e32 v5, v5, v180
	v_fma_f32 v8, v14, v16, v8
	v_fma_f32 v9, v15, v17, v9
	v_lshlrev_b32_e32 v16, 16, v72
	v_and_b32_e32 v17, 0xffff0000, v72
	v_lshlrev_b32_e32 v14, 16, v68
	v_and_b32_e32 v15, 0xffff0000, v68
	v_mul_f32_e32 v2, v2, v16
	v_mul_f32_e32 v3, v3, v17
	v_mul_f32_e32 v12, v12, v180
	v_mul_f32_e32 v13, v13, v180
	v_fma_f32 v10, v10, v14, v2
	v_fma_f32 v11, v11, v15, v3
	v_mul_f32_e32 v3, 0xbfb8aa3b, v4
	v_exp_f32_e32 v3, v3
	v_mul_f32_e32 v5, 0xbfb8aa3b, v5
	v_mul_f32_e32 v2, 0xbfb8aa3b, v12
	v_exp_f32_e32 v5, v5
	v_add_f32_e32 v3, 1.0, v3
	v_rcp_f32_e32 v4, v3
	v_mul_f32_e32 v3, 0xbfb8aa3b, v13
	v_exp_f32_e32 v2, v2
	v_exp_f32_e32 v3, v3
	v_add_f32_e32 v5, 1.0, v5
	v_rcp_f32_e32 v5, v5
	v_add_f32_e32 v2, 1.0, v2
	v_add_f32_e32 v3, 1.0, v3
	v_rcp_f32_e32 v2, v2
	v_rcp_f32_e32 v3, v3
	v_lshlrev_b32_e32 v14, 16, v73
	v_and_b32_e32 v15, 0xffff0000, v73
	v_lshlrev_b32_e32 v12, 16, v69
	v_and_b32_e32 v13, 0xffff0000, v69
	v_mul_f32_e32 v4, v4, v14
	v_mul_f32_e32 v5, v5, v15
	v_mov_b32_e32 v195, 0x3727c5ac
	v_fma_f32 v12, v2, v12, v4
	v_fma_f32 v13, v3, v13, v5
	v_lshlrev_b64 v[2:3], 11, v[178:179]
	v_lshl_add_u64 v[2:3], s[40:41], 0, v[2:3]
	v_lshl_add_u64 v[2:3], v[2:3], 0, s[4:5]
	v_lshl_add_u64 v[2:3], v[2:3], 0, s[12:13]
	v_lshl_add_u64 v[14:15], v[2:3], 0, v[0:1]
	v_cvt_pk_bf16_f32 v2, v6, v7
	v_cvt_pk_bf16_f32 v3, v8, v9
	v_cvt_pk_bf16_f32 v4, v10, v11
	v_cvt_pk_bf16_f32 v5, v12, v13
	s_mov_b64 s[4:5], -1
	global_store_dwordx4 v[14:15], v[2:5], off
	s_cbranch_vccnz .LBB0_1075
	s_andn2_b64 vcc, exec, s[0:1]
	s_cbranch_vccnz .LBB0_1074
	s_barrier
	s_branch .LBB0_1074

;     __device__ __forceinline__ void operator()(const f32x4 (&acc)[2][2][4][2], const Unit& u, int wr, int wc, int fr, int fq) const {
;     ...
;                 if (mode == EP_RESID) {
; #pragma unroll
;                     for (int m = 0; m < 4; ++m)
; #pragma unroll
;                         for (int bj = 0; bj < 2; ++bj) yall[ai][m][bj] = *(const u32x4*)(xb + (size_t)(row0 + ai * HALF + m * 16) * DM + u.pn * BM + bj * HALF + wc * 32 + 8 * fq);
;     ...
;                         const size_t off = (size_t)row * DM + col8;
;                         const u32x4 xi = yall[ai][m][bj];
;                         const f32x4 x0 = (f32x4){bf_lo(xi.x), bf_hi(xi.x), bf_lo(xi.y), bf_hi(xi.y)} + v0, x1 = (f32x4){bf_lo(xi.z), bf_hi(xi.z), bf_lo(xi.w), bf_hi(xi.w)} + v1;
;                         store8(xb + off, x0, x1);
;                         ssacc += (x0[0] * x0[0] + x0[1] * x0[1]) + (x0[2] * x0[2] + x0[3] * x0[3]) + (x1[0] * x1[0] + x1[1] * x1[1]) + (x1[2] * x1[2] + x1[3] * x1[3]);
;                     }
;                 }
;                 if (mode == EP_RESID) {
;                     ssacc += __shfl_xor(ssacc, 16); ssacc += __shfl_xor(ssacc, 32);
;                     if (fq == 0) ss_out[(size_t)row * 16 + u.pn * 4 + wc] = ssacc;
;                 }
.LBB0_1150:
	v_lshl_add_u32 v174, s12, 8, v188
	s_lshl_b32 s28, s54, 8
	s_ashr_i32 s29, s28, 31
	v_ashrrev_i32_e32 v175, 31, v174
	v_lshl_add_u64 v[172:173], s[28:29], 1, v[164:165]
	v_lshlrev_b64 v[192:193], 11, v[174:175]
	v_lshl_add_u64 v[130:131], v[172:173], 0, v[192:193]
	global_load_dwordx4 v[196:199], v[130:131], off
	global_load_dwordx4 v[154:157], v[130:131], off offset:256
	v_or_b32_e32 v184, 16, v174
	v_ashrrev_i32_e32 v185, 31, v184
	v_or_b32_e32 v178, 32, v174
	v_lshlrev_b64 v[186:187], 11, v[184:185]
	v_ashrrev_i32_e32 v179, 31, v178
	v_or_b32_e32 v176, 48, v174
	v_lshl_add_u64 v[130:131], v[172:173], 0, v[186:187]
	v_lshlrev_b64 v[182:183], 11, v[178:179]
	v_ashrrev_i32_e32 v177, 31, v176
	global_load_dwordx4 v[150:153], v[130:131], off
	global_load_dwordx4 v[146:149], v[130:131], off offset:256
	v_lshl_add_u64 v[130:131], v[172:173], 0, v[182:183]
	v_lshlrev_b64 v[180:181], 11, v[176:177]
	global_load_dwordx4 v[142:145], v[130:131], off
	global_load_dwordx4 v[138:141], v[130:131], off offset:256
	v_lshl_add_u64 v[130:131], v[172:173], 0, v[180:181]
	global_load_dwordx4 v[134:137], v[130:131], off
	s_nop 0
	global_load_dwordx4 v[130:133], v[130:131], off offset:256
	v_or_b32_e32 v170, s28, v190
	v_ashrrev_i32_e32 v171, 31, v170
	s_waitcnt vmcnt(0)
	v_lshlrev_b32_e32 v200, 16, v196
	v_and_b32_e32 v201, 0xffff0000, v196
	v_lshlrev_b32_e32 v196, 16, v197
	v_and_b32_e32 v197, 0xffff0000, v197
	v_add_f32_e32 v128, v128, v196
	v_add_f32_e32 v129, v129, v197
	v_lshlrev_b32_e32 v196, 16, v198
	v_and_b32_e32 v197, 0xffff0000, v198
	v_lshlrev_b32_e32 v198, 16, v199
	v_and_b32_e32 v199, 0xffff0000, v199
	v_add_f32_e32 v126, v126, v200
	v_add_f32_e32 v127, v127, v201
	v_add_f32_e32 v198, v124, v198
	v_add_f32_e32 v199, v125, v199
	v_add_f32_e32 v196, v122, v196
	v_add_f32_e32 v197, v123, v197
	v_lshl_add_u64 v[122:123], s[6:7], 0, v[192:193]
	v_lshl_add_u64 v[192:193], v[170:171], 1, v[122:123]
	v_cvt_pk_bf16_f32 v122, v126, v127
	v_cvt_pk_bf16_f32 v123, v128, v129
	v_cvt_pk_bf16_f32 v124, v196, v197
	v_cvt_pk_bf16_f32 v125, v198, v199
	global_store_dwordx4 v[192:193], v[122:125], off
	s_nop 1
	v_mul_f32_e32 v122, v127, v127
	v_mul_f32_e32 v123, v129, v129
	v_fmac_f32_e32 v122, v126, v126
	v_fmac_f32_e32 v123, v128, v128
	v_add_f32_e32 v122, v122, v123
	v_mul_f32_e32 v123, v197, v197
	v_fmac_f32_e32 v123, v196, v196
	v_add_f32_e32 v122, v123, v122
	v_mul_f32_e32 v123, v199, v199
	v_fmac_f32_e32 v123, v198, v198
	v_add_f32_e32 v126, v123, v122
	v_lshlrev_b32_e32 v122, 16, v154
	v_and_b32_e32 v123, 0xffff0000, v154
	v_lshlrev_b32_e32 v124, 16, v155
	v_and_b32_e32 v125, 0xffff0000, v155
	v_add_f32_e32 v120, v120, v124
	v_add_f32_e32 v121, v121, v125
	v_add_f32_e32 v118, v118, v122
	v_add_f32_e32 v119, v119, v123
	v_lshlrev_b32_e32 v122, 16, v156
	v_and_b32_e32 v123, 0xffff0000, v156
	v_lshlrev_b32_e32 v124, 16, v157
	v_and_b32_e32 v125, 0xffff0000, v157
	v_add_f32_e32 v124, v116, v124
	v_add_f32_e32 v125, v117, v125
	v_add_f32_e32 v122, v114, v122
	v_add_f32_e32 v123, v115, v123
	v_cvt_pk_bf16_f32 v114, v118, v119
	v_cvt_pk_bf16_f32 v115, v120, v121
	v_cvt_pk_bf16_f32 v116, v122, v123
	v_cvt_pk_bf16_f32 v117, v124, v125
	global_store_dwordx4 v[192:193], v[114:117], off offset:256
	s_nop 1
	v_mul_f32_e32 v114, v119, v119
	v_mul_f32_e32 v115, v121, v121
	v_fmac_f32_e32 v114, v118, v118
	v_fmac_f32_e32 v115, v120, v120
	v_add_f32_e32 v114, v114, v115
	v_mul_f32_e32 v115, v123, v123
	v_fmac_f32_e32 v115, v122, v122
	v_add_f32_e32 v114, v115, v114
	v_mul_f32_e32 v115, v125, v125
	v_fmac_f32_e32 v115, v124, v124
	v_add_f32_e32 v114, v115, v114
	v_add_f32_e32 v114, v126, v114
	ds_bpermute_b32 v115, v216, v114
	s_waitcnt lgkmcnt(0)
	v_add_f32_e32 v114, v114, v115
	ds_bpermute_b32 v115, v217, v114
	s_and_saveexec_b64 s[16:17], s[0:1]
	s_cbranch_execz .LBB0_1152
	s_waitcnt lgkmcnt(0)
	v_add_f32_e32 v116, v114, v115
	s_lshl_b32 s28, s54, 2
	v_lshlrev_b64 v[114:115], 6, v[174:175]
	s_ashr_i32 s29, s28, 31
	v_lshl_add_u64 v[114:115], s[8:9], 0, v[114:115]
	v_lshl_add_u64 v[114:115], s[28:29], 2, v[114:115]
	s_lshl_b32 s12, s50, 2
	v_lshl_add_u64 v[114:115], v[114:115], 0, s[12:13]
	global_store_dword v[114:115], v116, off
.LBB0_1152:
	s_or_b64 exec, exec, s[16:17]
	v_lshlrev_b32_e32 v114, 16, v150
	s_waitcnt lgkmcnt(0)
	v_and_b32_e32 v115, 0xffff0000, v150
	v_lshlrev_b32_e32 v116, 16, v151
	v_and_b32_e32 v117, 0xffff0000, v151
	v_add_f32_e32 v112, v112, v116
	v_add_f32_e32 v113, v113, v117
	v_add_f32_e32 v110, v110, v114
	v_add_f32_e32 v111, v111, v115
	v_lshlrev_b32_e32 v114, 16, v152
	v_and_b32_e32 v115, 0xffff0000, v152
	v_lshlrev_b32_e32 v116, 16, v153
	v_and_b32_e32 v117, 0xffff0000, v153
	v_add_f32_e32 v116, v108, v116
	v_add_f32_e32 v117, v109, v117
	v_add_f32_e32 v108, v106, v114
	v_add_f32_e32 v109, v107, v115
	v_lshl_add_u64 v[106:107], s[6:7], 0, v[186:187]
	v_lshl_add_u64 v[114:115], v[170:171], 1, v[106:107]
	v_cvt_pk_bf16_f32 v106, v110, v111
	v_mul_f32_e32 v111, v111, v111
	v_fmac_f32_e32 v111, v110, v110
	v_mul_f32_e32 v110, v113, v113
	v_fmac_f32_e32 v110, v112, v112
	v_add_f32_e32 v110, v111, v110
	v_mul_f32_e32 v111, v109, v109
	v_fmac_f32_e32 v111, v108, v108
	v_add_f32_e32 v110, v111, v110
	v_mul_f32_e32 v111, v117, v117
	v_fmac_f32_e32 v111, v116, v116
	v_cvt_pk_bf16_f32 v107, v112, v113
	v_add_f32_e32 v118, v111, v110
	v_lshlrev_b32_e32 v110, 16, v146
	v_and_b32_e32 v111, 0xffff0000, v146
	v_lshlrev_b32_e32 v112, 16, v147
	v_and_b32_e32 v113, 0xffff0000, v147
	v_add_f32_e32 v104, v104, v112
	v_add_f32_e32 v105, v105, v113
	v_add_f32_e32 v102, v102, v110
	v_add_f32_e32 v103, v103, v111
	v_lshlrev_b32_e32 v110, 16, v148
	v_and_b32_e32 v111, 0xffff0000, v148
	v_add_f32_e32 v110, v98, v110
	v_add_f32_e32 v111, v99, v111
	v_mul_f32_e32 v98, v103, v103
	v_mul_f32_e32 v99, v105, v105
	v_fmac_f32_e32 v98, v102, v102
	v_fmac_f32_e32 v99, v104, v104
	v_lshlrev_b32_e32 v112, 16, v149
	v_and_b32_e32 v113, 0xffff0000, v149
	v_add_f32_e32 v98, v98, v99
	v_mul_f32_e32 v99, v111, v111
	v_add_f32_e32 v112, v100, v112
	v_add_f32_e32 v113, v101, v113
	v_fmac_f32_e32 v99, v110, v110
	v_add_f32_e32 v98, v99, v98
	v_mul_f32_e32 v99, v113, v113
	v_fmac_f32_e32 v99, v112, v112
	v_add_f32_e32 v98, v99, v98
	v_add_f32_e32 v98, v118, v98
	ds_bpermute_b32 v99, v216, v98
	v_cvt_pk_bf16_f32 v108, v108, v109
	v_cvt_pk_bf16_f32 v109, v116, v117
	v_cvt_pk_bf16_f32 v100, v102, v103
	v_cvt_pk_bf16_f32 v101, v104, v105
	s_waitcnt lgkmcnt(0)
	v_add_f32_e32 v98, v98, v99
	ds_bpermute_b32 v99, v217, v98
	v_cvt_pk_bf16_f32 v102, v110, v111
	v_cvt_pk_bf16_f32 v103, v112, v113
	global_store_dwordx4 v[114:115], v[106:109], off
	global_store_dwordx4 v[114:115], v[100:103], off offset:256
	s_and_saveexec_b64 s[16:17], s[0:1]
	s_cbranch_execz .LBB0_1154
;     __device__ __forceinline__ void operator()(const f32x4 (&acc)[2][2][4][2], const Unit& u, int wr, int wc, int fr, int fq) const {
;     ...
;                         const size_t off = (size_t)row * DM + col8;
;                         const u32x4 xi = yall[ai][m][bj];
;                         const f32x4 x0 = (f32x4){bf_lo(xi.x), bf_hi(xi.x), bf_lo(xi.y), bf_hi(xi.y)} + v0, x1 = (f32x4){bf_lo(xi.z), bf_hi(xi.z), bf_lo(xi.w), bf_hi(xi.w)} + v1;
;                         store8(xb + off, x0, x1);
;                         ssacc += (x0[0] * x0[0] + x0[1] * x0[1]) + (x0[2] * x0[2] + x0[3] * x0[3]) + (x1[0] * x1[0] + x1[1] * x1[1]) + (x1[2] * x1[2] + x1[3] * x1[3]);
;                     }
;                 }
;                 if (mode == EP_RESID) {
;                     ssacc += __shfl_xor(ssacc, 16); ssacc += __shfl_xor(ssacc, 32);
;                     if (fq == 0) ss_out[(size_t)row * 16 + u.pn * 4 + wc] = ssacc;
;                 }
	s_waitcnt lgkmcnt(0)
	v_add_f32_e32 v100, v98, v99
	s_lshl_b32 s28, s54, 2
	v_lshlrev_b64 v[98:99], 6, v[184:185]
	s_ashr_i32 s29, s28, 31
	v_lshl_add_u64 v[98:99], s[8:9], 0, v[98:99]
	v_lshl_add_u64 v[98:99], s[28:29], 2, v[98:99]
	s_lshl_b32 s12, s50, 2
	v_lshl_add_u64 v[98:99], v[98:99], 0, s[12:13]
	global_store_dword v[98:99], v100, off
.LBB0_1154:
	s_or_b64 exec, exec, s[16:17]
	v_lshlrev_b32_e32 v98, 16, v142
	s_waitcnt lgkmcnt(0)
	v_and_b32_e32 v99, 0xffff0000, v142
	v_lshlrev_b32_e32 v100, 16, v143
	v_and_b32_e32 v101, 0xffff0000, v143
	v_add_f32_e32 v96, v96, v100
	v_add_f32_e32 v97, v97, v101
	v_add_f32_e32 v94, v94, v98
	v_add_f32_e32 v95, v95, v99
	v_lshlrev_b32_e32 v98, 16, v144
	v_and_b32_e32 v99, 0xffff0000, v144
	v_lshlrev_b32_e32 v100, 16, v145
	v_and_b32_e32 v101, 0xffff0000, v145
	v_add_f32_e32 v100, v92, v100
	v_add_f32_e32 v101, v93, v101
	v_add_f32_e32 v92, v90, v98
	v_add_f32_e32 v93, v91, v99
	v_lshl_add_u64 v[90:91], s[6:7], 0, v[182:183]
	v_lshl_add_u64 v[98:99], v[170:171], 1, v[90:91]
	v_cvt_pk_bf16_f32 v90, v94, v95
	v_mul_f32_e32 v95, v95, v95
	v_fmac_f32_e32 v95, v94, v94
	v_mul_f32_e32 v94, v97, v97
	v_fmac_f32_e32 v94, v96, v96
	v_add_f32_e32 v94, v95, v94
	v_mul_f32_e32 v95, v93, v93
	v_fmac_f32_e32 v95, v92, v92
	v_add_f32_e32 v94, v95, v94
	v_mul_f32_e32 v95, v101, v101
	v_fmac_f32_e32 v95, v100, v100
	v_cvt_pk_bf16_f32 v91, v96, v97
	v_add_f32_e32 v102, v95, v94
	v_lshlrev_b32_e32 v94, 16, v138
	v_and_b32_e32 v95, 0xffff0000, v138
	v_lshlrev_b32_e32 v96, 16, v139
	v_and_b32_e32 v97, 0xffff0000, v139
	v_add_f32_e32 v88, v88, v96
	v_add_f32_e32 v89, v89, v97
	v_add_f32_e32 v86, v86, v94
	v_add_f32_e32 v87, v87, v95
	v_lshlrev_b32_e32 v94, 16, v140
	v_and_b32_e32 v95, 0xffff0000, v140
	v_add_f32_e32 v94, v82, v94
	v_add_f32_e32 v95, v83, v95
	v_mul_f32_e32 v82, v87, v87
	v_mul_f32_e32 v83, v89, v89
	v_fmac_f32_e32 v82, v86, v86
	v_fmac_f32_e32 v83, v88, v88
	v_lshlrev_b32_e32 v96, 16, v141
	v_and_b32_e32 v97, 0xffff0000, v141
	v_add_f32_e32 v82, v82, v83
	v_mul_f32_e32 v83, v95, v95
	v_add_f32_e32 v96, v84, v96
	v_add_f32_e32 v97, v85, v97
	v_fmac_f32_e32 v83, v94, v94
	v_add_f32_e32 v82, v83, v82
	v_mul_f32_e32 v83, v97, v97
	v_fmac_f32_e32 v83, v96, v96
	v_add_f32_e32 v82, v83, v82
	v_add_f32_e32 v82, v102, v82
	ds_bpermute_b32 v83, v216, v82
	v_cvt_pk_bf16_f32 v92, v92, v93
	v_cvt_pk_bf16_f32 v93, v100, v101
	v_cvt_pk_bf16_f32 v84, v86, v87
	v_cvt_pk_bf16_f32 v85, v88, v89
	s_waitcnt lgkmcnt(0)
	v_add_f32_e32 v82, v82, v83
	ds_bpermute_b32 v83, v217, v82
	v_cvt_pk_bf16_f32 v86, v94, v95
	v_cvt_pk_bf16_f32 v87, v96, v97
	global_store_dwordx4 v[98:99], v[90:93], off
	global_store_dwordx4 v[98:99], v[84:87], off offset:256
	s_and_saveexec_b64 s[16:17], s[0:1]
	s_cbranch_execz .LBB0_1156
	s_waitcnt lgkmcnt(0)
	v_add_f32_e32 v84, v82, v83
	s_lshl_b32 s28, s54, 2
	v_lshlrev_b64 v[82:83], 6, v[178:179]
	s_ashr_i32 s29, s28, 31
	v_lshl_add_u64 v[82:83], s[8:9], 0, v[82:83]
	v_lshl_add_u64 v[82:83], s[28:29], 2, v[82:83]
	s_lshl_b32 s12, s50, 2
	v_lshl_add_u64 v[82:83], v[82:83], 0, s[12:13]
	global_store_dword v[82:83], v84, off
.LBB0_1156:
	s_or_b64 exec, exec, s[16:17]
	v_lshlrev_b32_e32 v82, 16, v134
	s_waitcnt lgkmcnt(0)
	v_and_b32_e32 v83, 0xffff0000, v134
	v_lshlrev_b32_e32 v84, 16, v135
	v_and_b32_e32 v85, 0xffff0000, v135
	v_add_f32_e32 v80, v80, v84
	v_add_f32_e32 v81, v81, v85
	v_add_f32_e32 v78, v78, v82
	v_add_f32_e32 v79, v79, v83
	v_lshlrev_b32_e32 v82, 16, v136
	v_and_b32_e32 v83, 0xffff0000, v136
	v_lshlrev_b32_e32 v84, 16, v137
	v_and_b32_e32 v85, 0xffff0000, v137
	v_add_f32_e32 v84, v76, v84
	v_add_f32_e32 v85, v77, v85
	v_add_f32_e32 v76, v74, v82
	v_add_f32_e32 v77, v75, v83
	v_lshl_add_u64 v[74:75], s[6:7], 0, v[180:181]
	v_lshl_add_u64 v[82:83], v[170:171], 1, v[74:75]
	v_cvt_pk_bf16_f32 v74, v78, v79
	v_mul_f32_e32 v79, v79, v79
	v_fmac_f32_e32 v79, v78, v78
	v_mul_f32_e32 v78, v81, v81
	v_fmac_f32_e32 v78, v80, v80
	v_add_f32_e32 v78, v79, v78
	v_mul_f32_e32 v79, v77, v77
	v_fmac_f32_e32 v79, v76, v76
	v_add_f32_e32 v78, v79, v78
	v_mul_f32_e32 v79, v85, v85
	v_fmac_f32_e32 v79, v84, v84
	v_cvt_pk_bf16_f32 v75, v80, v81
	v_add_f32_e32 v86, v79, v78
	v_lshlrev_b32_e32 v78, 16, v130
	v_and_b32_e32 v79, 0xffff0000, v130
	v_lshlrev_b32_e32 v80, 16, v131
	v_and_b32_e32 v81, 0xffff0000, v131
	v_add_f32_e32 v72, v72, v80
	v_add_f32_e32 v73, v73, v81
	v_add_f32_e32 v70, v70, v78
	v_add_f32_e32 v71, v71, v79
	v_lshlrev_b32_e32 v78, 16, v132
	v_and_b32_e32 v79, 0xffff0000, v132
	v_add_f32_e32 v78, v66, v78
	v_add_f32_e32 v79, v67, v79
	v_mul_f32_e32 v66, v71, v71
	v_mul_f32_e32 v67, v73, v73
	v_fmac_f32_e32 v66, v70, v70
	v_fmac_f32_e32 v67, v72, v72
	v_lshlrev_b32_e32 v80, 16, v133
	v_and_b32_e32 v81, 0xffff0000, v133
	v_add_f32_e32 v66, v66, v67
	v_mul_f32_e32 v67, v79, v79
	v_add_f32_e32 v80, v68, v80
	v_add_f32_e32 v81, v69, v81
	v_fmac_f32_e32 v67, v78, v78
	v_add_f32_e32 v66, v67, v66
	v_mul_f32_e32 v67, v81, v81
	v_fmac_f32_e32 v67, v80, v80
	v_add_f32_e32 v66, v67, v66
	v_add_f32_e32 v66, v86, v66
	ds_bpermute_b32 v67, v216, v66
	v_cvt_pk_bf16_f32 v76, v76, v77
	v_cvt_pk_bf16_f32 v77, v84, v85
	v_cvt_pk_bf16_f32 v68, v70, v71
	v_cvt_pk_bf16_f32 v69, v72, v73
	s_waitcnt lgkmcnt(0)
	v_add_f32_e32 v66, v66, v67
	ds_bpermute_b32 v67, v217, v66
	v_cvt_pk_bf16_f32 v70, v78, v79
	v_cvt_pk_bf16_f32 v71, v80, v81
	global_store_dwordx4 v[82:83], v[74:77], off
	global_store_dwordx4 v[82:83], v[68:71], off offset:256
	s_and_saveexec_b64 s[16:17], s[0:1]
	s_cbranch_execz .LBB0_1158
	s_waitcnt lgkmcnt(0)
	v_add_f32_e32 v68, v66, v67
	s_lshl_b32 s28, s54, 2
	v_lshlrev_b64 v[66:67], 6, v[176:177]
	s_ashr_i32 s29, s28, 31
	v_lshl_add_u64 v[66:67], s[8:9], 0, v[66:67]
	v_lshl_add_u64 v[66:67], s[28:29], 2, v[66:67]
	s_lshl_b32 s12, s50, 2
	v_lshl_add_u64 v[66:67], v[66:67], 0, s[12:13]
	global_store_dword v[66:67], v68, off
;     __device__ __forceinline__ void operator()(const f32x4 (&acc)[2][2][4][2], const Unit& u, int wr, int wc, int fr, int fq) const {
;     ...
;                 if (mode == EP_RESID) {
; #pragma unroll
;                     for (int m = 0; m < 4; ++m)
; #pragma unroll
;                         for (int bj = 0; bj < 2; ++bj) yall[ai][m][bj] = *(const u32x4*)(xb + (size_t)(row0 + ai * HALF + m * 16) * DM + u.pn * BM + bj * HALF + wc * 32 + 8 * fq);
;     ...
;                         const size_t off = (size_t)row * DM + col8;
;                         const u32x4 xi = yall[ai][m][bj];
;                         const f32x4 x0 = (f32x4){bf_lo(xi.x), bf_hi(xi.x), bf_lo(xi.y), bf_hi(xi.y)} + v0, x1 = (f32x4){bf_lo(xi.z), bf_hi(xi.z), bf_lo(xi.w), bf_hi(xi.w)} + v1;
;                         store8(xb + off, x0, x1);
;                         ssacc += (x0[0] * x0[0] + x0[1] * x0[1]) + (x0[2] * x0[2] + x0[3] * x0[3]) + (x1[0] * x1[0] + x1[1] * x1[1]) + (x1[2] * x1[2] + x1[3] * x1[3]);
;                     }
;                 }
;                 if (mode == EP_RESID) {
;                     ssacc += __shfl_xor(ssacc, 16); ssacc += __shfl_xor(ssacc, 32);
;                     if (fq == 0) ss_out[(size_t)row * 16 + u.pn * 4 + wc] = ssacc;
;                 }
.LBB0_1158:
	s_or_b64 exec, exec, s[16:17]
	v_add_u32_e32 v106, 0x80, v174
	v_ashrrev_i32_e32 v107, 31, v106
	v_lshlrev_b64 v[112:113], 11, v[106:107]
	s_waitcnt lgkmcnt(0)
	v_lshl_add_u64 v[66:67], v[172:173], 0, v[112:113]
	global_load_dwordx4 v[108:111], v[66:67], off
	global_load_dwordx4 v[90:93], v[66:67], off offset:256
	v_add_u32_e32 v102, 0x90, v174
	v_ashrrev_i32_e32 v103, 31, v102
	v_add_u32_e32 v96, 0xa0, v174
	v_lshlrev_b64 v[104:105], 11, v[102:103]
	v_ashrrev_i32_e32 v97, 31, v96
	v_add_u32_e32 v94, 0xb0, v174
	v_lshl_add_u64 v[66:67], v[172:173], 0, v[104:105]
	v_lshlrev_b64 v[100:101], 11, v[96:97]
	v_ashrrev_i32_e32 v95, 31, v94
	global_load_dwordx4 v[86:89], v[66:67], off
	global_load_dwordx4 v[82:85], v[66:67], off offset:256
	v_lshl_add_u64 v[66:67], v[172:173], 0, v[100:101]
	v_lshlrev_b64 v[98:99], 11, v[94:95]
	global_load_dwordx4 v[78:81], v[66:67], off
	global_load_dwordx4 v[74:77], v[66:67], off offset:256
	v_lshl_add_u64 v[66:67], v[172:173], 0, v[98:99]
	global_load_dwordx4 v[70:73], v[66:67], off
	s_nop 0
	global_load_dwordx4 v[66:69], v[66:67], off offset:256
	s_waitcnt vmcnt(7)
	v_lshlrev_b32_e32 v114, 16, v108
	v_and_b32_e32 v115, 0xffff0000, v108
	v_lshlrev_b32_e32 v108, 16, v109
	v_and_b32_e32 v109, 0xffff0000, v109
	v_add_f32_e32 v64, v64, v108
	v_add_f32_e32 v65, v65, v109
	v_lshlrev_b32_e32 v108, 16, v110
	v_and_b32_e32 v109, 0xffff0000, v110
	v_lshlrev_b32_e32 v110, 16, v111
	v_and_b32_e32 v111, 0xffff0000, v111
	v_add_f32_e32 v62, v62, v114
	v_add_f32_e32 v63, v63, v115
	v_add_f32_e32 v110, v60, v110
	v_add_f32_e32 v111, v61, v111
	v_add_f32_e32 v108, v58, v108
	v_add_f32_e32 v109, v59, v109
	v_lshl_add_u64 v[58:59], s[6:7], 0, v[112:113]
	v_lshl_add_u64 v[112:113], v[170:171], 1, v[58:59]
	v_cvt_pk_bf16_f32 v58, v62, v63
	v_cvt_pk_bf16_f32 v59, v64, v65
	v_cvt_pk_bf16_f32 v60, v108, v109
	v_cvt_pk_bf16_f32 v61, v110, v111
	global_store_dwordx4 v[112:113], v[58:61], off
	s_nop 1
	v_mul_f32_e32 v58, v63, v63
	v_mul_f32_e32 v59, v65, v65
	v_fmac_f32_e32 v58, v62, v62
	v_fmac_f32_e32 v59, v64, v64
	v_add_f32_e32 v58, v58, v59
	v_mul_f32_e32 v59, v109, v109
	v_fmac_f32_e32 v59, v108, v108
	v_add_f32_e32 v58, v59, v58
	v_mul_f32_e32 v59, v111, v111
	v_fmac_f32_e32 v59, v110, v110
	v_add_f32_e32 v62, v59, v58
	s_waitcnt vmcnt(7)
	v_lshlrev_b32_e32 v58, 16, v90
	v_and_b32_e32 v59, 0xffff0000, v90
	v_lshlrev_b32_e32 v60, 16, v91
	v_and_b32_e32 v61, 0xffff0000, v91
	v_add_f32_e32 v56, v56, v60
	v_add_f32_e32 v57, v57, v61
	v_add_f32_e32 v54, v54, v58
	v_add_f32_e32 v55, v55, v59
	v_lshlrev_b32_e32 v58, 16, v92
	v_and_b32_e32 v59, 0xffff0000, v92
	v_lshlrev_b32_e32 v60, 16, v93
	v_and_b32_e32 v61, 0xffff0000, v93
	v_add_f32_e32 v60, v52, v60
	v_add_f32_e32 v61, v53, v61
	v_add_f32_e32 v58, v50, v58
	v_add_f32_e32 v59, v51, v59
	v_cvt_pk_bf16_f32 v50, v54, v55
	v_cvt_pk_bf16_f32 v51, v56, v57
	v_cvt_pk_bf16_f32 v52, v58, v59
	v_cvt_pk_bf16_f32 v53, v60, v61
	global_store_dwordx4 v[112:113], v[50:53], off offset:256
	s_nop 1
	v_mul_f32_e32 v50, v55, v55
	v_mul_f32_e32 v51, v57, v57
	v_fmac_f32_e32 v50, v54, v54
	v_fmac_f32_e32 v51, v56, v56
	v_add_f32_e32 v50, v50, v51
	v_mul_f32_e32 v51, v59, v59
	v_fmac_f32_e32 v51, v58, v58
	v_add_f32_e32 v50, v51, v50
	v_mul_f32_e32 v51, v61, v61
	v_fmac_f32_e32 v51, v60, v60
	v_add_f32_e32 v50, v51, v50
	v_add_f32_e32 v50, v62, v50
	ds_bpermute_b32 v51, v216, v50
	s_waitcnt lgkmcnt(0)
	v_add_f32_e32 v50, v50, v51
	ds_bpermute_b32 v51, v217, v50
	s_and_saveexec_b64 s[16:17], s[0:1]
	s_cbranch_execz .LBB0_1160
	s_waitcnt lgkmcnt(0)
	v_add_f32_e32 v52, v50, v51
	s_lshl_b32 s28, s54, 2
	v_lshlrev_b64 v[50:51], 6, v[106:107]
	s_ashr_i32 s29, s28, 31
	v_lshl_add_u64 v[50:51], s[8:9], 0, v[50:51]
	v_lshl_add_u64 v[50:51], s[28:29], 2, v[50:51]
	s_lshl_b32 s12, s50, 2
	v_lshl_add_u64 v[50:51], v[50:51], 0, s[12:13]
	global_store_dword v[50:51], v52, off
.LBB0_1160:
	s_or_b64 exec, exec, s[16:17]
	s_waitcnt vmcnt(7)
	v_lshlrev_b32_e32 v50, 16, v86
	s_waitcnt lgkmcnt(0)
	v_and_b32_e32 v51, 0xffff0000, v86
	v_lshlrev_b32_e32 v52, 16, v87
	v_and_b32_e32 v53, 0xffff0000, v87
	v_add_f32_e32 v48, v48, v52
	v_add_f32_e32 v49, v49, v53
	v_add_f32_e32 v46, v46, v50
	v_add_f32_e32 v47, v47, v51
	v_lshlrev_b32_e32 v50, 16, v88
	v_and_b32_e32 v51, 0xffff0000, v88
	v_lshlrev_b32_e32 v52, 16, v89
	v_and_b32_e32 v53, 0xffff0000, v89
	v_add_f32_e32 v52, v44, v52
	v_add_f32_e32 v53, v45, v53
	v_add_f32_e32 v44, v42, v50
	v_add_f32_e32 v45, v43, v51
	v_lshl_add_u64 v[42:43], s[6:7], 0, v[104:105]
	v_lshl_add_u64 v[50:51], v[170:171], 1, v[42:43]
	v_cvt_pk_bf16_f32 v42, v46, v47
	v_mul_f32_e32 v47, v47, v47
	v_fmac_f32_e32 v47, v46, v46
	v_mul_f32_e32 v46, v49, v49
	v_fmac_f32_e32 v46, v48, v48
	v_add_f32_e32 v46, v47, v46
	v_mul_f32_e32 v47, v45, v45
	v_fmac_f32_e32 v47, v44, v44
	v_add_f32_e32 v46, v47, v46
	v_mul_f32_e32 v47, v53, v53
	v_fmac_f32_e32 v47, v52, v52
	v_cvt_pk_bf16_f32 v43, v48, v49
	v_add_f32_e32 v54, v47, v46
	s_waitcnt vmcnt(6)
	v_lshlrev_b32_e32 v46, 16, v82
	v_and_b32_e32 v47, 0xffff0000, v82
	v_lshlrev_b32_e32 v48, 16, v83
	v_and_b32_e32 v49, 0xffff0000, v83
	v_add_f32_e32 v40, v40, v48
	v_add_f32_e32 v41, v41, v49
	v_add_f32_e32 v38, v38, v46
	v_add_f32_e32 v39, v39, v47
	v_lshlrev_b32_e32 v46, 16, v84
	v_and_b32_e32 v47, 0xffff0000, v84
	v_add_f32_e32 v46, v34, v46
	v_add_f32_e32 v47, v35, v47
	v_mul_f32_e32 v34, v39, v39
	v_mul_f32_e32 v35, v41, v41
	v_fmac_f32_e32 v34, v38, v38
	v_fmac_f32_e32 v35, v40, v40
	v_lshlrev_b32_e32 v48, 16, v85
	v_and_b32_e32 v49, 0xffff0000, v85
	v_add_f32_e32 v34, v34, v35
	v_mul_f32_e32 v35, v47, v47
	v_add_f32_e32 v48, v36, v48
	v_add_f32_e32 v49, v37, v49
	v_fmac_f32_e32 v35, v46, v46
	v_add_f32_e32 v34, v35, v34
	v_mul_f32_e32 v35, v49, v49
	v_fmac_f32_e32 v35, v48, v48
	v_add_f32_e32 v34, v35, v34
	v_add_f32_e32 v34, v54, v34
	ds_bpermute_b32 v35, v216, v34
	v_cvt_pk_bf16_f32 v44, v44, v45
	v_cvt_pk_bf16_f32 v45, v52, v53
	v_cvt_pk_bf16_f32 v36, v38, v39
	v_cvt_pk_bf16_f32 v37, v40, v41
	s_waitcnt lgkmcnt(0)
	v_add_f32_e32 v34, v34, v35
	ds_bpermute_b32 v35, v217, v34
	v_cvt_pk_bf16_f32 v38, v46, v47
	v_cvt_pk_bf16_f32 v39, v48, v49
	global_store_dwordx4 v[50:51], v[42:45], off
	global_store_dwordx4 v[50:51], v[36:39], off offset:256
	s_and_saveexec_b64 s[16:17], s[0:1]
	s_cbranch_execz .LBB0_1162
	s_waitcnt lgkmcnt(0)
	v_add_f32_e32 v36, v34, v35
	s_lshl_b32 s28, s54, 2
	v_lshlrev_b64 v[34:35], 6, v[102:103]
	s_ashr_i32 s29, s28, 31
	v_lshl_add_u64 v[34:35], s[8:9], 0, v[34:35]
	v_lshl_add_u64 v[34:35], s[28:29], 2, v[34:35]
	s_lshl_b32 s12, s50, 2
	v_lshl_add_u64 v[34:35], v[34:35], 0, s[12:13]
	global_store_dword v[34:35], v36, off
;     __device__ __forceinline__ void operator()(const f32x4 (&acc)[2][2][4][2], const Unit& u, int wr, int wc, int fr, int fq) const {
;     ...
;                         const size_t off = (size_t)row * DM + col8;
;                         const u32x4 xi = yall[ai][m][bj];
;                         const f32x4 x0 = (f32x4){bf_lo(xi.x), bf_hi(xi.x), bf_lo(xi.y), bf_hi(xi.y)} + v0, x1 = (f32x4){bf_lo(xi.z), bf_hi(xi.z), bf_lo(xi.w), bf_hi(xi.w)} + v1;
;                         store8(xb + off, x0, x1);
;                         ssacc += (x0[0] * x0[0] + x0[1] * x0[1]) + (x0[2] * x0[2] + x0[3] * x0[3]) + (x1[0] * x1[0] + x1[1] * x1[1]) + (x1[2] * x1[2] + x1[3] * x1[3]);
;                     }
;                 }
;                 if (mode == EP_RESID) {
;                     ssacc += __shfl_xor(ssacc, 16); ssacc += __shfl_xor(ssacc, 32);
;                     if (fq == 0) ss_out[(size_t)row * 16 + u.pn * 4 + wc] = ssacc;
;                 }
.LBB0_1162:
	s_or_b64 exec, exec, s[16:17]
	s_waitcnt vmcnt(7)
	v_lshlrev_b32_e32 v34, 16, v78
	s_waitcnt lgkmcnt(0)
	v_and_b32_e32 v35, 0xffff0000, v78
	v_lshlrev_b32_e32 v36, 16, v79
	v_and_b32_e32 v37, 0xffff0000, v79
	v_add_f32_e32 v32, v32, v36
	v_add_f32_e32 v33, v33, v37
	v_add_f32_e32 v30, v30, v34
	v_add_f32_e32 v31, v31, v35
	v_lshlrev_b32_e32 v34, 16, v80
	v_and_b32_e32 v35, 0xffff0000, v80
	v_lshlrev_b32_e32 v36, 16, v81
	v_and_b32_e32 v37, 0xffff0000, v81
	v_add_f32_e32 v36, v28, v36
	v_add_f32_e32 v37, v29, v37
	v_add_f32_e32 v28, v26, v34
	v_add_f32_e32 v29, v27, v35
	v_lshl_add_u64 v[26:27], s[6:7], 0, v[100:101]
	v_lshl_add_u64 v[34:35], v[170:171], 1, v[26:27]
	v_cvt_pk_bf16_f32 v26, v30, v31
	v_mul_f32_e32 v31, v31, v31
	v_fmac_f32_e32 v31, v30, v30
	v_mul_f32_e32 v30, v33, v33
	v_fmac_f32_e32 v30, v32, v32
	v_add_f32_e32 v30, v31, v30
	v_mul_f32_e32 v31, v29, v29
	v_fmac_f32_e32 v31, v28, v28
	v_add_f32_e32 v30, v31, v30
	v_mul_f32_e32 v31, v37, v37
	v_fmac_f32_e32 v31, v36, v36
	v_cvt_pk_bf16_f32 v27, v32, v33
	v_add_f32_e32 v38, v31, v30
	s_waitcnt vmcnt(6)
	v_lshlrev_b32_e32 v30, 16, v74
	v_and_b32_e32 v31, 0xffff0000, v74
	v_lshlrev_b32_e32 v32, 16, v75
	v_and_b32_e32 v33, 0xffff0000, v75
	v_add_f32_e32 v24, v24, v32
	v_add_f32_e32 v25, v25, v33
	v_add_f32_e32 v22, v22, v30
	v_add_f32_e32 v23, v23, v31
	v_lshlrev_b32_e32 v30, 16, v76
	v_and_b32_e32 v31, 0xffff0000, v76
	v_add_f32_e32 v30, v18, v30
	v_add_f32_e32 v31, v19, v31
	v_mul_f32_e32 v18, v23, v23
	v_mul_f32_e32 v19, v25, v25
	v_fmac_f32_e32 v18, v22, v22
	v_fmac_f32_e32 v19, v24, v24
	v_lshlrev_b32_e32 v32, 16, v77
	v_and_b32_e32 v33, 0xffff0000, v77
	v_add_f32_e32 v18, v18, v19
	v_mul_f32_e32 v19, v31, v31
	v_add_f32_e32 v32, v20, v32
	v_add_f32_e32 v33, v21, v33
	v_fmac_f32_e32 v19, v30, v30
	v_add_f32_e32 v18, v19, v18
	v_mul_f32_e32 v19, v33, v33
	v_fmac_f32_e32 v19, v32, v32
	v_add_f32_e32 v18, v19, v18
	v_add_f32_e32 v18, v38, v18
	ds_bpermute_b32 v19, v216, v18
	v_cvt_pk_bf16_f32 v28, v28, v29
	v_cvt_pk_bf16_f32 v29, v36, v37
	v_cvt_pk_bf16_f32 v20, v22, v23
	v_cvt_pk_bf16_f32 v21, v24, v25
	s_waitcnt lgkmcnt(0)
	v_add_f32_e32 v18, v18, v19
	ds_bpermute_b32 v19, v217, v18
	v_cvt_pk_bf16_f32 v22, v30, v31
	v_cvt_pk_bf16_f32 v23, v32, v33
	global_store_dwordx4 v[34:35], v[26:29], off
	global_store_dwordx4 v[34:35], v[20:23], off offset:256
	s_and_saveexec_b64 s[16:17], s[0:1]
	s_cbranch_execz .LBB0_1164
	s_waitcnt lgkmcnt(0)
	v_add_f32_e32 v20, v18, v19
	s_lshl_b32 s28, s54, 2
	v_lshlrev_b64 v[18:19], 6, v[96:97]
	s_ashr_i32 s29, s28, 31
	v_lshl_add_u64 v[18:19], s[8:9], 0, v[18:19]
	v_lshl_add_u64 v[18:19], s[28:29], 2, v[18:19]
	s_lshl_b32 s12, s50, 2
	v_lshl_add_u64 v[18:19], v[18:19], 0, s[12:13]
	global_store_dword v[18:19], v20, off
.LBB0_1164:
	s_or_b64 exec, exec, s[16:17]
	s_waitcnt vmcnt(7)
	v_lshlrev_b32_e32 v18, 16, v70
	s_waitcnt lgkmcnt(0)
	v_and_b32_e32 v19, 0xffff0000, v70
	v_lshlrev_b32_e32 v20, 16, v71
	v_and_b32_e32 v21, 0xffff0000, v71
	v_add_f32_e32 v16, v16, v20
	v_add_f32_e32 v17, v17, v21
	v_add_f32_e32 v14, v14, v18
	v_add_f32_e32 v15, v15, v19
	v_lshlrev_b32_e32 v18, 16, v72
	v_and_b32_e32 v19, 0xffff0000, v72
	v_lshlrev_b32_e32 v20, 16, v73
	v_and_b32_e32 v21, 0xffff0000, v73
	v_add_f32_e32 v20, v12, v20
	v_add_f32_e32 v21, v13, v21
	v_add_f32_e32 v12, v10, v18
	v_add_f32_e32 v13, v11, v19
	v_lshl_add_u64 v[10:11], s[6:7], 0, v[98:99]
	v_lshl_add_u64 v[18:19], v[170:171], 1, v[10:11]
	v_cvt_pk_bf16_f32 v10, v14, v15
	v_mul_f32_e32 v15, v15, v15
	v_fmac_f32_e32 v15, v14, v14
	v_mul_f32_e32 v14, v17, v17
	v_fmac_f32_e32 v14, v16, v16
	v_add_f32_e32 v14, v15, v14
	v_mul_f32_e32 v15, v13, v13
	v_fmac_f32_e32 v15, v12, v12
	v_add_f32_e32 v14, v15, v14
	v_mul_f32_e32 v15, v21, v21
	v_fmac_f32_e32 v15, v20, v20
	v_cvt_pk_bf16_f32 v11, v16, v17
	v_add_f32_e32 v22, v15, v14
	s_waitcnt vmcnt(6)
	v_lshlrev_b32_e32 v14, 16, v66
	v_and_b32_e32 v15, 0xffff0000, v66
	v_lshlrev_b32_e32 v16, 16, v67
	v_and_b32_e32 v17, 0xffff0000, v67
	v_add_f32_e32 v8, v8, v16
	v_add_f32_e32 v9, v9, v17
	v_add_f32_e32 v6, v6, v14
	v_add_f32_e32 v7, v7, v15
	v_lshlrev_b32_e32 v14, 16, v68
	v_and_b32_e32 v15, 0xffff0000, v68
	v_add_f32_e32 v14, v2, v14
	v_add_f32_e32 v15, v3, v15
	v_mul_f32_e32 v2, v7, v7
	v_mul_f32_e32 v3, v9, v9
	v_fmac_f32_e32 v2, v6, v6
	v_fmac_f32_e32 v3, v8, v8
	v_lshlrev_b32_e32 v16, 16, v69
	v_and_b32_e32 v17, 0xffff0000, v69
	v_add_f32_e32 v2, v2, v3
	v_mul_f32_e32 v3, v15, v15
	v_add_f32_e32 v16, v4, v16
	v_add_f32_e32 v17, v5, v17
	v_fmac_f32_e32 v3, v14, v14
	v_add_f32_e32 v2, v3, v2
	v_mul_f32_e32 v3, v17, v17
	v_fmac_f32_e32 v3, v16, v16
	v_add_f32_e32 v2, v3, v2
	v_add_f32_e32 v2, v22, v2
	ds_bpermute_b32 v3, v216, v2
	v_cvt_pk_bf16_f32 v12, v12, v13
	v_cvt_pk_bf16_f32 v13, v20, v21
	v_cvt_pk_bf16_f32 v4, v6, v7
	v_cvt_pk_bf16_f32 v5, v8, v9
	s_waitcnt lgkmcnt(0)
	v_add_f32_e32 v2, v2, v3
	ds_bpermute_b32 v3, v217, v2
	v_cvt_pk_bf16_f32 v6, v14, v15
	v_cvt_pk_bf16_f32 v7, v16, v17
	global_store_dwordx4 v[18:19], v[10:13], off
	global_store_dwordx4 v[18:19], v[4:7], off offset:256
	s_and_saveexec_b64 s[16:17], s[0:1]
	s_cbranch_execz .LBB0_1166
	s_waitcnt lgkmcnt(0)
	v_add_f32_e32 v4, v2, v3
	s_lshl_b32 s28, s54, 2
	v_lshlrev_b64 v[2:3], 6, v[94:95]
	s_ashr_i32 s29, s28, 31
	v_lshl_add_u64 v[2:3], s[8:9], 0, v[2:3]
	v_lshl_add_u64 v[2:3], s[28:29], 2, v[2:3]
	s_lshl_b32 s12, s50, 2
	v_lshl_add_u64 v[2:3], v[2:3], 0, s[12:13]
	global_store_dword v[2:3], v4, off

;     __device__ __forceinline__ void operator()(const f32x4 (&acc)[2][2][4][2], const Unit& u, int wr, int wc, int fr, int fq) const {
;     ...
;                     if (4 * fq < rs_n) part[ai][m] = *(const f32x4*)(rs + (size_t)(row0 + ai * HALF + m * 16) * rs_ld + rs_off + 4 * fq);
;                 }
; #pragma unroll
;             for (int ai = 0; ai < 2; ++ai)
; #pragma unroll
;                 for (int m = 0; m < 4; ++m) {
;                     float t = (part[ai][m][0] + part[ai][m][1]) + (part[ai][m][2] + part[ai][m][3]);
;                     t += __shfl_xor(t, 16); t += __shfl_xor(t, 32);
;                     rsc[ai][m] = __builtin_amdgcn_rsqf(t * rs_inv + EPS);
;     ...
;                     f32x4 v0 = acc[ai][bj][m][0] * rs1, v1 = acc[ai][bj][m][1] * rs1;
;                     if (mode == EP_PLAIN) { store8(O + (size_t)row * ldc + col8, v0, v1); }
;                     else if (mode == EP_RELU2) {
; #pragma unroll
;                         for (int e = 0; e < 4; ++e) { float a = fmaxf(v0[e], 0.f), b = fmaxf(v1[e], 0.f); v0[e] = a * a; v1[e] = b * b; }
;                         store8(O + (size_t)row * ldc + col8, v0, v1);
.LBB0_1234:
	v_lshl_add_u32 v174, s49, 8, v167
	v_ashrrev_i32_e32 v175, 31, v174
	v_lshlrev_b64 v[130:131], 6, v[174:175]
	v_lshl_add_u64 v[130:131], v[148:149], 0, v[130:131]
	global_load_dwordx4 v[178:181], v[130:131], off
	v_or_b32_e32 v168, 16, v174
	v_ashrrev_i32_e32 v169, 31, v168
	v_lshlrev_b64 v[130:131], 6, v[168:169]
	v_lshl_add_u64 v[130:131], v[148:149], 0, v[130:131]
	global_load_dwordx4 v[182:185], v[130:131], off
	v_or_b32_e32 v164, 32, v174
	v_ashrrev_i32_e32 v165, 31, v164
	v_lshlrev_b64 v[130:131], 6, v[164:165]
	v_lshl_add_u64 v[130:131], v[148:149], 0, v[130:131]
	global_load_dwordx4 v[186:189], v[130:131], off
	v_or_b32_e32 v162, 48, v174
	v_ashrrev_i32_e32 v163, 31, v162
	v_lshlrev_b64 v[130:131], 6, v[162:163]
	v_lshl_add_u64 v[130:131], v[148:149], 0, v[130:131]
	global_load_dwordx4 v[190:193], v[130:131], off
	v_add_u32_e32 v160, 0x80, v174
	v_ashrrev_i32_e32 v161, 31, v160
	v_lshlrev_b64 v[130:131], 6, v[160:161]
	v_lshl_add_u64 v[130:131], v[148:149], 0, v[130:131]
	global_load_dwordx4 v[196:199], v[130:131], off
	v_add_u32_e32 v158, 0x90, v174
	v_ashrrev_i32_e32 v159, 31, v158
	v_lshlrev_b64 v[130:131], 6, v[158:159]
	v_add_u32_e32 v156, 0xa0, v174
	v_lshl_add_u64 v[130:131], v[148:149], 0, v[130:131]
	v_ashrrev_i32_e32 v157, 31, v156
	global_load_dwordx4 v[138:141], v[130:131], off
	v_lshlrev_b64 v[130:131], 6, v[156:157]
	v_add_u32_e32 v154, 0xb0, v174
	v_lshl_add_u64 v[130:131], v[148:149], 0, v[130:131]
	v_ashrrev_i32_e32 v155, 31, v154
	global_load_dwordx4 v[134:137], v[130:131], off
	v_lshlrev_b64 v[130:131], 6, v[154:155]
	v_lshl_add_u64 v[130:131], v[148:149], 0, v[130:131]
	global_load_dwordx4 v[130:133], v[130:131], off
	s_mov_b64 s[16:17], -1
	s_andn2_b64 vcc, exec, s[0:1]
	s_waitcnt vmcnt(0)
	v_mov_b32_e32 v200, v179
	v_mov_b32_e32 v201, v180
	v_mov_b32_e32 v179, v181
	v_add_f32_e32 v178, v200, v178
	v_add_f32_e32 v179, v201, v179
	v_mov_b32_e32 v180, v183
	v_add_f32_e32 v166, v178, v179
	ds_bpermute_b32 v170, v216, v166
	v_mov_b32_e32 v181, v184
	v_mov_b32_e32 v183, v185
	v_add_f32_e32 v180, v180, v182
	v_add_f32_e32 v181, v181, v183
	s_waitcnt lgkmcnt(0)
	v_add_f32_e32 v166, v166, v170
	ds_bpermute_b32 v170, v217, v166
	s_waitcnt lgkmcnt(0)
	v_add_f32_e32 v166, v166, v170
	v_fmamk_f32 v166, v166, 0x3a800000, v195
	v_rsq_f32_e32 v178, v166
	v_add_f32_e32 v166, v180, v181
	ds_bpermute_b32 v170, v216, v166
	v_mov_b32_e32 v180, v187
	v_mov_b32_e32 v181, v188
	v_mov_b32_e32 v187, v189
	v_add_f32_e32 v180, v180, v186
	v_add_f32_e32 v181, v181, v187
	s_waitcnt lgkmcnt(0)
	v_add_f32_e32 v166, v166, v170
	ds_bpermute_b32 v170, v217, v166
	s_waitcnt lgkmcnt(0)
	v_add_f32_e32 v166, v166, v170
	v_fmamk_f32 v166, v166, 0x3a800000, v195
	v_rsq_f32_e32 v176, v166
	v_add_f32_e32 v166, v180, v181
	ds_bpermute_b32 v170, v216, v166
	v_mov_b32_e32 v180, v191
	v_mov_b32_e32 v181, v192
	v_mov_b32_e32 v191, v193
	v_add_f32_e32 v180, v180, v190
	v_add_f32_e32 v181, v181, v191
	s_waitcnt lgkmcnt(0)
	v_add_f32_e32 v166, v166, v170
	ds_bpermute_b32 v170, v217, v166
	v_mul_f32_e32 v106, v106, v176
	v_mul_f32_e32 v107, v107, v176
	v_mul_f32_e32 v112, v112, v176
	v_mul_f32_e32 v113, v113, v176
	v_max_f32_e32 v106, 0, v106
	v_max_f32_e32 v107, 0, v107
	s_waitcnt lgkmcnt(0)
	v_add_f32_e32 v166, v166, v170
	v_fmamk_f32 v166, v166, 0x3a800000, v195
	v_rsq_f32_e32 v172, v166
	v_add_f32_e32 v166, v180, v181
	ds_bpermute_b32 v170, v216, v166
	v_mov_b32_e32 v180, v197
	v_mov_b32_e32 v181, v198
	v_mov_b32_e32 v197, v199
	v_add_f32_e32 v180, v180, v196
	v_add_f32_e32 v181, v181, v197
	s_waitcnt lgkmcnt(0)
	v_add_f32_e32 v166, v166, v170
	ds_bpermute_b32 v170, v217, v166
	v_mul_f32_e32 v110, v110, v176
	v_mul_f32_e32 v111, v111, v176
	v_mul_f32_e32 v108, v108, v176
	v_mul_f32_e32 v109, v109, v176
	v_max_f32_e32 v110, 0, v110
	v_max_f32_e32 v111, 0, v111
	s_waitcnt lgkmcnt(0)
	v_add_f32_e32 v166, v166, v170
	v_fmamk_f32 v166, v166, 0x3a800000, v195
	v_rsq_f32_e32 v170, v166
	v_add_f32_e32 v166, v180, v181
	ds_bpermute_b32 v179, v216, v166
	v_mov_b32_e32 v180, v139
	v_mov_b32_e32 v181, v140
	v_mov_b32_e32 v139, v141
	v_mov_b32_e32 v140, v135
	s_waitcnt lgkmcnt(0)
	v_add_f32_e32 v166, v166, v179
	ds_bpermute_b32 v179, v217, v166
	v_mov_b32_e32 v141, v136
	v_mov_b32_e32 v135, v137
	v_mov_b32_e32 v136, v131
	v_mov_b32_e32 v137, v132
	s_waitcnt lgkmcnt(0)
;     __device__ __forceinline__ void operator()(const f32x4 (&acc)[2][2][4][2], const Unit& u, int wr, int wc, int fr, int fq) const {
;     ...
;                     float t = (part[ai][m][0] + part[ai][m][1]) + (part[ai][m][2] + part[ai][m][3]);
;                     t += __shfl_xor(t, 16); t += __shfl_xor(t, 32);
;                     rsc[ai][m] = __builtin_amdgcn_rsqf(t * rs_inv + EPS);
;     ...
;                     f32x4 v0 = acc[ai][bj][m][0] * rs1, v1 = acc[ai][bj][m][1] * rs1;
;                     if (mode == EP_PLAIN) { store8(O + (size_t)row * ldc + col8, v0, v1); }
;                     else if (mode == EP_RELU2) {
; #pragma unroll
;                         for (int e = 0; e < 4; ++e) { float a = fmaxf(v0[e], 0.f), b = fmaxf(v1[e], 0.f); v0[e] = a * a; v1[e] = b * b; }
;                         store8(O + (size_t)row * ldc + col8, v0, v1);
	v_mul_f32_e32 v122, v122, v178
	v_mul_f32_e32 v123, v123, v178
	v_mov_b32_e32 v131, v133
	v_mul_f32_e32 v128, v128, v178
	v_mul_f32_e32 v129, v129, v178
	v_max_f32_e32 v122, 0, v122
	v_max_f32_e32 v123, 0, v123
	v_add_f32_e32 v130, v136, v130
	v_add_f32_e32 v131, v137, v131
	v_lshl_or_b32 v132, s48, 8, v173
	v_mul_f32_e32 v126, v126, v178
	v_mul_f32_e32 v127, v127, v178
	v_mul_f32_e32 v124, v124, v178
	v_mul_f32_e32 v125, v125, v178
	v_mul_f32_e32 v136, v122, v122
	v_mul_f32_e32 v137, v123, v123
	v_max_f32_e32 v122, 0, v128
	v_max_f32_e32 v123, 0, v129
	v_max_f32_e32 v126, 0, v126
	v_max_f32_e32 v127, 0, v127
	v_max_f32_e32 v124, 0, v124
	v_max_f32_e32 v125, 0, v125
	v_mul_f32_e32 v128, v122, v122
	v_mul_f32_e32 v129, v123, v123
	v_lshlrev_b64 v[122:123], 13, v[174:175]
	v_ashrrev_i32_e32 v133, 31, v132
	v_add_f32_e32 v134, v140, v134
	v_add_f32_e32 v135, v141, v135
	v_mul_f32_e32 v126, v126, v126
	v_mul_f32_e32 v127, v127, v127
	v_mul_f32_e32 v140, v124, v124
	v_mul_f32_e32 v141, v125, v125
	v_lshl_add_u64 v[124:125], s[6:7], 0, v[122:123]
	v_lshlrev_b64 v[122:123], 1, v[132:133]
	v_mul_f32_e32 v114, v114, v178
	v_mul_f32_e32 v115, v115, v178
	v_lshl_add_u64 v[132:133], v[124:125], 0, v[122:123]
	v_cvt_pk_bf16_f32 v124, v126, v127
	v_cvt_pk_bf16_f32 v125, v128, v129
	v_cvt_pk_bf16_f32 v126, v136, v137
	v_cvt_pk_bf16_f32 v127, v140, v141
	v_mul_f32_e32 v120, v120, v178
	v_mul_f32_e32 v121, v121, v178
	v_mul_f32_e32 v118, v118, v178
	v_mul_f32_e32 v119, v119, v178
	v_mul_f32_e32 v116, v116, v178
	v_mul_f32_e32 v117, v117, v178
	v_max_f32_e32 v114, 0, v114
	v_max_f32_e32 v115, 0, v115
	global_store_dwordx4 v[132:133], v[124:127], off
	v_max_f32_e32 v118, 0, v118
	v_max_f32_e32 v119, 0, v119
	v_mul_f32_e32 v124, v114, v114
	v_mul_f32_e32 v125, v115, v115
	v_max_f32_e32 v114, 0, v120
	v_max_f32_e32 v116, 0, v116
	v_max_f32_e32 v115, 0, v121
	v_max_f32_e32 v117, 0, v117
	v_mul_f32_e32 v118, v118, v118
	v_mul_f32_e32 v119, v119, v119
	v_mul_f32_e32 v120, v114, v114
	v_mul_f32_e32 v121, v115, v115
	v_mul_f32_e32 v126, v116, v116
	v_mul_f32_e32 v127, v117, v117
	v_cvt_pk_bf16_f32 v114, v118, v119
	v_cvt_pk_bf16_f32 v115, v120, v121
	v_cvt_pk_bf16_f32 v116, v124, v125
	v_cvt_pk_bf16_f32 v117, v126, v127
	global_store_dwordx4 v[132:133], v[114:117], off offset:256
	v_max_f32_e32 v108, 0, v108
	v_max_f32_e32 v109, 0, v109
	v_mul_f32_e32 v114, v106, v106
	v_mul_f32_e32 v115, v107, v107
	v_max_f32_e32 v106, 0, v112
	v_max_f32_e32 v107, 0, v113
	v_mul_f32_e32 v112, v106, v106
	v_mul_f32_e32 v113, v107, v107
	v_lshlrev_b64 v[106:107], 13, v[168:169]
	v_mul_f32_e32 v110, v110, v110
	v_mul_f32_e32 v111, v111, v111
	v_mul_f32_e32 v116, v108, v108
	v_mul_f32_e32 v117, v109, v109
	v_lshl_add_u64 v[106:107], s[6:7], 0, v[106:107]
	v_mul_f32_e32 v98, v98, v176
	v_mul_f32_e32 v99, v99, v176
	v_lshl_add_u64 v[118:119], v[106:107], 0, v[122:123]
	v_cvt_pk_bf16_f32 v106, v110, v111
	v_cvt_pk_bf16_f32 v107, v112, v113
	v_cvt_pk_bf16_f32 v108, v114, v115
	v_cvt_pk_bf16_f32 v109, v116, v117
	v_mul_f32_e32 v104, v104, v176
	v_mul_f32_e32 v105, v105, v176
	v_mul_f32_e32 v102, v102, v176
	v_mul_f32_e32 v103, v103, v176
	v_mul_f32_e32 v100, v100, v176
	v_mul_f32_e32 v101, v101, v176
	v_max_f32_e32 v98, 0, v98
	v_max_f32_e32 v99, 0, v99
	global_store_dwordx4 v[118:119], v[106:109], off
	v_max_f32_e32 v102, 0, v102
	v_max_f32_e32 v103, 0, v103
	v_mul_f32_e32 v106, v98, v98
	v_mul_f32_e32 v107, v99, v99
	v_max_f32_e32 v98, 0, v104
	v_max_f32_e32 v100, 0, v100
	v_max_f32_e32 v99, 0, v105
	v_max_f32_e32 v101, 0, v101
	v_mul_f32_e32 v102, v102, v102
	v_mul_f32_e32 v103, v103, v103
	v_mul_f32_e32 v104, v98, v98
	v_mul_f32_e32 v105, v99, v99
	v_mul_f32_e32 v108, v100, v100
	v_mul_f32_e32 v109, v101, v101
	v_mul_f32_e32 v90, v90, v172
	v_mul_f32_e32 v91, v91, v172
	v_add_f32_e32 v138, v180, v138
	v_add_f32_e32 v139, v181, v139
	v_cvt_pk_bf16_f32 v98, v102, v103
	v_cvt_pk_bf16_f32 v99, v104, v105
	v_cvt_pk_bf16_f32 v100, v106, v107
	v_cvt_pk_bf16_f32 v101, v108, v109
	v_mul_f32_e32 v96, v96, v172
	v_mul_f32_e32 v97, v97, v172
	v_mul_f32_e32 v94, v94, v172
	v_mul_f32_e32 v95, v95, v172
	v_mul_f32_e32 v92, v92, v172
	v_mul_f32_e32 v93, v93, v172
	v_max_f32_e32 v90, 0, v90
	v_max_f32_e32 v91, 0, v91
	v_add_f32_e32 v138, v138, v139
	global_store_dwordx4 v[118:119], v[98:101], off offset:256
	v_max_f32_e32 v94, 0, v94
	v_max_f32_e32 v95, 0, v95
	v_lshlrev_b64 v[98:99], 13, v[164:165]
	v_mul_f32_e32 v100, v90, v90
	v_mul_f32_e32 v101, v91, v91
	v_max_f32_e32 v90, 0, v96
	v_max_f32_e32 v92, 0, v92
	v_max_f32_e32 v91, 0, v97
	v_max_f32_e32 v93, 0, v93
	ds_bpermute_b32 v139, v216, v138
	v_mul_f32_e32 v94, v94, v94
	v_mul_f32_e32 v95, v95, v95
	v_mul_f32_e32 v96, v90, v90
	v_mul_f32_e32 v97, v91, v91
	v_mul_f32_e32 v102, v92, v92
	v_mul_f32_e32 v103, v93, v93
	v_lshl_add_u64 v[90:91], s[6:7], 0, v[98:99]
	v_mul_f32_e32 v82, v82, v172
	v_mul_f32_e32 v83, v83, v172
	v_lshl_add_u64 v[98:99], v[90:91], 0, v[122:123]
	v_cvt_pk_bf16_f32 v90, v94, v95
	v_cvt_pk_bf16_f32 v91, v96, v97
	v_cvt_pk_bf16_f32 v92, v100, v101
	v_cvt_pk_bf16_f32 v93, v102, v103
	v_mul_f32_e32 v88, v88, v172
	v_mul_f32_e32 v89, v89, v172
	v_mul_f32_e32 v86, v86, v172
	v_mul_f32_e32 v87, v87, v172
	v_mul_f32_e32 v84, v84, v172
	v_mul_f32_e32 v85, v85, v172
	v_max_f32_e32 v82, 0, v82
	v_max_f32_e32 v83, 0, v83
	global_store_dwordx4 v[98:99], v[90:93], off
	v_max_f32_e32 v86, 0, v86
	v_max_f32_e32 v87, 0, v87
	v_mul_f32_e32 v90, v82, v82
	v_mul_f32_e32 v91, v83, v83
	v_max_f32_e32 v82, 0, v88
	v_max_f32_e32 v84, 0, v84
	v_max_f32_e32 v83, 0, v89
	v_max_f32_e32 v85, 0, v85
	v_mul_f32_e32 v86, v86, v86
	v_mul_f32_e32 v87, v87, v87
	v_mul_f32_e32 v88, v82, v82
	v_mul_f32_e32 v89, v83, v83
	v_mul_f32_e32 v92, v84, v84
	v_mul_f32_e32 v93, v85, v85
	v_mul_f32_e32 v74, v74, v170
	v_mul_f32_e32 v75, v75, v170
	v_add_f32_e32 v166, v166, v179
	v_cvt_pk_bf16_f32 v82, v86, v87
	v_cvt_pk_bf16_f32 v83, v88, v89
	v_cvt_pk_bf16_f32 v84, v90, v91
	v_cvt_pk_bf16_f32 v85, v92, v93
	v_mul_f32_e32 v80, v80, v170
	v_mul_f32_e32 v81, v81, v170
	v_max_f32_e32 v74, 0, v74
	v_max_f32_e32 v75, 0, v75
	v_fmamk_f32 v166, v166, 0x3a800000, v195
	s_waitcnt lgkmcnt(0)
;     __device__ __forceinline__ void operator()(const f32x4 (&acc)[2][2][4][2], const Unit& u, int wr, int wc, int fr, int fq) const {
;     ...
;                     f32x4 v0 = acc[ai][bj][m][0] * rs1, v1 = acc[ai][bj][m][1] * rs1;
;                     if (mode == EP_PLAIN) { store8(O + (size_t)row * ldc + col8, v0, v1); }
;                     else if (mode == EP_RELU2) {
; #pragma unroll
;                         for (int e = 0; e < 4; ++e) { float a = fmaxf(v0[e], 0.f), b = fmaxf(v1[e], 0.f); v0[e] = a * a; v1[e] = b * b; }
;                         store8(O + (size_t)row * ldc + col8, v0, v1);
	v_add_f32_e32 v138, v138, v139
	global_store_dwordx4 v[98:99], v[82:85], off offset:256
	v_mul_f32_e32 v78, v78, v170
	v_mul_f32_e32 v79, v79, v170
	v_mul_f32_e32 v76, v76, v170
	v_mul_f32_e32 v77, v77, v170
	v_mul_f32_e32 v82, v74, v74
	v_mul_f32_e32 v83, v75, v75
	v_max_f32_e32 v74, 0, v80
	v_max_f32_e32 v75, 0, v81
	v_rsq_f32_e32 v166, v166
	ds_bpermute_b32 v139, v217, v138
	v_add_f32_e32 v134, v134, v135
	v_max_f32_e32 v78, 0, v78
	v_max_f32_e32 v79, 0, v79
	v_max_f32_e32 v76, 0, v76
	v_max_f32_e32 v77, 0, v77
	v_mul_f32_e32 v80, v74, v74
	v_mul_f32_e32 v81, v75, v75
	v_lshlrev_b64 v[74:75], 13, v[162:163]
	ds_bpermute_b32 v135, v216, v134
	v_mul_f32_e32 v78, v78, v78
	v_mul_f32_e32 v79, v79, v79
	v_mul_f32_e32 v84, v76, v76
	v_mul_f32_e32 v85, v77, v77
	v_lshl_add_u64 v[74:75], s[6:7], 0, v[74:75]
	v_mul_f32_e32 v66, v66, v170
	v_mul_f32_e32 v67, v67, v170
	v_lshl_add_u64 v[86:87], v[74:75], 0, v[122:123]
	v_cvt_pk_bf16_f32 v74, v78, v79
	v_cvt_pk_bf16_f32 v75, v80, v81
	v_cvt_pk_bf16_f32 v76, v82, v83
	v_cvt_pk_bf16_f32 v77, v84, v85
	v_mul_f32_e32 v72, v72, v170
	v_mul_f32_e32 v73, v73, v170
	v_mul_f32_e32 v70, v70, v170
	v_mul_f32_e32 v71, v71, v170
	v_mul_f32_e32 v68, v68, v170
	v_mul_f32_e32 v69, v69, v170
	v_max_f32_e32 v66, 0, v66
	v_max_f32_e32 v67, 0, v67
	global_store_dwordx4 v[86:87], v[74:77], off
	v_max_f32_e32 v70, 0, v70
	v_max_f32_e32 v71, 0, v71
	v_mul_f32_e32 v74, v66, v66
	v_mul_f32_e32 v75, v67, v67
	v_max_f32_e32 v66, 0, v72
	v_max_f32_e32 v68, 0, v68
	v_max_f32_e32 v67, 0, v73
	v_max_f32_e32 v69, 0, v69
	v_mul_f32_e32 v70, v70, v70
	v_mul_f32_e32 v71, v71, v71
	v_mul_f32_e32 v72, v66, v66
	v_mul_f32_e32 v73, v67, v67
	v_mul_f32_e32 v76, v68, v68
	v_mul_f32_e32 v77, v69, v69
	v_mul_f32_e32 v58, v58, v166
	v_mul_f32_e32 v59, v59, v166
	s_waitcnt lgkmcnt(1)
	v_add_f32_e32 v138, v138, v139
	v_cvt_pk_bf16_f32 v66, v70, v71
	v_cvt_pk_bf16_f32 v67, v72, v73
	v_cvt_pk_bf16_f32 v68, v74, v75
	v_cvt_pk_bf16_f32 v69, v76, v77
	v_mul_f32_e32 v64, v64, v166
	v_mul_f32_e32 v65, v65, v166
	v_max_f32_e32 v58, 0, v58
	v_max_f32_e32 v59, 0, v59
	v_fmamk_f32 v138, v138, 0x3a800000, v195
	s_waitcnt lgkmcnt(0)
	v_add_f32_e32 v134, v134, v135
	v_add_f32_e32 v130, v130, v131
	global_store_dwordx4 v[86:87], v[66:69], off offset:256
	v_mul_f32_e32 v62, v62, v166
	v_mul_f32_e32 v63, v63, v166
	v_mul_f32_e32 v60, v60, v166
	v_mul_f32_e32 v61, v61, v166
	v_mul_f32_e32 v66, v58, v58
	v_mul_f32_e32 v67, v59, v59
	v_max_f32_e32 v58, 0, v64
	v_max_f32_e32 v59, 0, v65
	v_rsq_f32_e32 v138, v138
	ds_bpermute_b32 v135, v217, v134
	ds_bpermute_b32 v131, v216, v130
	v_max_f32_e32 v62, 0, v62
	v_max_f32_e32 v63, 0, v63
	v_max_f32_e32 v60, 0, v60
	v_max_f32_e32 v61, 0, v61
	v_mul_f32_e32 v64, v58, v58
	v_mul_f32_e32 v65, v59, v59
	v_lshlrev_b64 v[58:59], 13, v[160:161]
	v_mul_f32_e32 v62, v62, v62
	v_mul_f32_e32 v63, v63, v63
	v_mul_f32_e32 v68, v60, v60
	v_mul_f32_e32 v69, v61, v61
	v_lshl_add_u64 v[58:59], s[6:7], 0, v[58:59]
	v_mul_f32_e32 v50, v50, v166
	v_mul_f32_e32 v51, v51, v166
	v_lshl_add_u64 v[70:71], v[58:59], 0, v[122:123]
	v_cvt_pk_bf16_f32 v58, v62, v63
	v_cvt_pk_bf16_f32 v59, v64, v65
	v_cvt_pk_bf16_f32 v60, v66, v67
	v_cvt_pk_bf16_f32 v61, v68, v69
	v_mul_f32_e32 v56, v56, v166
	v_mul_f32_e32 v57, v57, v166
	v_mul_f32_e32 v54, v54, v166
	v_mul_f32_e32 v55, v55, v166
	v_mul_f32_e32 v52, v52, v166
	v_mul_f32_e32 v53, v53, v166
	v_max_f32_e32 v50, 0, v50
	v_max_f32_e32 v51, 0, v51
	global_store_dwordx4 v[70:71], v[58:61], off
	v_max_f32_e32 v54, 0, v54
	v_max_f32_e32 v55, 0, v55
	v_mul_f32_e32 v58, v50, v50
	v_mul_f32_e32 v59, v51, v51
	v_max_f32_e32 v50, 0, v56
	v_max_f32_e32 v52, 0, v52
	v_max_f32_e32 v51, 0, v57
	v_max_f32_e32 v53, 0, v53
	v_mul_f32_e32 v54, v54, v54
	v_mul_f32_e32 v55, v55, v55
	v_mul_f32_e32 v56, v50, v50
	v_mul_f32_e32 v57, v51, v51
	v_mul_f32_e32 v60, v52, v52
	v_mul_f32_e32 v61, v53, v53
	v_mul_f32_e32 v42, v42, v138
	v_mul_f32_e32 v43, v43, v138
	s_waitcnt lgkmcnt(1)
	v_add_f32_e32 v134, v134, v135
	s_waitcnt lgkmcnt(0)
	v_add_f32_e32 v130, v130, v131
	v_cvt_pk_bf16_f32 v50, v54, v55
	v_cvt_pk_bf16_f32 v51, v56, v57
	v_cvt_pk_bf16_f32 v52, v58, v59
	v_cvt_pk_bf16_f32 v53, v60, v61
	v_mul_f32_e32 v48, v48, v138
	v_mul_f32_e32 v49, v49, v138
	v_max_f32_e32 v42, 0, v42
	v_max_f32_e32 v43, 0, v43
	v_fmamk_f32 v134, v134, 0x3a800000, v195
	ds_bpermute_b32 v131, v217, v130
	global_store_dwordx4 v[70:71], v[50:53], off offset:256
	v_mul_f32_e32 v46, v46, v138
	v_mul_f32_e32 v47, v47, v138
	v_mul_f32_e32 v44, v44, v138
	v_mul_f32_e32 v45, v45, v138
	v_mul_f32_e32 v50, v42, v42
	v_mul_f32_e32 v51, v43, v43
	v_max_f32_e32 v42, 0, v48
	v_max_f32_e32 v43, 0, v49
	v_rsq_f32_e32 v134, v134
	v_max_f32_e32 v46, 0, v46
	v_max_f32_e32 v47, 0, v47
	v_max_f32_e32 v44, 0, v44
	v_max_f32_e32 v45, 0, v45
	v_mul_f32_e32 v48, v42, v42
	v_mul_f32_e32 v49, v43, v43
	v_lshlrev_b64 v[42:43], 13, v[158:159]
	v_mul_f32_e32 v46, v46, v46
	v_mul_f32_e32 v47, v47, v47
	v_mul_f32_e32 v52, v44, v44
	v_mul_f32_e32 v53, v45, v45
	v_lshl_add_u64 v[42:43], s[6:7], 0, v[42:43]
	v_mul_f32_e32 v34, v34, v138
	v_mul_f32_e32 v35, v35, v138
	v_lshl_add_u64 v[54:55], v[42:43], 0, v[122:123]
	v_cvt_pk_bf16_f32 v42, v46, v47
	v_cvt_pk_bf16_f32 v43, v48, v49
	v_cvt_pk_bf16_f32 v44, v50, v51
	v_cvt_pk_bf16_f32 v45, v52, v53
	v_mul_f32_e32 v40, v40, v138
	v_mul_f32_e32 v41, v41, v138
	v_mul_f32_e32 v38, v38, v138
	v_mul_f32_e32 v39, v39, v138
	v_mul_f32_e32 v36, v36, v138
	v_mul_f32_e32 v37, v37, v138
	v_max_f32_e32 v34, 0, v34
	v_max_f32_e32 v35, 0, v35
	global_store_dwordx4 v[54:55], v[42:45], off
	v_max_f32_e32 v38, 0, v38
	v_max_f32_e32 v39, 0, v39
	v_mul_f32_e32 v42, v34, v34
	v_mul_f32_e32 v43, v35, v35
	v_max_f32_e32 v34, 0, v40
	v_max_f32_e32 v36, 0, v36
	v_max_f32_e32 v35, 0, v41
	v_max_f32_e32 v37, 0, v37
	s_waitcnt lgkmcnt(0)
;     __device__ __forceinline__ void operator()(const f32x4 (&acc)[2][2][4][2], const Unit& u, int wr, int wc, int fr, int fq) const {
;     ...
;                     f32x4 v0 = acc[ai][bj][m][0] * rs1, v1 = acc[ai][bj][m][1] * rs1;
;                     if (mode == EP_PLAIN) { store8(O + (size_t)row * ldc + col8, v0, v1); }
;                     else if (mode == EP_RELU2) {
; #pragma unroll
;                         for (int e = 0; e < 4; ++e) { float a = fmaxf(v0[e], 0.f), b = fmaxf(v1[e], 0.f); v0[e] = a * a; v1[e] = b * b; }
;                         store8(O + (size_t)row * ldc + col8, v0, v1);
	v_add_f32_e32 v130, v130, v131
	v_mul_f32_e32 v38, v38, v38
	v_mul_f32_e32 v39, v39, v39
	v_mul_f32_e32 v40, v34, v34
	v_mul_f32_e32 v41, v35, v35
	v_mul_f32_e32 v44, v36, v36
	v_mul_f32_e32 v45, v37, v37
	v_mul_f32_e32 v26, v26, v134
	v_mul_f32_e32 v27, v27, v134
	v_fmamk_f32 v130, v130, 0x3a800000, v195
	v_cvt_pk_bf16_f32 v34, v38, v39
	v_cvt_pk_bf16_f32 v35, v40, v41
	v_cvt_pk_bf16_f32 v36, v42, v43
	v_cvt_pk_bf16_f32 v37, v44, v45
	v_mul_f32_e32 v32, v32, v134
	v_mul_f32_e32 v33, v33, v134
	v_mul_f32_e32 v30, v30, v134
	v_mul_f32_e32 v31, v31, v134
	v_mul_f32_e32 v28, v28, v134
	v_mul_f32_e32 v29, v29, v134
	v_max_f32_e32 v26, 0, v26
	v_max_f32_e32 v27, 0, v27
	v_rsq_f32_e32 v130, v130
	global_store_dwordx4 v[54:55], v[34:37], off offset:256
	v_max_f32_e32 v30, 0, v30
	v_max_f32_e32 v31, 0, v31
	v_lshlrev_b64 v[34:35], 13, v[156:157]
	v_mul_f32_e32 v36, v26, v26
	v_mul_f32_e32 v37, v27, v27
	v_max_f32_e32 v26, 0, v32
	v_max_f32_e32 v28, 0, v28
	v_max_f32_e32 v27, 0, v33
	v_max_f32_e32 v29, 0, v29
	v_mul_f32_e32 v30, v30, v30
	v_mul_f32_e32 v31, v31, v31
	v_mul_f32_e32 v32, v26, v26
	v_mul_f32_e32 v33, v27, v27
	v_mul_f32_e32 v38, v28, v28
	v_mul_f32_e32 v39, v29, v29
	v_lshl_add_u64 v[26:27], s[6:7], 0, v[34:35]
	v_mul_f32_e32 v18, v18, v134
	v_mul_f32_e32 v19, v19, v134
	v_lshl_add_u64 v[34:35], v[26:27], 0, v[122:123]
	v_cvt_pk_bf16_f32 v26, v30, v31
	v_cvt_pk_bf16_f32 v27, v32, v33
	v_cvt_pk_bf16_f32 v28, v36, v37
	v_cvt_pk_bf16_f32 v29, v38, v39
	v_mul_f32_e32 v24, v24, v134
	v_mul_f32_e32 v25, v25, v134
	v_mul_f32_e32 v22, v22, v134
	v_mul_f32_e32 v23, v23, v134
	v_mul_f32_e32 v20, v20, v134
	v_mul_f32_e32 v21, v21, v134
	v_max_f32_e32 v18, 0, v18
	v_max_f32_e32 v19, 0, v19
	global_store_dwordx4 v[34:35], v[26:29], off
	v_max_f32_e32 v22, 0, v22
	v_max_f32_e32 v23, 0, v23
	v_mul_f32_e32 v26, v18, v18
	v_mul_f32_e32 v27, v19, v19
	v_max_f32_e32 v18, 0, v24
	v_max_f32_e32 v20, 0, v20
	v_max_f32_e32 v19, 0, v25
	v_max_f32_e32 v21, 0, v21
	v_mul_f32_e32 v22, v22, v22
	v_mul_f32_e32 v23, v23, v23
	v_mul_f32_e32 v24, v18, v18
	v_mul_f32_e32 v25, v19, v19
	v_mul_f32_e32 v28, v20, v20
	v_mul_f32_e32 v29, v21, v21
	v_mul_f32_e32 v10, v10, v130
	v_mul_f32_e32 v11, v11, v130
	v_cvt_pk_bf16_f32 v18, v22, v23
	v_cvt_pk_bf16_f32 v19, v24, v25
	v_cvt_pk_bf16_f32 v20, v26, v27
	v_cvt_pk_bf16_f32 v21, v28, v29
	v_mul_f32_e32 v16, v16, v130
	v_mul_f32_e32 v17, v17, v130
	v_max_f32_e32 v10, 0, v10
	v_max_f32_e32 v11, 0, v11
	global_store_dwordx4 v[34:35], v[18:21], off offset:256
	v_mul_f32_e32 v14, v14, v130
	v_mul_f32_e32 v15, v15, v130
	v_mul_f32_e32 v12, v12, v130
	v_mul_f32_e32 v13, v13, v130
	v_mul_f32_e32 v18, v10, v10
	v_mul_f32_e32 v19, v11, v11
	v_max_f32_e32 v10, 0, v16
	v_max_f32_e32 v11, 0, v17
	v_max_f32_e32 v14, 0, v14
	v_max_f32_e32 v15, 0, v15
	v_max_f32_e32 v12, 0, v12
	v_max_f32_e32 v13, 0, v13
	v_mul_f32_e32 v16, v10, v10
	v_mul_f32_e32 v17, v11, v11
	v_lshlrev_b64 v[10:11], 13, v[154:155]
	v_mul_f32_e32 v14, v14, v14
	v_mul_f32_e32 v15, v15, v15
	v_mul_f32_e32 v20, v12, v12
	v_mul_f32_e32 v21, v13, v13
	v_lshl_add_u64 v[10:11], s[6:7], 0, v[10:11]
	v_mul_f32_e32 v2, v2, v130
	v_mul_f32_e32 v3, v3, v130
	v_lshl_add_u64 v[22:23], v[10:11], 0, v[122:123]
	v_cvt_pk_bf16_f32 v10, v14, v15
	v_cvt_pk_bf16_f32 v11, v16, v17
	v_cvt_pk_bf16_f32 v12, v18, v19
	v_cvt_pk_bf16_f32 v13, v20, v21
	v_mul_f32_e32 v8, v8, v130
	v_mul_f32_e32 v9, v9, v130
	v_mul_f32_e32 v6, v6, v130
	v_mul_f32_e32 v7, v7, v130
	v_mul_f32_e32 v4, v4, v130
	v_mul_f32_e32 v5, v5, v130
	v_max_f32_e32 v2, 0, v2
	v_max_f32_e32 v3, 0, v3
	global_store_dwordx4 v[22:23], v[10:13], off
	v_max_f32_e32 v6, 0, v6
	v_max_f32_e32 v7, 0, v7
	v_mul_f32_e32 v10, v2, v2
	v_mul_f32_e32 v11, v3, v3
	v_max_f32_e32 v2, 0, v8
	v_max_f32_e32 v4, 0, v4
	v_max_f32_e32 v3, 0, v9
	v_max_f32_e32 v5, 0, v5
	v_mul_f32_e32 v6, v6, v6
	v_mul_f32_e32 v7, v7, v7
	v_mul_f32_e32 v8, v2, v2
	v_mul_f32_e32 v9, v3, v3
	v_mul_f32_e32 v12, v4, v4
	v_mul_f32_e32 v13, v5, v5
	v_cvt_pk_bf16_f32 v2, v6, v7
	v_cvt_pk_bf16_f32 v3, v8, v9
	v_cvt_pk_bf16_f32 v4, v10, v11
	v_cvt_pk_bf16_f32 v5, v12, v13
	global_store_dwordx4 v[22:23], v[2:5], off offset:256
	s_cbranch_vccnz .LBB0_1227
	s_andn2_b64 vcc, exec, s[4:5]
	s_cbranch_vccnz .LBB0_1226
	s_barrier
	s_branch .LBB0_1226
